# write-through (sc1) stores in the two small elementwise phases P2a and P6b so the following grid barrier's release finds no dirty L2 lines
# speedup vs baseline: 1.0022x; 1.0022x over previous
; __device__ __forceinline__ unsigned cvt_pk_bf16(float lo, float hi) { unsigned r; asm volatile("v_cvt_pk_bf16_f32 %0, %1, %2" : "=v"(r) : "v"(lo), "v"(hi)); return r; }
; #define UNPK8(q, f) const float f[8] = {bf_lo((q).x), bf_hi((q).x), bf_lo((q).y), bf_hi((q).y), bf_lo((q).z), bf_hi((q).z), bf_lo((q).w), bf_hi((q).w)}
; template <int W> __device__ __forceinline__ void pool_run(const bf16_t* up, bf16_t* dp, int t0) {
;     u32x4 q[W + 15];
; #pragma unroll
;     for (int i = 0; i < W + 15; ++i) { const int dt = i - (W - 1); const bool ok = (t0 + dt >= 0); const u32x4 v = *(const u32x4*)(up + (ptrdiff_t)(ok ? dt : 0) * PW); q[i] = ok ? v : (u32x4){0u, 0u, 0u, 0u}; }
;     float s[8];
; #pragma unroll
;     for (int e = 0; e < 8; ++e) s[e] = 0.f;
; #pragma unroll
;     for (int i = 0; i < W - 1; ++i) { UNPK8(q[i], f);
; #pragma unroll
;         for (int e = 0; e < 8; ++e) s[e] += f[e]; }
; #pragma unroll
;     for (int j = 0; j < 16; ++j) {
;         UNPK8(q[j + W - 1], cur);
; #pragma unroll
;         for (int e = 0; e < 8; ++e) s[e] += cur[e];
;         const int cnt = (t0 + j + 1) < W ? (t0 + j + 1) : W; const float inv = 1.0f / (float)cnt;
;         u32x4 o; o.x = cvt_pk_bf16(s[0] * inv - cur[0], s[1] * inv - cur[1]); o.y = cvt_pk_bf16(s[2] * inv - cur[2], s[3] * inv - cur[3]);
;         o.z = cvt_pk_bf16(s[4] * inv - cur[4], s[5] * inv - cur[5]); o.w = cvt_pk_bf16(s[6] * inv - cur[6], s[7] * inv - cur[7]);
;         *(u32x4*)(dp + (size_t)j * PW) = o;
;         UNPK8(q[j], old);
; #pragma unroll
;         for (int e = 0; e < 8; ++e) s[e] -= old[e];
;     }
; }
.LBB0_412:
	s_or_b64 exec, exec, s[6:7]
	global_load_dwordx4 v[86:89], v[126:127], off
	global_load_dwordx4 v[90:93], v[126:127], off offset:2048
	v_add_co_u32_e32 v0, vcc, 0x1000, v126
	s_waitcnt vmcnt(2)
	v_lshlrev_b32_e32 v85, 16, v60
	v_addc_co_u32_e32 v1, vcc, 0, v127, vcc
	global_load_dwordx4 v[52:55], v[0:1], off
	global_load_dwordx4 v[48:51], v[0:1], off offset:2048
	v_lshlrev_b32_e32 v95, 16, v62
	v_add_f32_e32 v97, 0, v85
	v_add_f32_e32 v101, 0, v95
	v_lshlrev_b32_e32 v105, 16, v56
	v_lshlrev_b32_e32 v109, 16, v58
	v_and_b32_e32 v106, 0xffff0000, v56
	v_add_f32_e32 v56, v97, v105
	v_add_f32_e32 v97, v101, v109
	v_lshlrev_b32_e32 v101, 16, v68
	v_and_b32_e32 v60, 0xffff0000, v60
	v_add_f32_e32 v56, v56, v101
	v_lshlrev_b32_e32 v113, 16, v64
	v_lshlrev_b32_e32 v94, 16, v61
	v_and_b32_e32 v62, 0xffff0000, v62
	v_add_f32_e32 v98, 0, v60
	v_add_f32_e32 v56, v56, v113
	v_lshlrev_b32_e32 v117, 16, v76
	v_add_co_u32_e32 v0, vcc, 0x2000, v126
	v_add_f32_e32 v99, 0, v94
	v_add_f32_e32 v102, 0, v62
	v_lshlrev_b32_e32 v107, 16, v57
	v_and_b32_e32 v108, 0xffff0000, v57
	v_and_b32_e32 v110, 0xffff0000, v58
	v_add_f32_e32 v57, v98, v106
	v_and_b32_e32 v68, 0xffff0000, v68
	v_add_f32_e32 v56, v56, v117
	v_lshlrev_b32_e32 v121, 16, v72
	v_addc_co_u32_e32 v1, vcc, 0, v127, vcc
	v_add_f32_e32 v58, v99, v107
	v_add_f32_e32 v98, v102, v110
	v_lshlrev_b32_e32 v102, 16, v69
	v_add_f32_e32 v57, v57, v68
	v_and_b32_e32 v64, 0xffff0000, v64
	v_add_f32_e32 v56, v56, v121
	v_lshlrev_b32_e32 v131, 16, v80
	global_load_dwordx4 v[44:47], v[0:1], off
	global_load_dwordx4 v[40:43], v[0:1], off offset:2048
	v_add_co_u32_e32 v0, vcc, 0x3000, v126
	v_add_f32_e32 v58, v58, v102
	v_lshlrev_b32_e32 v114, 16, v65
	v_add_f32_e32 v57, v57, v64
	v_and_b32_e32 v76, 0xffff0000, v76
	v_add_f32_e32 v56, v56, v131
	v_addc_co_u32_e32 v1, vcc, 0, v127, vcc
	v_and_b32_e32 v61, 0xffff0000, v61
	v_add_f32_e32 v58, v58, v114
	v_lshlrev_b32_e32 v118, 16, v77
	v_add_f32_e32 v57, v57, v76
	v_and_b32_e32 v72, 0xffff0000, v72
	global_load_dwordx4 v[36:39], v[0:1], off
	global_load_dwordx4 v[32:35], v[0:1], off offset:2048
	v_add_co_u32_e32 v0, vcc, 0x4000, v126
	v_add_f32_e32 v100, 0, v61
	v_add_f32_e32 v58, v58, v118
	v_lshlrev_b32_e32 v122, 16, v73
	v_add_f32_e32 v57, v57, v72
	v_and_b32_e32 v80, 0xffff0000, v80
	v_addc_co_u32_e32 v1, vcc, 0, v127, vcc
	v_lshlrev_b32_e32 v111, 16, v59
	v_and_b32_e32 v112, 0xffff0000, v59
	v_add_f32_e32 v59, v100, v108
	v_and_b32_e32 v69, 0xffff0000, v69
	v_add_f32_e32 v58, v58, v122
	v_lshlrev_b32_e32 v132, 16, v81
	v_add_f32_e32 v57, v57, v80
	global_load_dwordx4 v[28:31], v[0:1], off
	global_load_dwordx4 v[24:27], v[0:1], off offset:2048
	v_add_co_u32_e32 v0, vcc, 0x5000, v126
	s_waitcnt vmcnt(9)
	v_lshlrev_b32_e32 v135, 16, v86
	v_add_f32_e32 v139, v56, v135
	v_min_u32_e32 v56, 7, v129
	v_add_u32_e32 v56, 1, v56
	v_and_b32_e32 v86, 0xffff0000, v86
	v_cvt_f32_ubyte0_e32 v56, v56
	v_add_f32_e32 v59, v59, v69
	v_and_b32_e32 v65, 0xffff0000, v65
	v_add_f32_e32 v58, v58, v132
	v_lshlrev_b32_e32 v136, 16, v87
	v_add_f32_e32 v140, v57, v86
	v_div_scale_f32 v57, s[14:15], v56, v56, 1.0
	v_addc_co_u32_e32 v1, vcc, 0, v127, vcc
	v_add_f32_e32 v59, v59, v65
	v_and_b32_e32 v77, 0xffff0000, v77
	v_add_f32_e32 v141, v58, v136
	v_rcp_f32_e32 v58, v57
	global_load_dwordx4 v[20:23], v[0:1], off
	global_load_dwordx4 v[16:19], v[0:1], off offset:2048
	v_add_co_u32_e32 v0, vcc, 0x6000, v126
	v_add_f32_e32 v59, v59, v77
	v_and_b32_e32 v73, 0xffff0000, v73
	v_addc_co_u32_e32 v1, vcc, 0, v127, vcc
	v_add_f32_e32 v59, v59, v73
	v_and_b32_e32 v81, 0xffff0000, v81
	global_load_dwordx4 v[12:15], v[0:1], off
	global_load_dwordx4 v[8:11], v[0:1], off offset:2048
	v_add_co_u32_e32 v0, vcc, 0x7000, v126
	v_add_f32_e32 v59, v59, v81
	v_and_b32_e32 v87, 0xffff0000, v87
	v_addc_co_u32_e32 v1, vcc, 0, v127, vcc
	v_add_f32_e32 v142, v59, v87
	v_fma_f32 v59, -v57, v58, 1.0
	v_lshlrev_b32_e32 v96, 16, v63
	v_fmac_f32_e32 v58, v59, v58
	v_div_scale_f32 v59, vcc, 1.0, v56, 1.0
	v_and_b32_e32 v63, 0xffff0000, v63
	v_add_f32_e32 v103, 0, v96
	v_mul_f32_e32 v143, v59, v58
	v_add_f32_e32 v104, 0, v63
	v_add_f32_e32 v99, v103, v111
	v_lshlrev_b32_e32 v103, 16, v70
	v_and_b32_e32 v70, 0xffff0000, v70
	v_fma_f32 v144, -v57, v143, v59
	v_add_f32_e32 v100, v104, v112
	v_lshlrev_b32_e32 v104, 16, v71
	v_and_b32_e32 v71, 0xffff0000, v71
	v_add_f32_e32 v97, v97, v103
	v_add_f32_e32 v98, v98, v70
	v_lshlrev_b32_e32 v115, 16, v66
	v_and_b32_e32 v66, 0xffff0000, v66
	v_fmac_f32_e32 v143, v144, v58
	v_add_f32_e32 v99, v99, v104
	v_add_f32_e32 v100, v100, v71
	v_lshlrev_b32_e32 v116, 16, v67
	v_and_b32_e32 v67, 0xffff0000, v67
	v_add_f32_e32 v97, v97, v115
	v_add_f32_e32 v98, v98, v66
	v_lshlrev_b32_e32 v119, 16, v78
	v_and_b32_e32 v78, 0xffff0000, v78
	v_fma_f32 v57, -v57, v143, v59
	v_add_f32_e32 v99, v99, v116
	v_add_f32_e32 v100, v100, v67
	v_lshlrev_b32_e32 v120, 16, v79
	v_and_b32_e32 v79, 0xffff0000, v79
	v_add_f32_e32 v97, v97, v119
	v_add_f32_e32 v98, v98, v78
	v_lshlrev_b32_e32 v123, 16, v74
	v_and_b32_e32 v74, 0xffff0000, v74
	v_div_fmas_f32 v57, v57, v58, v143
	v_add_f32_e32 v99, v99, v120
	v_add_f32_e32 v100, v100, v79
	v_lshlrev_b32_e32 v130, 16, v75
	v_and_b32_e32 v75, 0xffff0000, v75
	v_add_f32_e32 v97, v97, v123
	v_add_f32_e32 v98, v98, v74
	v_lshlrev_b32_e32 v133, 16, v82
	v_and_b32_e32 v82, 0xffff0000, v82
	v_div_fixup_f32 v59, v57, v56, 1.0
	v_add_f32_e32 v99, v99, v130
	v_add_f32_e32 v100, v100, v75
	v_lshlrev_b32_e32 v134, 16, v83
	v_and_b32_e32 v83, 0xffff0000, v83
	v_add_f32_e32 v97, v97, v133
	v_add_f32_e32 v98, v98, v82
	v_lshlrev_b32_e32 v137, 16, v88
	v_and_b32_e32 v88, 0xffff0000, v88
	v_fma_f32 v56, v59, v139, -v135
	v_fma_f32 v57, v59, v140, -v86
	global_load_dwordx4 v[4:7], v[0:1], off
	s_nop 0
	global_load_dwordx4 v[0:3], v[0:1], off offset:2048
	v_add_f32_e32 v99, v99, v134
	v_add_f32_e32 v100, v100, v83
	v_lshlrev_b32_e32 v138, 16, v89
	v_and_b32_e32 v89, 0xffff0000, v89
	v_add_f32_e32 v97, v97, v137
	v_add_f32_e32 v98, v98, v88
	v_cvt_pk_bf16_f32 v56, v56, v57
	v_fma_f32 v57, v59, v141, -v136
	v_fma_f32 v58, v59, v142, -v87
	v_add_f32_e32 v99, v99, v138
	v_add_f32_e32 v100, v100, v89
	v_cvt_pk_bf16_f32 v57, v57, v58
	v_fma_f32 v58, v59, v97, -v137
	v_fma_f32 v143, v59, v98, -v88
	v_cvt_pk_bf16_f32 v58, v58, v143
	v_fma_f32 v143, v59, v99, -v138
	v_fma_f32 v59, v59, v100, -v89
	v_cvt_pk_bf16_f32 v59, v143, v59
	global_store_dwordx4 v[124:125], v[56:59], off sc1
	v_sub_f32_e32 v63, v100, v63
	s_movk_i32 s12, 0x1000
	v_sub_f32_e32 v56, v139, v85
	s_waitcnt vmcnt(15)
; __device__ __forceinline__ unsigned cvt_pk_bf16(float lo, float hi) { unsigned r; asm volatile("v_cvt_pk_bf16_f32 %0, %1, %2" : "=v"(r) : "v"(lo), "v"(hi)); return r; }
; #define UNPK8(q, f) const float f[8] = {bf_lo((q).x), bf_hi((q).x), bf_lo((q).y), bf_hi((q).y), bf_lo((q).z), bf_hi((q).z), bf_lo((q).w), bf_hi((q).w)}
; template <int W> __device__ __forceinline__ void pool_run(const bf16_t* up, bf16_t* dp, int t0) {
;     u32x4 q[W + 15];
; #pragma unroll
;     for (int i = 0; i < W + 15; ++i) { const int dt = i - (W - 1); const bool ok = (t0 + dt >= 0); const u32x4 v = *(const u32x4*)(up + (ptrdiff_t)(ok ? dt : 0) * PW); q[i] = ok ? v : (u32x4){0u, 0u, 0u, 0u}; }
;     float s[8];
; #pragma unroll
;     for (int e = 0; e < 8; ++e) s[e] = 0.f;
; #pragma unroll
;     for (int i = 0; i < W - 1; ++i) { UNPK8(q[i], f);
; #pragma unroll
;         for (int e = 0; e < 8; ++e) s[e] += f[e]; }
; #pragma unroll
;     for (int j = 0; j < 16; ++j) {
;         UNPK8(q[j + W - 1], cur);
; #pragma unroll
;         for (int e = 0; e < 8; ++e) s[e] += cur[e];
;         const int cnt = (t0 + j + 1) < W ? (t0 + j + 1) : W; const float inv = 1.0f / (float)cnt;
;         u32x4 o; o.x = cvt_pk_bf16(s[0] * inv - cur[0], s[1] * inv - cur[1]); o.y = cvt_pk_bf16(s[2] * inv - cur[2], s[3] * inv - cur[3]);
;         o.z = cvt_pk_bf16(s[4] * inv - cur[4], s[5] * inv - cur[5]); o.w = cvt_pk_bf16(s[6] * inv - cur[6], s[7] * inv - cur[7]);
;         *(u32x4*)(dp + (size_t)j * PW) = o;
;         UNPK8(q[j], old);
; #pragma unroll
;         for (int e = 0; e < 8; ++e) s[e] -= old[e];
;     }
; }
	v_lshlrev_b32_e32 v85, 16, v90
	v_sub_f32_e32 v57, v140, v60
	v_sub_f32_e32 v60, v97, v95
	v_add_f32_e32 v97, v56, v85
	v_min_u32_e32 v56, 6, v129
	v_add_u32_e32 v56, 2, v56
	v_and_b32_e32 v90, 0xffff0000, v90
	v_cvt_f32_ubyte0_e32 v56, v56
	v_sub_f32_e32 v58, v141, v94
	v_sub_f32_e32 v59, v142, v61
	v_sub_f32_e32 v61, v98, v62
	v_lshlrev_b32_e32 v94, 16, v91
	v_add_f32_e32 v98, v57, v90
	v_div_scale_f32 v57, s[14:15], v56, v56, 1.0
	v_sub_f32_e32 v62, v99, v96
	v_add_f32_e32 v99, v58, v94
	v_rcp_f32_e32 v58, v57
	v_and_b32_e32 v91, 0xffff0000, v91
	v_add_f32_e32 v100, v59, v91
	v_lshlrev_b32_e32 v95, 16, v92
	v_fma_f32 v59, -v57, v58, 1.0
	v_fmac_f32_e32 v58, v59, v58
	v_div_scale_f32 v59, vcc, 1.0, v56, 1.0
	v_mul_f32_e32 v139, v59, v58
	v_fma_f32 v140, -v57, v139, v59
	v_fmac_f32_e32 v139, v140, v58
	v_fma_f32 v57, -v57, v139, v59
	v_div_fmas_f32 v57, v57, v58, v139
	v_div_fixup_f32 v59, v57, v56, 1.0
	v_and_b32_e32 v92, 0xffff0000, v92
	v_fma_f32 v56, v59, v97, -v85
	v_fma_f32 v57, v59, v98, -v90
	v_lshlrev_b32_e32 v96, 16, v93
	v_and_b32_e32 v93, 0xffff0000, v93
	v_add_f32_e32 v60, v60, v95
	v_add_f32_e32 v61, v61, v92
	v_cvt_pk_bf16_f32 v56, v56, v57
	v_fma_f32 v57, v59, v99, -v94
	v_fma_f32 v58, v59, v100, -v91
	v_add_f32_e32 v62, v62, v96
	v_add_f32_e32 v63, v63, v93
	v_cvt_pk_bf16_f32 v57, v57, v58
	v_fma_f32 v58, v59, v60, -v95
	v_fma_f32 v139, v59, v61, -v92
	v_cvt_pk_bf16_f32 v58, v58, v139
	v_fma_f32 v139, v59, v62, -v96
	v_fma_f32 v59, v59, v63, -v93
	v_cvt_pk_bf16_f32 v59, v139, v59
	global_store_dwordx4 v[124:125], v[56:59], off offset:2048 sc1
	v_sub_f32_e32 v60, v60, v109
	v_sub_f32_e32 v61, v61, v110
	v_sub_f32_e32 v56, v97, v105
	v_sub_f32_e32 v57, v98, v106
	s_waitcnt vmcnt(15)
	v_lshlrev_b32_e32 v97, 16, v52
	v_and_b32_e32 v98, 0xffff0000, v52
	v_min_u32_e32 v52, 5, v129
	v_add_u32_e32 v52, 3, v52
	v_cvt_f32_ubyte0_e32 v52, v52
	v_sub_f32_e32 v58, v99, v107
	v_sub_f32_e32 v59, v100, v108
	v_lshlrev_b32_e32 v99, 16, v53
	v_and_b32_e32 v100, 0xffff0000, v53
	v_div_scale_f32 v53, s[14:15], v52, v52, 1.0
	v_lshlrev_b32_e32 v105, 16, v54
	v_and_b32_e32 v106, 0xffff0000, v54
	v_rcp_f32_e32 v54, v53
	v_lshlrev_b32_e32 v107, 16, v55
	v_and_b32_e32 v108, 0xffff0000, v55
	v_add_f32_e32 v109, v56, v97
	v_fma_f32 v55, -v53, v54, 1.0
	v_fmac_f32_e32 v54, v55, v54
	v_div_scale_f32 v55, vcc, 1.0, v52, 1.0
	v_mul_f32_e32 v56, v55, v54
	v_add_f32_e32 v110, v57, v98
	v_fma_f32 v57, -v53, v56, v55
	v_fmac_f32_e32 v56, v57, v54
	v_fma_f32 v53, -v53, v56, v55
	v_div_fmas_f32 v53, v53, v54, v56
	v_div_fixup_f32 v55, v53, v52, 1.0
	v_sub_f32_e32 v62, v62, v111
	v_sub_f32_e32 v63, v63, v112
	v_add_f32_e32 v111, v58, v99
	v_add_f32_e32 v112, v59, v100
	v_fma_f32 v52, v55, v109, -v97
	v_fma_f32 v53, v55, v110, -v98
	v_add_f32_e32 v60, v60, v105
	v_add_f32_e32 v61, v61, v106
	v_cvt_pk_bf16_f32 v52, v52, v53
	v_fma_f32 v53, v55, v111, -v99
	v_fma_f32 v54, v55, v112, -v100
	v_add_f32_e32 v62, v62, v107
	v_add_f32_e32 v63, v63, v108
	v_cvt_pk_bf16_f32 v53, v53, v54
	v_fma_f32 v54, v55, v60, -v105
	v_fma_f32 v56, v55, v61, -v106
	v_cvt_pk_bf16_f32 v54, v54, v56
	v_fma_f32 v56, v55, v62, -v107
	v_fma_f32 v55, v55, v63, -v108
	v_cvt_pk_bf16_f32 v55, v56, v55
	v_add_co_u32_e32 v56, vcc, s12, v124
	s_movk_i32 s13, 0x2000
	s_nop 0
	v_addc_co_u32_e32 v57, vcc, 0, v125, vcc
	v_add_co_u32_e32 v58, vcc, s13, v124
	v_sub_f32_e32 v61, v61, v70
	s_nop 0
	v_addc_co_u32_e32 v59, vcc, 0, v125, vcc
	global_store_dwordx4 v[58:59], v[52:55], off offset:-4096 sc1
	v_sub_f32_e32 v63, v63, v71
	s_waitcnt vmcnt(15)
	v_lshlrev_b32_e32 v70, 16, v49
	v_sub_f32_e32 v53, v110, v68
	v_sub_f32_e32 v55, v112, v69
	v_lshlrev_b32_e32 v68, 16, v48
	v_and_b32_e32 v69, 0xffff0000, v48
	v_min_u32_e32 v48, 4, v129
	v_add_u32_e32 v48, 4, v48
	v_cvt_f32_ubyte0_e32 v48, v48
	v_and_b32_e32 v71, 0xffff0000, v49
	v_div_scale_f32 v49, s[12:13], v48, v48, 1.0
	v_sub_f32_e32 v52, v109, v101
	v_sub_f32_e32 v54, v111, v102
	v_lshlrev_b32_e32 v101, 16, v50
	v_and_b32_e32 v102, 0xffff0000, v50
	v_rcp_f32_e32 v50, v49
	v_sub_f32_e32 v60, v60, v103
	v_sub_f32_e32 v62, v62, v104
	v_lshlrev_b32_e32 v103, 16, v51
	v_and_b32_e32 v104, 0xffff0000, v51
	v_fma_f32 v51, -v49, v50, 1.0
	v_fmac_f32_e32 v50, v51, v50
	v_div_scale_f32 v51, vcc, 1.0, v48, 1.0
	v_mul_f32_e32 v109, v51, v50
	v_fma_f32 v110, -v49, v109, v51
	v_fmac_f32_e32 v109, v110, v50
	v_fma_f32 v49, -v49, v109, v51
	v_div_fmas_f32 v49, v49, v50, v109
	v_add_f32_e32 v52, v52, v68
	v_add_f32_e32 v53, v53, v69
	v_div_fixup_f32 v51, v49, v48, 1.0
	v_add_f32_e32 v54, v54, v70
	v_add_f32_e32 v55, v55, v71
	v_fma_f32 v48, v51, v52, -v68
	v_fma_f32 v49, v51, v53, -v69
	v_add_f32_e32 v60, v60, v101
	v_add_f32_e32 v61, v61, v102
	v_cvt_pk_bf16_f32 v48, v48, v49
	v_fma_f32 v49, v51, v54, -v70
	v_fma_f32 v50, v51, v55, -v71
	v_add_f32_e32 v62, v62, v103
	v_add_f32_e32 v63, v63, v104
	v_cvt_pk_bf16_f32 v49, v49, v50
	v_fma_f32 v50, v51, v60, -v101
	v_fma_f32 v109, v51, v61, -v102
	v_cvt_pk_bf16_f32 v50, v50, v109
	v_fma_f32 v109, v51, v62, -v103
	v_fma_f32 v51, v51, v63, -v104
	v_cvt_pk_bf16_f32 v51, v109, v51
	global_store_dwordx4 v[56:57], v[48:51], off offset:2048 sc1
	s_waitcnt vmcnt(15)
; __device__ __forceinline__ unsigned cvt_pk_bf16(float lo, float hi) { unsigned r; asm volatile("v_cvt_pk_bf16_f32 %0, %1, %2" : "=v"(r) : "v"(lo), "v"(hi)); return r; }
; #define UNPK8(q, f) const float f[8] = {bf_lo((q).x), bf_hi((q).x), bf_lo((q).y), bf_hi((q).y), bf_lo((q).z), bf_hi((q).z), bf_lo((q).w), bf_hi((q).w)}
; template <int W> __device__ __forceinline__ void pool_run(const bf16_t* up, bf16_t* dp, int t0) {
;     u32x4 q[W + 15];
; #pragma unroll
;     for (int i = 0; i < W + 15; ++i) { const int dt = i - (W - 1); const bool ok = (t0 + dt >= 0); const u32x4 v = *(const u32x4*)(up + (ptrdiff_t)(ok ? dt : 0) * PW); q[i] = ok ? v : (u32x4){0u, 0u, 0u, 0u}; }
;     float s[8];
; #pragma unroll
;     for (int e = 0; e < 8; ++e) s[e] = 0.f;
; #pragma unroll
;     for (int i = 0; i < W - 1; ++i) { UNPK8(q[i], f);
; #pragma unroll
;         for (int e = 0; e < 8; ++e) s[e] += f[e]; }
; #pragma unroll
;     for (int j = 0; j < 16; ++j) {
;         UNPK8(q[j + W - 1], cur);
; #pragma unroll
;         for (int e = 0; e < 8; ++e) s[e] += cur[e];
;         const int cnt = (t0 + j + 1) < W ? (t0 + j + 1) : W; const float inv = 1.0f / (float)cnt;
;         u32x4 o; o.x = cvt_pk_bf16(s[0] * inv - cur[0], s[1] * inv - cur[1]); o.y = cvt_pk_bf16(s[2] * inv - cur[2], s[3] * inv - cur[3]);
;         o.z = cvt_pk_bf16(s[4] * inv - cur[4], s[5] * inv - cur[5]); o.w = cvt_pk_bf16(s[6] * inv - cur[6], s[7] * inv - cur[7]);
;         *(u32x4*)(dp + (size_t)j * PW) = o;
;         UNPK8(q[j], old);
; #pragma unroll
;         for (int e = 0; e < 8; ++e) s[e] -= old[e];
;     }
; }
	v_lshlrev_b32_e32 v56, 16, v44
	v_and_b32_e32 v57, 0xffff0000, v44
	v_min_u32_e32 v44, 3, v129
	v_add_u32_e32 v44, 5, v44
	v_cvt_f32_ubyte0_e32 v44, v44
	v_sub_f32_e32 v48, v52, v113
	v_sub_f32_e32 v49, v53, v64
	v_sub_f32_e32 v52, v60, v115
	v_sub_f32_e32 v53, v61, v66
	v_lshlrev_b32_e32 v60, 16, v45
	v_and_b32_e32 v61, 0xffff0000, v45
	v_div_scale_f32 v45, s[12:13], v44, v44, 1.0
	v_sub_f32_e32 v50, v54, v114
	v_sub_f32_e32 v51, v55, v65
	v_sub_f32_e32 v54, v62, v116
	v_sub_f32_e32 v55, v63, v67
	v_lshlrev_b32_e32 v62, 16, v46
	v_and_b32_e32 v63, 0xffff0000, v46
	v_rcp_f32_e32 v46, v45
	v_lshlrev_b32_e32 v64, 16, v47
	v_and_b32_e32 v65, 0xffff0000, v47
	v_add_f32_e32 v48, v48, v56
	v_fma_f32 v47, -v45, v46, 1.0
	v_fmac_f32_e32 v46, v47, v46
	v_div_scale_f32 v47, vcc, 1.0, v44, 1.0
	v_mul_f32_e32 v66, v47, v46
	v_fma_f32 v67, -v45, v66, v47
	v_fmac_f32_e32 v66, v67, v46
	v_fma_f32 v45, -v45, v66, v47
	v_div_fmas_f32 v45, v45, v46, v66
	v_add_f32_e32 v49, v49, v57
	v_div_fixup_f32 v47, v45, v44, 1.0
	v_add_f32_e32 v50, v50, v60
	v_add_f32_e32 v51, v51, v61
	v_fma_f32 v44, v47, v48, -v56
	v_fma_f32 v45, v47, v49, -v57
	v_add_f32_e32 v52, v52, v62
	v_add_f32_e32 v53, v53, v63
	v_cvt_pk_bf16_f32 v44, v44, v45
	v_fma_f32 v45, v47, v50, -v60
	v_fma_f32 v46, v47, v51, -v61
	v_add_f32_e32 v54, v54, v64
	v_add_f32_e32 v55, v55, v65
	v_cvt_pk_bf16_f32 v45, v45, v46
	v_fma_f32 v46, v47, v52, -v62
	v_fma_f32 v66, v47, v53, -v63
	v_cvt_pk_bf16_f32 v46, v46, v66
	v_fma_f32 v66, v47, v54, -v64
	v_fma_f32 v47, v47, v55, -v65
	v_cvt_pk_bf16_f32 v47, v66, v47
	global_store_dwordx4 v[58:59], v[44:47], off sc1
	s_waitcnt vmcnt(15)
	v_lshlrev_b32_e32 v66, 16, v42
	v_and_b32_e32 v67, 0xffff0000, v42
	v_sub_f32_e32 v44, v48, v117
	v_sub_f32_e32 v45, v49, v76
	v_sub_f32_e32 v48, v52, v119
	v_sub_f32_e32 v49, v53, v78
	v_lshlrev_b32_e32 v52, 16, v40
	v_and_b32_e32 v53, 0xffff0000, v40
	v_min_u32_e32 v40, 2, v129
	v_add_u32_e32 v40, 6, v40
	v_cvt_f32_ubyte0_e32 v40, v40
	v_sub_f32_e32 v46, v50, v118
	v_sub_f32_e32 v47, v51, v77
	v_sub_f32_e32 v50, v54, v120
	v_sub_f32_e32 v51, v55, v79
	v_lshlrev_b32_e32 v54, 16, v41
	v_and_b32_e32 v55, 0xffff0000, v41
	v_div_scale_f32 v41, s[12:13], v40, v40, 1.0
	v_rcp_f32_e32 v42, v41
	v_lshlrev_b32_e32 v76, 16, v43
	v_and_b32_e32 v77, 0xffff0000, v43
	v_add_f32_e32 v44, v44, v52
	v_fma_f32 v43, -v41, v42, 1.0
	v_fmac_f32_e32 v42, v43, v42
	v_div_scale_f32 v43, vcc, 1.0, v40, 1.0
	v_mul_f32_e32 v78, v43, v42
	v_fma_f32 v79, -v41, v78, v43
	v_fmac_f32_e32 v78, v79, v42
	v_fma_f32 v41, -v41, v78, v43
	v_div_fmas_f32 v41, v41, v42, v78
	v_add_f32_e32 v45, v45, v53
	v_div_fixup_f32 v43, v41, v40, 1.0
	v_add_f32_e32 v46, v46, v54
	v_add_f32_e32 v47, v47, v55
	v_fma_f32 v40, v43, v44, -v52
	v_fma_f32 v41, v43, v45, -v53
	v_add_f32_e32 v48, v48, v66
	v_add_f32_e32 v49, v49, v67
	v_cvt_pk_bf16_f32 v40, v40, v41
	v_fma_f32 v41, v43, v46, -v54
	v_fma_f32 v42, v43, v47, -v55
	v_add_f32_e32 v50, v50, v76
	v_add_f32_e32 v51, v51, v77
	v_cvt_pk_bf16_f32 v41, v41, v42
	v_fma_f32 v42, v43, v48, -v66
	v_fma_f32 v78, v43, v49, -v67
	v_cvt_pk_bf16_f32 v42, v42, v78
	v_fma_f32 v78, v43, v50, -v76
	v_fma_f32 v43, v43, v51, -v77
	v_cvt_pk_bf16_f32 v43, v78, v43
	global_store_dwordx4 v[58:59], v[40:43], off offset:2048 sc1
	s_waitcnt vmcnt(15)
	v_lshlrev_b32_e32 v58, 16, v38
	v_and_b32_e32 v59, 0xffff0000, v38
	v_sub_f32_e32 v40, v44, v121
	v_sub_f32_e32 v41, v45, v72
	v_sub_f32_e32 v44, v48, v123
	v_sub_f32_e32 v45, v49, v74
	v_lshlrev_b32_e32 v48, 16, v36
	v_and_b32_e32 v49, 0xffff0000, v36
	v_div_scale_f32 v36, s[12:13], v84, v84, 1.0
	v_sub_f32_e32 v42, v46, v122
	v_sub_f32_e32 v43, v47, v73
	v_sub_f32_e32 v46, v50, v130
	v_sub_f32_e32 v47, v51, v75
	v_lshlrev_b32_e32 v50, 16, v37
	v_and_b32_e32 v51, 0xffff0000, v37
	v_rcp_f32_e32 v37, v36
	v_lshlrev_b32_e32 v72, 16, v39
	v_and_b32_e32 v73, 0xffff0000, v39
	v_add_f32_e32 v74, v40, v48
	v_fma_f32 v38, -v36, v37, 1.0
	v_fmac_f32_e32 v37, v38, v37
	v_div_scale_f32 v38, vcc, 1.0, v84, 1.0
	v_mul_f32_e32 v39, v38, v37
	v_fma_f32 v40, -v36, v39, v38
	v_fmac_f32_e32 v39, v40, v37
	v_fma_f32 v36, -v36, v39, v38
	v_div_fmas_f32 v36, v36, v37, v39
	v_add_f32_e32 v75, v41, v49
	v_div_fixup_f32 v39, v36, v84, 1.0
	v_add_f32_e32 v78, v42, v50
	v_add_f32_e32 v79, v43, v51
	v_fma_f32 v36, v39, v74, -v48
	v_fma_f32 v37, v39, v75, -v49
	v_add_f32_e32 v44, v44, v58
	v_add_f32_e32 v45, v45, v59
	v_cvt_pk_bf16_f32 v36, v36, v37
	v_fma_f32 v37, v39, v78, -v50
	v_fma_f32 v38, v39, v79, -v51
	v_add_f32_e32 v46, v46, v72
	v_add_f32_e32 v47, v47, v73
	v_cvt_pk_bf16_f32 v37, v37, v38
	v_fma_f32 v38, v39, v44, -v58
	v_fma_f32 v40, v39, v45, -v59
	s_movk_i32 s9, 0x3000
	v_cvt_pk_bf16_f32 v38, v38, v40
	v_fma_f32 v40, v39, v46, -v72
	v_fma_f32 v39, v39, v47, -v73
	v_cvt_pk_bf16_f32 v39, v40, v39
	v_add_co_u32_e32 v40, vcc, s9, v124
	s_movk_i32 s11, 0x4000
	s_nop 0
	v_addc_co_u32_e32 v41, vcc, 0, v125, vcc
	v_add_co_u32_e32 v42, vcc, s11, v124
	s_mov_b32 s9, 0x3e000000
	s_nop 0
	v_addc_co_u32_e32 v43, vcc, 0, v125, vcc
	global_store_dwordx4 v[42:43], v[36:39], off offset:-4096 sc1
	v_sub_f32_e32 v44, v44, v133
	v_sub_f32_e32 v45, v45, v82
	v_sub_f32_e32 v36, v74, v131
	v_sub_f32_e32 v37, v75, v80
	s_waitcnt vmcnt(15)
; __device__ __forceinline__ unsigned cvt_pk_bf16(float lo, float hi) { unsigned r; asm volatile("v_cvt_pk_bf16_f32 %0, %1, %2" : "=v"(r) : "v"(lo), "v"(hi)); return r; }
; #define UNPK8(q, f) const float f[8] = {bf_lo((q).x), bf_hi((q).x), bf_lo((q).y), bf_hi((q).y), bf_lo((q).z), bf_hi((q).z), bf_lo((q).w), bf_hi((q).w)}
; template <int W> __device__ __forceinline__ void pool_run(const bf16_t* up, bf16_t* dp, int t0) {
;     u32x4 q[W + 15];
; #pragma unroll
;     for (int i = 0; i < W + 15; ++i) { const int dt = i - (W - 1); const bool ok = (t0 + dt >= 0); const u32x4 v = *(const u32x4*)(up + (ptrdiff_t)(ok ? dt : 0) * PW); q[i] = ok ? v : (u32x4){0u, 0u, 0u, 0u}; }
;     float s[8];
; #pragma unroll
;     for (int e = 0; e < 8; ++e) s[e] = 0.f;
; #pragma unroll
;     for (int i = 0; i < W - 1; ++i) { UNPK8(q[i], f);
; #pragma unroll
;         for (int e = 0; e < 8; ++e) s[e] += f[e]; }
; #pragma unroll
;     for (int j = 0; j < 16; ++j) {
;         UNPK8(q[j + W - 1], cur);
; #pragma unroll
;         for (int e = 0; e < 8; ++e) s[e] += cur[e];
;         const int cnt = (t0 + j + 1) < W ? (t0 + j + 1) : W; const float inv = 1.0f / (float)cnt;
;         u32x4 o; o.x = cvt_pk_bf16(s[0] * inv - cur[0], s[1] * inv - cur[1]); o.y = cvt_pk_bf16(s[2] * inv - cur[2], s[3] * inv - cur[3]);
;         o.z = cvt_pk_bf16(s[4] * inv - cur[4], s[5] * inv - cur[5]); o.w = cvt_pk_bf16(s[6] * inv - cur[6], s[7] * inv - cur[7]);
;         *(u32x4*)(dp + (size_t)j * PW) = o;
;         UNPK8(q[j], old);
; #pragma unroll
;         for (int e = 0; e < 8; ++e) s[e] -= old[e];
;     }
; }
	v_lshlrev_b32_e32 v74, 16, v32
	v_and_b32_e32 v75, 0xffff0000, v32
	v_sub_f32_e32 v38, v78, v132
	v_sub_f32_e32 v39, v79, v81
	v_lshlrev_b32_e32 v78, 16, v33
	v_and_b32_e32 v79, 0xffff0000, v33
	v_add_f32_e32 v36, v36, v74
	v_add_f32_e32 v37, v37, v75
	v_lshlrev_b32_e32 v80, 16, v34
	v_and_b32_e32 v81, 0xffff0000, v34
	v_add_f32_e32 v38, v38, v78
	v_add_f32_e32 v39, v39, v79
	v_fma_f32 v32, v36, s9, -v74
	v_fma_f32 v33, v37, s9, -v75
	v_sub_f32_e32 v46, v46, v134
	v_lshlrev_b32_e32 v82, 16, v35
	v_add_f32_e32 v44, v44, v80
	v_add_f32_e32 v45, v45, v81
	v_cvt_pk_bf16_f32 v32, v32, v33
	v_fma_f32 v33, v38, s9, -v78
	v_fma_f32 v34, v39, s9, -v79
	v_sub_f32_e32 v47, v47, v83
	v_and_b32_e32 v83, 0xffff0000, v35
	v_add_f32_e32 v46, v46, v82
	v_cvt_pk_bf16_f32 v33, v33, v34
	v_fma_f32 v34, v44, s9, -v80
	v_fma_f32 v35, v45, s9, -v81
	v_add_f32_e32 v47, v47, v83
	v_cvt_pk_bf16_f32 v34, v34, v35
	v_fma_f32 v35, v46, s9, -v82
	v_fma_f32 v84, v47, s9, -v83
	v_cvt_pk_bf16_f32 v35, v35, v84
	global_store_dwordx4 v[40:41], v[32:35], off offset:2048 sc1
	s_waitcnt vmcnt(15)
	v_lshlrev_b32_e32 v40, 16, v28
	v_and_b32_e32 v28, 0xffff0000, v28
	v_sub_f32_e32 v32, v36, v135
	v_sub_f32_e32 v33, v37, v86
	v_sub_f32_e32 v34, v38, v136
	v_sub_f32_e32 v35, v39, v87
	v_lshlrev_b32_e32 v41, 16, v29
	v_and_b32_e32 v29, 0xffff0000, v29
	v_add_f32_e32 v32, v32, v40
	v_add_f32_e32 v33, v33, v28
	v_sub_f32_e32 v36, v44, v137
	v_sub_f32_e32 v37, v45, v88
	v_sub_f32_e32 v39, v47, v89
	v_lshlrev_b32_e32 v44, 16, v30
	v_and_b32_e32 v30, 0xffff0000, v30
	v_lshlrev_b32_e32 v45, 16, v31
	v_and_b32_e32 v31, 0xffff0000, v31
	v_add_f32_e32 v34, v34, v41
	v_add_f32_e32 v35, v35, v29
	v_fma_f32 v40, v32, s9, -v40
	v_fma_f32 v28, v33, s9, -v28
	v_sub_f32_e32 v38, v46, v138
	v_add_f32_e32 v36, v36, v44
	v_add_f32_e32 v37, v37, v30
	v_add_f32_e32 v39, v39, v31
	v_cvt_pk_bf16_f32 v28, v40, v28
	v_fma_f32 v40, v34, s9, -v41
	v_fma_f32 v29, v35, s9, -v29
	v_add_f32_e32 v38, v38, v45
	v_cvt_pk_bf16_f32 v29, v40, v29
	v_fma_f32 v40, v36, s9, -v44
	v_fma_f32 v30, v37, s9, -v30
	v_fma_f32 v31, v39, s9, -v31
	v_cvt_pk_bf16_f32 v30, v40, v30
	v_fma_f32 v40, v38, s9, -v45
	v_cvt_pk_bf16_f32 v31, v40, v31
	global_store_dwordx4 v[42:43], v[28:31], off sc1
	s_movk_i32 s7, 0x5000
	s_movk_i32 s8, 0x6000
	v_sub_f32_e32 v28, v32, v85
	v_sub_f32_e32 v29, v33, v90
	v_sub_f32_e32 v32, v36, v95
	s_waitcnt vmcnt(15)
	v_lshlrev_b32_e32 v36, 16, v24
	v_and_b32_e32 v24, 0xffff0000, v24
	v_sub_f32_e32 v30, v34, v94
	v_sub_f32_e32 v31, v35, v91
	v_sub_f32_e32 v33, v37, v92
	v_lshlrev_b32_e32 v37, 16, v25
	v_and_b32_e32 v25, 0xffff0000, v25
	v_add_f32_e32 v28, v28, v36
	v_add_f32_e32 v29, v29, v24
	v_sub_f32_e32 v34, v38, v96
	v_sub_f32_e32 v35, v39, v93
	v_lshlrev_b32_e32 v38, 16, v26
	v_and_b32_e32 v26, 0xffff0000, v26
	v_lshlrev_b32_e32 v39, 16, v27
	v_and_b32_e32 v27, 0xffff0000, v27
	v_add_f32_e32 v30, v30, v37
	v_add_f32_e32 v31, v31, v25
	v_fma_f32 v36, v28, s9, -v36
	v_fma_f32 v24, v29, s9, -v24
	v_add_f32_e32 v32, v32, v38
	v_add_f32_e32 v33, v33, v26
	v_add_f32_e32 v35, v35, v27
	v_cvt_pk_bf16_f32 v24, v36, v24
	v_fma_f32 v36, v30, s9, -v37
	v_fma_f32 v25, v31, s9, -v25
	v_add_f32_e32 v34, v34, v39
	v_cvt_pk_bf16_f32 v25, v36, v25
	v_fma_f32 v36, v32, s9, -v38
	v_fma_f32 v26, v33, s9, -v26
	v_fma_f32 v27, v35, s9, -v27
	v_cvt_pk_bf16_f32 v26, v36, v26
	v_fma_f32 v36, v34, s9, -v39
	v_cvt_pk_bf16_f32 v27, v36, v27
	global_store_dwordx4 v[42:43], v[24:27], off offset:2048 sc1
	s_movk_i32 s6, 0x7000
	s_nop 0
	v_sub_f32_e32 v24, v28, v97
	v_sub_f32_e32 v25, v29, v98
	v_sub_f32_e32 v28, v32, v105
	s_waitcnt vmcnt(15)
	v_lshlrev_b32_e32 v32, 16, v20
	v_and_b32_e32 v20, 0xffff0000, v20
	v_sub_f32_e32 v26, v30, v99
	v_sub_f32_e32 v27, v31, v100
	v_sub_f32_e32 v29, v33, v106
	v_lshlrev_b32_e32 v33, 16, v21
	v_and_b32_e32 v21, 0xffff0000, v21
	v_add_f32_e32 v36, v24, v32
	v_add_f32_e32 v37, v25, v20
	v_sub_f32_e32 v30, v34, v107
	v_lshlrev_b32_e32 v34, 16, v22
	v_and_b32_e32 v22, 0xffff0000, v22
	v_add_f32_e32 v38, v26, v33
	v_add_f32_e32 v39, v27, v21
	v_fma_f32 v24, v36, s9, -v32
	v_fma_f32 v20, v37, s9, -v20
	v_sub_f32_e32 v31, v35, v108
	v_lshlrev_b32_e32 v35, 16, v23
	v_and_b32_e32 v23, 0xffff0000, v23
	v_add_f32_e32 v28, v28, v34
	v_add_f32_e32 v29, v29, v22
	v_cvt_pk_bf16_f32 v20, v24, v20
	v_fma_f32 v24, v38, s9, -v33
	v_fma_f32 v21, v39, s9, -v21
	v_add_f32_e32 v30, v30, v35
	v_add_f32_e32 v31, v31, v23
	v_cvt_pk_bf16_f32 v21, v24, v21
	v_fma_f32 v24, v28, s9, -v34
	v_fma_f32 v22, v29, s9, -v22
	v_cvt_pk_bf16_f32 v22, v24, v22
	v_fma_f32 v24, v30, s9, -v35
	v_fma_f32 v23, v31, s9, -v23
	v_cvt_pk_bf16_f32 v23, v24, v23
	v_add_co_u32_e32 v24, vcc, s7, v124
	s_waitcnt vmcnt(14)
; __device__ __forceinline__ unsigned cvt_pk_bf16(float lo, float hi) { unsigned r; asm volatile("v_cvt_pk_bf16_f32 %0, %1, %2" : "=v"(r) : "v"(lo), "v"(hi)); return r; }
; #define UNPK8(q, f) const float f[8] = {bf_lo((q).x), bf_hi((q).x), bf_lo((q).y), bf_hi((q).y), bf_lo((q).z), bf_hi((q).z), bf_lo((q).w), bf_hi((q).w)}
; template <int W> __device__ __forceinline__ void pool_run(const bf16_t* up, bf16_t* dp, int t0) {
;     u32x4 q[W + 15];
; #pragma unroll
;     for (int i = 0; i < W + 15; ++i) { const int dt = i - (W - 1); const bool ok = (t0 + dt >= 0); const u32x4 v = *(const u32x4*)(up + (ptrdiff_t)(ok ? dt : 0) * PW); q[i] = ok ? v : (u32x4){0u, 0u, 0u, 0u}; }
;     float s[8];
; #pragma unroll
;     for (int e = 0; e < 8; ++e) s[e] = 0.f;
; #pragma unroll
;     for (int i = 0; i < W - 1; ++i) { UNPK8(q[i], f);
; #pragma unroll
;         for (int e = 0; e < 8; ++e) s[e] += f[e]; }
; #pragma unroll
;     for (int j = 0; j < 16; ++j) {
;         UNPK8(q[j + W - 1], cur);
; #pragma unroll
;         for (int e = 0; e < 8; ++e) s[e] += cur[e];
;         const int cnt = (t0 + j + 1) < W ? (t0 + j + 1) : W; const float inv = 1.0f / (float)cnt;
;         u32x4 o; o.x = cvt_pk_bf16(s[0] * inv - cur[0], s[1] * inv - cur[1]); o.y = cvt_pk_bf16(s[2] * inv - cur[2], s[3] * inv - cur[3]);
;         o.z = cvt_pk_bf16(s[4] * inv - cur[4], s[5] * inv - cur[5]); o.w = cvt_pk_bf16(s[6] * inv - cur[6], s[7] * inv - cur[7]);
;         *(u32x4*)(dp + (size_t)j * PW) = o;
;         UNPK8(q[j], old);
; #pragma unroll
;         for (int e = 0; e < 8; ++e) s[e] -= old[e];
;     }
; }
	v_lshlrev_b32_e32 v32, 16, v16
	v_addc_co_u32_e32 v25, vcc, 0, v125, vcc
	v_add_co_u32_e32 v26, vcc, s8, v124
	v_and_b32_e32 v16, 0xffff0000, v16
	s_nop 0
	v_addc_co_u32_e32 v27, vcc, 0, v125, vcc
	global_store_dwordx4 v[26:27], v[20:23], off offset:-4096 sc1
	v_lshlrev_b32_e32 v33, 16, v17
	v_and_b32_e32 v17, 0xffff0000, v17
	v_sub_f32_e32 v20, v36, v68
	v_sub_f32_e32 v21, v37, v69
	v_sub_f32_e32 v22, v38, v70
	v_sub_f32_e32 v23, v39, v71
	v_add_f32_e32 v20, v20, v32
	v_add_f32_e32 v21, v21, v16
	v_sub_f32_e32 v28, v28, v101
	v_sub_f32_e32 v29, v29, v102
	v_sub_f32_e32 v31, v31, v104
	v_lshlrev_b32_e32 v34, 16, v18
	v_and_b32_e32 v18, 0xffff0000, v18
	v_lshlrev_b32_e32 v35, 16, v19
	v_and_b32_e32 v19, 0xffff0000, v19
	v_add_f32_e32 v22, v22, v33
	v_add_f32_e32 v23, v23, v17
	v_fma_f32 v32, v20, s9, -v32
	v_fma_f32 v16, v21, s9, -v16
	v_sub_f32_e32 v30, v30, v103
	v_add_f32_e32 v28, v28, v34
	v_add_f32_e32 v29, v29, v18
	v_add_f32_e32 v31, v31, v19
	v_cvt_pk_bf16_f32 v16, v32, v16
	v_fma_f32 v32, v22, s9, -v33
	v_fma_f32 v17, v23, s9, -v17
	v_add_f32_e32 v30, v30, v35
	v_cvt_pk_bf16_f32 v17, v32, v17
	v_fma_f32 v32, v28, s9, -v34
	v_fma_f32 v18, v29, s9, -v18
	v_fma_f32 v19, v31, s9, -v19
	v_cvt_pk_bf16_f32 v18, v32, v18
	v_fma_f32 v32, v30, s9, -v35
	v_cvt_pk_bf16_f32 v19, v32, v19
	global_store_dwordx4 v[24:25], v[16:19], off offset:2048 sc1
	s_waitcnt vmcnt(15)
	v_lshlrev_b32_e32 v24, 16, v12
	v_and_b32_e32 v12, 0xffff0000, v12
	v_sub_f32_e32 v16, v20, v56
	v_sub_f32_e32 v17, v21, v57
	v_sub_f32_e32 v18, v22, v60
	v_sub_f32_e32 v19, v23, v61
	v_lshlrev_b32_e32 v25, 16, v13
	v_and_b32_e32 v13, 0xffff0000, v13
	v_add_f32_e32 v16, v16, v24
	v_add_f32_e32 v17, v17, v12
	v_sub_f32_e32 v20, v28, v62
	v_sub_f32_e32 v21, v29, v63
	v_sub_f32_e32 v23, v31, v65
	v_lshlrev_b32_e32 v28, 16, v14
	v_and_b32_e32 v14, 0xffff0000, v14
	v_lshlrev_b32_e32 v29, 16, v15
	v_and_b32_e32 v15, 0xffff0000, v15
	v_add_f32_e32 v18, v18, v25
	v_add_f32_e32 v19, v19, v13
	v_fma_f32 v24, v16, s9, -v24
	v_fma_f32 v12, v17, s9, -v12
	v_sub_f32_e32 v22, v30, v64
	v_add_f32_e32 v20, v20, v28
	v_add_f32_e32 v21, v21, v14
	v_add_f32_e32 v23, v23, v15
	v_cvt_pk_bf16_f32 v12, v24, v12
	v_fma_f32 v24, v18, s9, -v25
	v_fma_f32 v13, v19, s9, -v13
	v_add_f32_e32 v22, v22, v29
	v_cvt_pk_bf16_f32 v13, v24, v13
	v_fma_f32 v24, v20, s9, -v28
	v_fma_f32 v14, v21, s9, -v14
	v_fma_f32 v15, v23, s9, -v15
	v_cvt_pk_bf16_f32 v14, v24, v14
	v_fma_f32 v24, v22, s9, -v29
	v_cvt_pk_bf16_f32 v15, v24, v15
	global_store_dwordx4 v[26:27], v[12:15], off sc1
	s_nop 1
	v_sub_f32_e32 v12, v16, v52
	v_sub_f32_e32 v13, v17, v53
	v_sub_f32_e32 v16, v20, v66
	s_waitcnt vmcnt(15)
	v_lshlrev_b32_e32 v20, 16, v8
	v_and_b32_e32 v8, 0xffff0000, v8
	v_sub_f32_e32 v14, v18, v54
	v_sub_f32_e32 v15, v19, v55
	v_sub_f32_e32 v17, v21, v67
	v_lshlrev_b32_e32 v21, 16, v9
	v_and_b32_e32 v9, 0xffff0000, v9
	v_add_f32_e32 v12, v12, v20
	v_add_f32_e32 v13, v13, v8
	v_sub_f32_e32 v18, v22, v76
	v_sub_f32_e32 v19, v23, v77
	v_lshlrev_b32_e32 v22, 16, v10
	v_and_b32_e32 v10, 0xffff0000, v10
	v_lshlrev_b32_e32 v23, 16, v11
	v_and_b32_e32 v11, 0xffff0000, v11
	v_add_f32_e32 v14, v14, v21
	v_add_f32_e32 v15, v15, v9
	v_fma_f32 v20, v12, s9, -v20
	v_fma_f32 v8, v13, s9, -v8
	v_add_f32_e32 v16, v16, v22
	v_add_f32_e32 v17, v17, v10
	v_add_f32_e32 v19, v19, v11
	v_cvt_pk_bf16_f32 v8, v20, v8
	v_fma_f32 v20, v14, s9, -v21
	v_fma_f32 v9, v15, s9, -v9
	v_add_f32_e32 v18, v18, v23
	v_cvt_pk_bf16_f32 v9, v20, v9
	v_fma_f32 v20, v16, s9, -v22
	v_fma_f32 v10, v17, s9, -v10
	v_fma_f32 v11, v19, s9, -v11
	v_cvt_pk_bf16_f32 v10, v20, v10
	v_fma_f32 v20, v18, s9, -v23
	v_cvt_pk_bf16_f32 v11, v20, v11
	global_store_dwordx4 v[26:27], v[8:11], off offset:2048 sc1
	s_nop 1
	v_sub_f32_e32 v8, v12, v48
	v_sub_f32_e32 v9, v13, v49
	v_sub_f32_e32 v12, v16, v58
	s_waitcnt vmcnt(15)
	v_lshlrev_b32_e32 v16, 16, v4
	v_and_b32_e32 v4, 0xffff0000, v4
	v_sub_f32_e32 v10, v14, v50
	v_sub_f32_e32 v11, v15, v51
	v_sub_f32_e32 v13, v17, v59
	v_lshlrev_b32_e32 v17, 16, v5
	v_and_b32_e32 v5, 0xffff0000, v5
	v_add_f32_e32 v20, v8, v16
	v_add_f32_e32 v21, v9, v4
	v_sub_f32_e32 v14, v18, v72
	v_lshlrev_b32_e32 v18, 16, v6
	v_and_b32_e32 v6, 0xffff0000, v6
	v_add_f32_e32 v10, v10, v17
	v_add_f32_e32 v11, v11, v5
	v_fma_f32 v8, v20, s9, -v16
	v_fma_f32 v4, v21, s9, -v4
	v_sub_f32_e32 v15, v19, v73
	v_lshlrev_b32_e32 v19, 16, v7
	v_and_b32_e32 v7, 0xffff0000, v7
	v_add_f32_e32 v12, v12, v18
	v_add_f32_e32 v13, v13, v6
	v_cvt_pk_bf16_f32 v4, v8, v4
	v_fma_f32 v8, v10, s9, -v17
	v_fma_f32 v5, v11, s9, -v5
	v_add_f32_e32 v14, v14, v19
	v_add_f32_e32 v15, v15, v7
	v_cvt_pk_bf16_f32 v5, v8, v5
	v_fma_f32 v8, v12, s9, -v18
	v_fma_f32 v6, v13, s9, -v6
	v_cvt_pk_bf16_f32 v6, v8, v6
	v_fma_f32 v8, v14, s9, -v19
	v_fma_f32 v7, v15, s9, -v7
	v_cvt_pk_bf16_f32 v7, v8, v7
	v_add_co_u32_e32 v8, vcc, s6, v124
	s_mov_b64 s[6:7], 0
	s_nop 0
	v_addc_co_u32_e32 v9, vcc, 0, v125, vcc
	global_store_dwordx4 v[8:9], v[4:7], off sc1
	v_sub_f32_e32 v8, v12, v80
	s_waitcnt vmcnt(15)
	v_lshlrev_b32_e32 v12, 16, v0
	v_sub_f32_e32 v4, v20, v74
	v_sub_f32_e32 v5, v21, v75
	v_and_b32_e32 v0, 0xffff0000, v0
	v_sub_f32_e32 v6, v10, v78
	v_sub_f32_e32 v7, v11, v79
	v_sub_f32_e32 v9, v13, v81
	v_lshlrev_b32_e32 v13, 16, v1
	v_and_b32_e32 v1, 0xffff0000, v1
	v_add_f32_e32 v4, v4, v12
	v_add_f32_e32 v5, v5, v0
	v_sub_f32_e32 v10, v14, v82
	v_sub_f32_e32 v11, v15, v83
	v_lshlrev_b32_e32 v14, 16, v2
	v_and_b32_e32 v2, 0xffff0000, v2
	v_lshlrev_b32_e32 v15, 16, v3
	v_and_b32_e32 v3, 0xffff0000, v3
	v_add_f32_e32 v6, v6, v13
	v_add_f32_e32 v7, v7, v1
	v_fma_f32 v4, v4, s9, -v12
	v_fma_f32 v0, v5, s9, -v0
	v_add_f32_e32 v8, v8, v14
	v_add_f32_e32 v9, v9, v2
	v_add_f32_e32 v11, v11, v3
	v_cvt_pk_bf16_f32 v0, v4, v0
	v_fma_f32 v4, v6, s9, -v13
	v_fma_f32 v1, v7, s9, -v1
	v_add_f32_e32 v10, v10, v15
	v_cvt_pk_bf16_f32 v1, v4, v1
	v_fma_f32 v4, v8, s9, -v14
	v_fma_f32 v2, v9, s9, -v2
	v_fma_f32 v3, v11, s9, -v3
	v_cvt_pk_bf16_f32 v2, v4, v2
	v_fma_f32 v4, v10, s9, -v15
	v_cvt_pk_bf16_f32 v3, v4, v3
	s_branch .LBB0_416

; __device__ __forceinline__ unsigned cvt_pk_bf16(float lo, float hi) { unsigned r; asm volatile("v_cvt_pk_bf16_f32 %0, %1, %2" : "=v"(r) : "v"(lo), "v"(hi)); return r; }
; #define UNPK8(q, f) const float f[8] = {bf_lo((q).x), bf_hi((q).x), bf_lo((q).y), bf_hi((q).y), bf_lo((q).z), bf_hi((q).z), bf_lo((q).w), bf_hi((q).w)}
; template <int W> __device__ __forceinline__ void pool_run(const bf16_t* up, bf16_t* dp, int t0) {
;     u32x4 q[W + 15];
; #pragma unroll
;     for (int i = 0; i < W + 15; ++i) { const int dt = i - (W - 1); const bool ok = (t0 + dt >= 0); const u32x4 v = *(const u32x4*)(up + (ptrdiff_t)(ok ? dt : 0) * PW); q[i] = ok ? v : (u32x4){0u, 0u, 0u, 0u}; }
;     float s[8];
; #pragma unroll
;     for (int e = 0; e < 8; ++e) s[e] = 0.f;
; #pragma unroll
;     for (int i = 0; i < W - 1; ++i) { UNPK8(q[i], f);
; #pragma unroll
;         for (int e = 0; e < 8; ++e) s[e] += f[e]; }
; #pragma unroll
;     for (int j = 0; j < 16; ++j) {
;         UNPK8(q[j + W - 1], cur);
; #pragma unroll
;         for (int e = 0; e < 8; ++e) s[e] += cur[e];
;         const int cnt = (t0 + j + 1) < W ? (t0 + j + 1) : W; const float inv = 1.0f / (float)cnt;
;         u32x4 o; o.x = cvt_pk_bf16(s[0] * inv - cur[0], s[1] * inv - cur[1]); o.y = cvt_pk_bf16(s[2] * inv - cur[2], s[3] * inv - cur[3]);
;         o.z = cvt_pk_bf16(s[4] * inv - cur[4], s[5] * inv - cur[5]); o.w = cvt_pk_bf16(s[6] * inv - cur[6], s[7] * inv - cur[7]);
;         *(u32x4*)(dp + (size_t)j * PW) = o;
;         UNPK8(q[j], old);
; #pragma unroll
;         for (int e = 0; e < 8; ++e) s[e] -= old[e];
;     }
; }
.LBB0_447:
	s_or_b64 exec, exec, s[4:5]
	global_load_dwordx4 v[120:123], v[126:127], off
	global_load_dwordx4 v[104:107], v[126:127], off offset:2048
	v_add_co_u32_e32 v0, vcc, 0x1000, v126
	s_waitcnt vmcnt(2)
	v_lshlrev_b32_e32 v171, 16, v52
	v_addc_co_u32_e32 v1, vcc, 0, v127, vcc
	global_load_dwordx4 v[84:87], v[0:1], off
	global_load_dwordx4 v[64:67], v[0:1], off offset:2048
	v_and_b32_e32 v172, 0xffff0000, v52
	v_add_f32_e32 v52, 0, v171
	v_lshlrev_b32_e32 v179, 16, v44
	v_and_b32_e32 v180, 0xffff0000, v44
	v_add_f32_e32 v44, v52, v179
	v_lshlrev_b32_e32 v187, 16, v60
	v_lshlrev_b32_e32 v173, 16, v53
	v_and_b32_e32 v174, 0xffff0000, v53
	v_add_f32_e32 v53, 0, v172
	v_add_f32_e32 v44, v44, v187
	v_lshlrev_b32_e32 v195, 16, v56
	v_lshlrev_b32_e32 v181, 16, v45
	v_and_b32_e32 v182, 0xffff0000, v45
	v_add_f32_e32 v45, v53, v180
	v_and_b32_e32 v188, 0xffff0000, v60
	v_add_f32_e32 v44, v44, v195
	v_lshlrev_b32_e32 v203, 16, v72
	v_lshlrev_b32_e32 v175, 16, v54
	v_and_b32_e32 v176, 0xffff0000, v54
	v_add_f32_e32 v54, 0, v173
	v_add_f32_e32 v45, v45, v188
	v_and_b32_e32 v196, 0xffff0000, v56
	v_add_f32_e32 v44, v44, v203
	v_lshlrev_b32_e32 v163, 16, v68
	v_lshlrev_b32_e32 v177, 16, v55
	v_and_b32_e32 v178, 0xffff0000, v55
	v_add_f32_e32 v55, 0, v174
	v_lshlrev_b32_e32 v183, 16, v46
	v_and_b32_e32 v184, 0xffff0000, v46
	v_add_f32_e32 v46, v54, v181
	v_lshlrev_b32_e32 v189, 16, v61
	v_add_f32_e32 v45, v45, v196
	v_and_b32_e32 v204, 0xffff0000, v72
	v_add_f32_e32 v44, v44, v163
	v_lshlrev_b32_e32 v155, 16, v80
	v_add_f32_e32 v131, 0, v175
	v_add_f32_e32 v132, 0, v176
	v_lshlrev_b32_e32 v185, 16, v47
	v_and_b32_e32 v186, 0xffff0000, v47
	v_add_f32_e32 v47, v55, v182
	v_and_b32_e32 v190, 0xffff0000, v61
	v_add_f32_e32 v46, v46, v189
	v_lshlrev_b32_e32 v197, 16, v57
	v_add_f32_e32 v45, v45, v204
	v_and_b32_e32 v164, 0xffff0000, v68
	v_add_f32_e32 v44, v44, v155
	v_lshlrev_b32_e32 v147, 16, v76
	v_add_f32_e32 v52, v131, v183
	v_add_f32_e32 v53, v132, v184
	v_lshlrev_b32_e32 v191, 16, v62
	v_and_b32_e32 v192, 0xffff0000, v62
	v_add_f32_e32 v47, v47, v190
	v_and_b32_e32 v198, 0xffff0000, v57
	v_add_f32_e32 v46, v46, v197
	v_lshlrev_b32_e32 v205, 16, v73
	v_add_f32_e32 v45, v45, v164
	v_and_b32_e32 v156, 0xffff0000, v80
	v_add_f32_e32 v44, v44, v147
	v_lshlrev_b32_e32 v139, 16, v92
	v_add_f32_e32 v52, v52, v191
	v_add_f32_e32 v53, v53, v192
	v_lshlrev_b32_e32 v199, 16, v58
	v_and_b32_e32 v200, 0xffff0000, v58
	v_add_f32_e32 v47, v47, v198
	v_and_b32_e32 v206, 0xffff0000, v73
	v_add_f32_e32 v46, v46, v205
	v_lshlrev_b32_e32 v165, 16, v69
	v_add_f32_e32 v45, v45, v156
	v_and_b32_e32 v148, 0xffff0000, v76
	v_add_f32_e32 v44, v44, v139
	v_lshlrev_b32_e32 v131, 16, v88
	v_add_f32_e32 v52, v52, v199
	v_add_f32_e32 v53, v53, v200
	v_lshlrev_b32_e32 v207, 16, v74
	v_and_b32_e32 v208, 0xffff0000, v74
	v_add_f32_e32 v47, v47, v206
	v_and_b32_e32 v166, 0xffff0000, v69
	v_add_f32_e32 v46, v46, v165
	v_lshlrev_b32_e32 v157, 16, v81
	v_add_f32_e32 v45, v45, v148
	v_and_b32_e32 v140, 0xffff0000, v92
	v_and_b32_e32 v132, 0xffff0000, v88
	v_add_f32_e32 v44, v44, v131
	v_lshlrev_b32_e32 v88, 16, v100
	v_add_f32_e32 v133, 0, v177
	v_add_f32_e32 v134, 0, v178
	v_add_f32_e32 v52, v52, v207
	v_add_f32_e32 v53, v53, v208
	v_lshlrev_b32_e32 v167, 16, v70
	v_and_b32_e32 v168, 0xffff0000, v70
	v_add_f32_e32 v47, v47, v166
	v_and_b32_e32 v158, 0xffff0000, v81
	v_add_f32_e32 v46, v46, v157
	v_lshlrev_b32_e32 v149, 16, v77
	v_add_f32_e32 v45, v45, v140
	v_add_f32_e32 v44, v44, v88
	v_lshlrev_b32_e32 v76, 16, v96
	v_add_f32_e32 v54, v133, v185
	v_add_f32_e32 v55, v134, v186
	v_lshlrev_b32_e32 v193, 16, v63
	v_and_b32_e32 v194, 0xffff0000, v63
	v_add_f32_e32 v52, v52, v167
	v_add_f32_e32 v53, v53, v168
	v_lshlrev_b32_e32 v159, 16, v82
	v_and_b32_e32 v160, 0xffff0000, v82
	v_add_f32_e32 v47, v47, v158
	v_and_b32_e32 v150, 0xffff0000, v77
	v_add_f32_e32 v46, v46, v149
	v_lshlrev_b32_e32 v141, 16, v93
	v_lshlrev_b32_e32 v133, 16, v89
	v_and_b32_e32 v134, 0xffff0000, v89
	v_add_f32_e32 v45, v45, v132
	v_and_b32_e32 v89, 0xffff0000, v100
	v_add_f32_e32 v44, v44, v76
	v_lshlrev_b32_e32 v68, 16, v112
	v_add_co_u32_e32 v0, vcc, 0x2000, v126
	v_add_f32_e32 v54, v54, v193
	v_add_f32_e32 v55, v55, v194
	v_lshlrev_b32_e32 v201, 16, v59
	v_and_b32_e32 v202, 0xffff0000, v59
	v_add_f32_e32 v52, v52, v159
	v_add_f32_e32 v53, v53, v160
	v_lshlrev_b32_e32 v151, 16, v78
	v_and_b32_e32 v152, 0xffff0000, v78
	v_add_f32_e32 v47, v47, v150
	v_and_b32_e32 v142, 0xffff0000, v93
	v_add_f32_e32 v46, v46, v141
	v_add_f32_e32 v45, v45, v89
	v_and_b32_e32 v77, 0xffff0000, v96
	v_add_f32_e32 v44, v44, v68
	v_lshlrev_b32_e32 v56, 16, v108
	v_addc_co_u32_e32 v1, vcc, 0, v127, vcc
	v_add_f32_e32 v54, v54, v201
	v_add_f32_e32 v55, v55, v202
	v_lshlrev_b32_e32 v209, 16, v75
	v_and_b32_e32 v210, 0xffff0000, v75
	v_add_f32_e32 v52, v52, v151
	v_add_f32_e32 v53, v53, v152
	v_lshlrev_b32_e32 v143, 16, v94
	v_and_b32_e32 v144, 0xffff0000, v94
	v_add_f32_e32 v47, v47, v142
	v_lshlrev_b32_e32 v135, 16, v90
	v_and_b32_e32 v136, 0xffff0000, v90
	v_add_f32_e32 v46, v46, v133
	v_lshlrev_b32_e32 v90, 16, v101
	v_add_f32_e32 v45, v45, v77
	v_and_b32_e32 v69, 0xffff0000, v112
	v_add_f32_e32 v96, v44, v56
	v_lshlrev_b32_e32 v44, 16, v116
	global_load_dwordx4 v[48:51], v[0:1], off
	global_load_dwordx4 v[40:43], v[0:1], off offset:2048
	v_add_co_u32_e32 v0, vcc, 0x3000, v126
	v_add_f32_e32 v54, v54, v209
	v_add_f32_e32 v55, v55, v210
	v_lshlrev_b32_e32 v169, 16, v71
	v_and_b32_e32 v170, 0xffff0000, v71
	v_add_f32_e32 v52, v52, v143
	v_add_f32_e32 v53, v53, v144
	v_lshlrev_b32_e32 v137, 16, v91
	v_and_b32_e32 v138, 0xffff0000, v91
	v_add_f32_e32 v47, v47, v134
	v_and_b32_e32 v91, 0xffff0000, v101
	v_add_f32_e32 v46, v46, v90
	v_lshlrev_b32_e32 v78, 16, v97
	v_add_f32_e32 v45, v45, v69
	v_and_b32_e32 v57, 0xffff0000, v108
	v_add_f32_e32 v96, v96, v44
	s_waitcnt vmcnt(5)
; __device__ __forceinline__ unsigned cvt_pk_bf16(float lo, float hi) { unsigned r; asm volatile("v_cvt_pk_bf16_f32 %0, %1, %2" : "=v"(r) : "v"(lo), "v"(hi)); return r; }
; #define UNPK8(q, f) const float f[8] = {bf_lo((q).x), bf_hi((q).x), bf_lo((q).y), bf_hi((q).y), bf_lo((q).z), bf_hi((q).z), bf_lo((q).w), bf_hi((q).w)}
; template <int W> __device__ __forceinline__ void pool_run(const bf16_t* up, bf16_t* dp, int t0) {
;     u32x4 q[W + 15];
; #pragma unroll
;     for (int i = 0; i < W + 15; ++i) { const int dt = i - (W - 1); const bool ok = (t0 + dt >= 0); const u32x4 v = *(const u32x4*)(up + (ptrdiff_t)(ok ? dt : 0) * PW); q[i] = ok ? v : (u32x4){0u, 0u, 0u, 0u}; }
;     float s[8];
; #pragma unroll
;     for (int e = 0; e < 8; ++e) s[e] = 0.f;
; #pragma unroll
;     for (int i = 0; i < W - 1; ++i) { UNPK8(q[i], f);
; #pragma unroll
;         for (int e = 0; e < 8; ++e) s[e] += f[e]; }
; #pragma unroll
;     for (int j = 0; j < 16; ++j) {
;         UNPK8(q[j + W - 1], cur);
; #pragma unroll
;         for (int e = 0; e < 8; ++e) s[e] += cur[e];
;         const int cnt = (t0 + j + 1) < W ? (t0 + j + 1) : W; const float inv = 1.0f / (float)cnt;
;         u32x4 o; o.x = cvt_pk_bf16(s[0] * inv - cur[0], s[1] * inv - cur[1]); o.y = cvt_pk_bf16(s[2] * inv - cur[2], s[3] * inv - cur[3]);
;         o.z = cvt_pk_bf16(s[4] * inv - cur[4], s[5] * inv - cur[5]); o.w = cvt_pk_bf16(s[6] * inv - cur[6], s[7] * inv - cur[7]);
;         *(u32x4*)(dp + (size_t)j * PW) = o;
;         UNPK8(q[j], old);
; #pragma unroll
;         for (int e = 0; e < 8; ++e) s[e] -= old[e];
;     }
; }
	v_lshlrev_b32_e32 v108, 16, v120
	v_addc_co_u32_e32 v1, vcc, 0, v127, vcc
	v_add_f32_e32 v54, v54, v169
	v_add_f32_e32 v55, v55, v170
	v_lshlrev_b32_e32 v161, 16, v83
	v_and_b32_e32 v162, 0xffff0000, v83
	v_lshlrev_b32_e32 v153, 16, v79
	v_and_b32_e32 v154, 0xffff0000, v79
	v_add_f32_e32 v52, v52, v135
	v_add_f32_e32 v53, v53, v136
	v_lshlrev_b32_e32 v92, 16, v102
	v_and_b32_e32 v93, 0xffff0000, v102
	v_add_f32_e32 v47, v47, v91
	v_and_b32_e32 v79, 0xffff0000, v97
	v_add_f32_e32 v46, v46, v78
	v_lshlrev_b32_e32 v70, 16, v113
	v_add_f32_e32 v97, v45, v57
	v_and_b32_e32 v45, 0xffff0000, v116
	v_add_f32_e32 v116, v96, v108
	v_min_u32_e32 v96, 15, v129
	global_load_dwordx4 v[36:39], v[0:1], off
	global_load_dwordx4 v[32:35], v[0:1], off offset:2048
	v_add_co_u32_e32 v0, vcc, 0x4000, v126
	v_add_f32_e32 v54, v54, v161
	v_add_f32_e32 v55, v55, v162
	v_add_f32_e32 v52, v52, v92
	v_add_f32_e32 v53, v53, v93
	v_lshlrev_b32_e32 v80, 16, v98
	v_and_b32_e32 v81, 0xffff0000, v98
	v_add_f32_e32 v47, v47, v79
	v_and_b32_e32 v71, 0xffff0000, v113
	v_add_f32_e32 v46, v46, v70
	v_lshlrev_b32_e32 v58, 16, v109
	v_add_u32_e32 v96, 1, v96
	v_addc_co_u32_e32 v1, vcc, 0, v127, vcc
	v_add_f32_e32 v54, v54, v153
	v_add_f32_e32 v55, v55, v154
	v_lshlrev_b32_e32 v145, 16, v95
	v_and_b32_e32 v146, 0xffff0000, v95
	v_add_f32_e32 v52, v52, v80
	v_add_f32_e32 v53, v53, v81
	v_lshlrev_b32_e32 v72, 16, v114
	v_and_b32_e32 v73, 0xffff0000, v114
	v_add_f32_e32 v47, v47, v71
	v_and_b32_e32 v59, 0xffff0000, v109
	v_add_f32_e32 v98, v46, v58
	v_lshlrev_b32_e32 v46, 16, v117
	v_add_f32_e32 v97, v97, v45
	v_and_b32_e32 v109, 0xffff0000, v120
	v_cvt_f32_ubyte0_e32 v96, v96
	global_load_dwordx4 v[28:31], v[0:1], off
	global_load_dwordx4 v[24:27], v[0:1], off offset:2048
	v_add_co_u32_e32 v0, vcc, 0x5000, v126
	v_add_f32_e32 v54, v54, v145
	v_add_f32_e32 v55, v55, v146
	v_lshlrev_b32_e32 v82, 16, v99
	v_and_b32_e32 v83, 0xffff0000, v99
	v_add_f32_e32 v52, v52, v72
	v_add_f32_e32 v53, v53, v73
	v_lshlrev_b32_e32 v60, 16, v110
	v_and_b32_e32 v61, 0xffff0000, v110
	v_add_f32_e32 v99, v47, v59
	v_and_b32_e32 v47, 0xffff0000, v117
	v_add_f32_e32 v98, v98, v46
	v_lshlrev_b32_e32 v110, 16, v121
	v_add_f32_e32 v117, v97, v109
	v_div_scale_f32 v97, s[12:13], v96, v96, 1.0
	v_addc_co_u32_e32 v1, vcc, 0, v127, vcc
	v_add_f32_e32 v54, v54, v137
	v_add_f32_e32 v55, v55, v138
	v_lshlrev_b32_e32 v94, 16, v103
	v_and_b32_e32 v95, 0xffff0000, v103
	v_add_f32_e32 v100, v52, v60
	v_add_f32_e32 v101, v53, v61
	v_lshlrev_b32_e32 v52, 16, v118
	v_and_b32_e32 v53, 0xffff0000, v118
	v_add_f32_e32 v118, v98, v110
	v_rcp_f32_e32 v98, v97
	global_load_dwordx4 v[20:23], v[0:1], off
	global_load_dwordx4 v[16:19], v[0:1], off offset:2048
	v_add_co_u32_e32 v0, vcc, 0x6000, v126
	v_add_f32_e32 v54, v54, v94
	v_add_f32_e32 v55, v55, v95
	v_addc_co_u32_e32 v1, vcc, 0, v127, vcc
	v_add_f32_e32 v54, v54, v82
	v_add_f32_e32 v55, v55, v83
	v_lshlrev_b32_e32 v74, 16, v115
	v_and_b32_e32 v75, 0xffff0000, v115
	global_load_dwordx4 v[12:15], v[0:1], off
	global_load_dwordx4 v[8:11], v[0:1], off offset:2048
	v_add_co_u32_e32 v0, vcc, 0x7000, v126
	v_add_f32_e32 v54, v54, v74
	v_add_f32_e32 v55, v55, v75
	v_lshlrev_b32_e32 v62, 16, v111
	v_and_b32_e32 v63, 0xffff0000, v111
	v_add_f32_e32 v99, v99, v47
	v_and_b32_e32 v111, 0xffff0000, v121
	v_addc_co_u32_e32 v1, vcc, 0, v127, vcc
	v_add_f32_e32 v102, v54, v62
	v_add_f32_e32 v103, v55, v63
	v_lshlrev_b32_e32 v54, 16, v119
	v_and_b32_e32 v55, 0xffff0000, v119
	v_add_f32_e32 v119, v99, v111
	v_fma_f32 v99, -v97, v98, 1.0
	v_fmac_f32_e32 v98, v99, v98
	v_div_scale_f32 v99, vcc, 1.0, v96, 1.0
	v_mul_f32_e32 v120, v99, v98
	v_fma_f32 v121, -v97, v120, v99
	v_fmac_f32_e32 v120, v121, v98
	v_fma_f32 v97, -v97, v120, v99
	v_div_fmas_f32 v97, v97, v98, v120
	v_div_fixup_f32 v99, v97, v96, 1.0
	v_add_f32_e32 v100, v100, v52
	v_add_f32_e32 v101, v101, v53
	v_lshlrev_b32_e32 v112, 16, v122
	v_and_b32_e32 v113, 0xffff0000, v122
	v_fma_f32 v96, v99, v116, -v108
	v_fma_f32 v97, v99, v117, -v109
	global_load_dwordx4 v[4:7], v[0:1], off
	s_nop 0
	global_load_dwordx4 v[0:3], v[0:1], off offset:2048
	v_add_f32_e32 v102, v102, v54
	v_add_f32_e32 v103, v103, v55
	v_lshlrev_b32_e32 v114, 16, v123
	v_and_b32_e32 v115, 0xffff0000, v123
	v_add_f32_e32 v100, v100, v112
	v_add_f32_e32 v101, v101, v113
	v_cvt_pk_bf16_f32 v96, v96, v97
	v_fma_f32 v97, v99, v118, -v110
	v_fma_f32 v98, v99, v119, -v111
	v_add_f32_e32 v102, v102, v114
	v_add_f32_e32 v103, v103, v115
	v_cvt_pk_bf16_f32 v97, v97, v98
	v_fma_f32 v98, v99, v100, -v112
	v_fma_f32 v108, v99, v101, -v113
	v_cvt_pk_bf16_f32 v98, v98, v108
	v_fma_f32 v108, v99, v102, -v114
	v_fma_f32 v99, v99, v103, -v115
	v_cvt_pk_bf16_f32 v99, v108, v99
	global_store_dwordx4 v[124:125], v[96:99], off sc1
	s_waitcnt vmcnt(15)
; __device__ __forceinline__ unsigned cvt_pk_bf16(float lo, float hi) { unsigned r; asm volatile("v_cvt_pk_bf16_f32 %0, %1, %2" : "=v"(r) : "v"(lo), "v"(hi)); return r; }
; #define UNPK8(q, f) const float f[8] = {bf_lo((q).x), bf_hi((q).x), bf_lo((q).y), bf_hi((q).y), bf_lo((q).z), bf_hi((q).z), bf_lo((q).w), bf_hi((q).w)}
; template <int W> __device__ __forceinline__ void pool_run(const bf16_t* up, bf16_t* dp, int t0) {
;     u32x4 q[W + 15];
; #pragma unroll
;     for (int i = 0; i < W + 15; ++i) { const int dt = i - (W - 1); const bool ok = (t0 + dt >= 0); const u32x4 v = *(const u32x4*)(up + (ptrdiff_t)(ok ? dt : 0) * PW); q[i] = ok ? v : (u32x4){0u, 0u, 0u, 0u}; }
;     float s[8];
; #pragma unroll
;     for (int e = 0; e < 8; ++e) s[e] = 0.f;
; #pragma unroll
;     for (int i = 0; i < W - 1; ++i) { UNPK8(q[i], f);
; #pragma unroll
;         for (int e = 0; e < 8; ++e) s[e] += f[e]; }
; #pragma unroll
;     for (int j = 0; j < 16; ++j) {
;         UNPK8(q[j + W - 1], cur);
; #pragma unroll
;         for (int e = 0; e < 8; ++e) s[e] += cur[e];
;         const int cnt = (t0 + j + 1) < W ? (t0 + j + 1) : W; const float inv = 1.0f / (float)cnt;
;         u32x4 o; o.x = cvt_pk_bf16(s[0] * inv - cur[0], s[1] * inv - cur[1]); o.y = cvt_pk_bf16(s[2] * inv - cur[2], s[3] * inv - cur[3]);
;         o.z = cvt_pk_bf16(s[4] * inv - cur[4], s[5] * inv - cur[5]); o.w = cvt_pk_bf16(s[6] * inv - cur[6], s[7] * inv - cur[7]);
;         *(u32x4*)(dp + (size_t)j * PW) = o;
;         UNPK8(q[j], old);
; #pragma unroll
;         for (int e = 0; e < 8; ++e) s[e] -= old[e];
;     }
; }
	v_lshlrev_b32_e32 v108, 16, v104
	v_and_b32_e32 v104, 0xffff0000, v104
	v_sub_f32_e32 v96, v116, v171
	v_add_f32_e32 v112, v96, v108
	v_min_u32_e32 v96, 14, v129
	v_add_u32_e32 v96, 2, v96
	v_sub_f32_e32 v97, v117, v172
	v_cvt_f32_ubyte0_e32 v96, v96
	v_sub_f32_e32 v98, v118, v173
	v_lshlrev_b32_e32 v109, 16, v105
	v_add_f32_e32 v113, v97, v104
	v_div_scale_f32 v97, s[12:13], v96, v96, 1.0
	v_add_f32_e32 v114, v98, v109
	v_rcp_f32_e32 v98, v97
	v_sub_f32_e32 v99, v119, v174
	v_and_b32_e32 v105, 0xffff0000, v105
	v_add_f32_e32 v115, v99, v105
	v_fma_f32 v99, -v97, v98, 1.0
	v_fmac_f32_e32 v98, v99, v98
	v_div_scale_f32 v99, vcc, 1.0, v96, 1.0
	v_mul_f32_e32 v116, v99, v98
	v_fma_f32 v117, -v97, v116, v99
	v_fmac_f32_e32 v116, v117, v98
	v_fma_f32 v97, -v97, v116, v99
	v_div_fmas_f32 v97, v97, v98, v116
	v_div_fixup_f32 v99, v97, v96, 1.0
	v_sub_f32_e32 v100, v100, v175
	v_sub_f32_e32 v101, v101, v176
	v_lshlrev_b32_e32 v110, 16, v106
	v_and_b32_e32 v106, 0xffff0000, v106
	v_fma_f32 v96, v99, v112, -v108
	v_fma_f32 v97, v99, v113, -v104
	v_sub_f32_e32 v102, v102, v177
	v_sub_f32_e32 v103, v103, v178
	v_lshlrev_b32_e32 v111, 16, v107
	v_and_b32_e32 v107, 0xffff0000, v107
	v_add_f32_e32 v100, v100, v110
	v_add_f32_e32 v101, v101, v106
	v_cvt_pk_bf16_f32 v96, v96, v97
	v_fma_f32 v97, v99, v114, -v109
	v_fma_f32 v98, v99, v115, -v105
	v_add_f32_e32 v102, v102, v111
	v_add_f32_e32 v103, v103, v107
	v_cvt_pk_bf16_f32 v97, v97, v98
	v_fma_f32 v98, v99, v100, -v110
	v_fma_f32 v104, v99, v101, -v106
	v_cvt_pk_bf16_f32 v98, v98, v104
	v_fma_f32 v104, v99, v102, -v111
	v_fma_f32 v99, v99, v103, -v107
	v_cvt_pk_bf16_f32 v99, v104, v99
	global_store_dwordx4 v[124:125], v[96:99], off offset:2048 sc1
	s_waitcnt vmcnt(15)
	v_lshlrev_b32_e32 v104, 16, v84
	v_and_b32_e32 v84, 0xffff0000, v84
	v_sub_f32_e32 v96, v112, v179
	v_add_f32_e32 v108, v96, v104
	v_min_u32_e32 v96, 13, v129
	v_add_u32_e32 v96, 3, v96
	v_sub_f32_e32 v97, v113, v180
	v_cvt_f32_ubyte0_e32 v96, v96
	v_sub_f32_e32 v98, v114, v181
	v_lshlrev_b32_e32 v105, 16, v85
	v_add_f32_e32 v109, v97, v84
	v_div_scale_f32 v97, s[12:13], v96, v96, 1.0
	v_add_f32_e32 v110, v98, v105
	v_rcp_f32_e32 v98, v97
	v_sub_f32_e32 v99, v115, v182
	v_and_b32_e32 v85, 0xffff0000, v85
	v_add_f32_e32 v111, v99, v85
	v_fma_f32 v99, -v97, v98, 1.0
	v_fmac_f32_e32 v98, v99, v98
	v_div_scale_f32 v99, vcc, 1.0, v96, 1.0
	v_mul_f32_e32 v112, v99, v98
	v_fma_f32 v113, -v97, v112, v99
	v_fmac_f32_e32 v112, v113, v98
	v_fma_f32 v97, -v97, v112, v99
	v_div_fmas_f32 v97, v97, v98, v112
	v_div_fixup_f32 v96, v97, v96, 1.0
	v_sub_f32_e32 v100, v100, v183
	v_sub_f32_e32 v101, v101, v184
	v_lshlrev_b32_e32 v106, 16, v86
	v_and_b32_e32 v86, 0xffff0000, v86
	v_fma_f32 v97, v96, v108, -v104
	v_fma_f32 v84, v96, v109, -v84
	v_sub_f32_e32 v102, v102, v185
	v_sub_f32_e32 v103, v103, v186
	v_lshlrev_b32_e32 v107, 16, v87
	v_and_b32_e32 v87, 0xffff0000, v87
	v_add_f32_e32 v100, v100, v106
	v_add_f32_e32 v101, v101, v86
	v_cvt_pk_bf16_f32 v84, v97, v84
	v_fma_f32 v97, v96, v110, -v105
	v_fma_f32 v85, v96, v111, -v85
	s_movk_i32 s9, 0x1000
	v_add_f32_e32 v102, v102, v107
	v_add_f32_e32 v103, v103, v87
	v_cvt_pk_bf16_f32 v85, v97, v85
	v_fma_f32 v97, v96, v100, -v106
	v_fma_f32 v86, v96, v101, -v86
	v_cvt_pk_bf16_f32 v86, v97, v86
	v_fma_f32 v97, v96, v102, -v107
	v_fma_f32 v87, v96, v103, -v87
	v_add_co_u32_e32 v96, vcc, s9, v124
	s_movk_i32 s10, 0x2000
	v_cvt_pk_bf16_f32 v87, v97, v87
	s_nop 0
	v_addc_co_u32_e32 v97, vcc, 0, v125, vcc
	v_add_co_u32_e32 v98, vcc, s10, v124
	s_waitcnt vmcnt(14)
	v_lshlrev_b32_e32 v104, 16, v64
	v_addc_co_u32_e32 v99, vcc, 0, v125, vcc
	global_store_dwordx4 v[98:99], v[84:87], off offset:-4096 sc1
	v_and_b32_e32 v64, 0xffff0000, v64
	v_sub_f32_e32 v101, v101, v192
	v_sub_f32_e32 v84, v108, v187
	v_min_u32_e32 v108, 12, v129
	v_add_u32_e32 v108, 4, v108
	v_cvt_f32_ubyte0_e32 v108, v108
	v_sub_f32_e32 v85, v109, v188
	v_div_scale_f32 v109, s[10:11], v108, v108, 1.0
	v_sub_f32_e32 v86, v110, v189
	v_rcp_f32_e32 v110, v109
	v_sub_f32_e32 v87, v111, v190
	v_lshlrev_b32_e32 v105, 16, v65
	v_and_b32_e32 v65, 0xffff0000, v65
	v_fma_f32 v111, -v109, v110, 1.0
	v_fmac_f32_e32 v110, v111, v110
	v_div_scale_f32 v111, vcc, 1.0, v108, 1.0
	v_mul_f32_e32 v112, v111, v110
	v_fma_f32 v113, -v109, v112, v111
	v_fmac_f32_e32 v112, v113, v110
	v_fma_f32 v109, -v109, v112, v111
	v_div_fmas_f32 v109, v109, v110, v112
	v_lshlrev_b32_e32 v106, 16, v66
	v_and_b32_e32 v66, 0xffff0000, v66
	v_add_f32_e32 v84, v84, v104
	v_add_f32_e32 v85, v85, v64
	v_div_fixup_f32 v108, v109, v108, 1.0
	v_sub_f32_e32 v100, v100, v191
	v_sub_f32_e32 v103, v103, v194
	v_lshlrev_b32_e32 v107, 16, v67
	v_and_b32_e32 v67, 0xffff0000, v67
	v_add_f32_e32 v86, v86, v105
	v_add_f32_e32 v87, v87, v65
	v_add_f32_e32 v101, v101, v66
	v_fma_f32 v104, v108, v84, -v104
	v_fma_f32 v64, v108, v85, -v64
	v_sub_f32_e32 v102, v102, v193
	v_add_f32_e32 v100, v100, v106
	v_add_f32_e32 v103, v103, v67
	v_cvt_pk_bf16_f32 v64, v104, v64
	v_fma_f32 v104, v108, v86, -v105
	v_fma_f32 v65, v108, v87, -v65
	v_fma_f32 v66, v108, v101, -v66
	v_add_f32_e32 v102, v102, v107
	v_cvt_pk_bf16_f32 v65, v104, v65
	v_fma_f32 v104, v108, v100, -v106
	v_cvt_pk_bf16_f32 v66, v104, v66
	v_fma_f32 v67, v108, v103, -v67
	v_fma_f32 v104, v108, v102, -v107
	v_cvt_pk_bf16_f32 v67, v104, v67
	global_store_dwordx4 v[96:97], v[64:67], off offset:2048 sc1
	s_waitcnt vmcnt(15)
; __device__ __forceinline__ unsigned cvt_pk_bf16(float lo, float hi) { unsigned r; asm volatile("v_cvt_pk_bf16_f32 %0, %1, %2" : "=v"(r) : "v"(lo), "v"(hi)); return r; }
; #define UNPK8(q, f) const float f[8] = {bf_lo((q).x), bf_hi((q).x), bf_lo((q).y), bf_hi((q).y), bf_lo((q).z), bf_hi((q).z), bf_lo((q).w), bf_hi((q).w)}
; template <int W> __device__ __forceinline__ void pool_run(const bf16_t* up, bf16_t* dp, int t0) {
;     u32x4 q[W + 15];
; #pragma unroll
;     for (int i = 0; i < W + 15; ++i) { const int dt = i - (W - 1); const bool ok = (t0 + dt >= 0); const u32x4 v = *(const u32x4*)(up + (ptrdiff_t)(ok ? dt : 0) * PW); q[i] = ok ? v : (u32x4){0u, 0u, 0u, 0u}; }
;     float s[8];
; #pragma unroll
;     for (int e = 0; e < 8; ++e) s[e] = 0.f;
; #pragma unroll
;     for (int i = 0; i < W - 1; ++i) { UNPK8(q[i], f);
; #pragma unroll
;         for (int e = 0; e < 8; ++e) s[e] += f[e]; }
; #pragma unroll
;     for (int j = 0; j < 16; ++j) {
;         UNPK8(q[j + W - 1], cur);
; #pragma unroll
;         for (int e = 0; e < 8; ++e) s[e] += cur[e];
;         const int cnt = (t0 + j + 1) < W ? (t0 + j + 1) : W; const float inv = 1.0f / (float)cnt;
;         u32x4 o; o.x = cvt_pk_bf16(s[0] * inv - cur[0], s[1] * inv - cur[1]); o.y = cvt_pk_bf16(s[2] * inv - cur[2], s[3] * inv - cur[3]);
;         o.z = cvt_pk_bf16(s[4] * inv - cur[4], s[5] * inv - cur[5]); o.w = cvt_pk_bf16(s[6] * inv - cur[6], s[7] * inv - cur[7]);
;         *(u32x4*)(dp + (size_t)j * PW) = o;
;         UNPK8(q[j], old);
; #pragma unroll
;         for (int e = 0; e < 8; ++e) s[e] -= old[e];
;     }
; }
	v_lshlrev_b32_e32 v96, 16, v48
	v_and_b32_e32 v48, 0xffff0000, v48
	v_sub_f32_e32 v66, v86, v197
	v_sub_f32_e32 v86, v102, v201
	v_min_u32_e32 v102, 11, v129
	v_add_u32_e32 v102, 5, v102
	v_cvt_f32_ubyte0_e32 v102, v102
	v_sub_f32_e32 v67, v87, v198
	v_sub_f32_e32 v87, v103, v202
	v_div_scale_f32 v103, s[10:11], v102, v102, 1.0
	v_rcp_f32_e32 v104, v103
	v_sub_f32_e32 v64, v84, v195
	v_sub_f32_e32 v65, v85, v196
	v_lshlrev_b32_e32 v97, 16, v49
	v_fma_f32 v105, -v103, v104, 1.0
	v_fmac_f32_e32 v104, v105, v104
	v_div_scale_f32 v105, vcc, 1.0, v102, 1.0
	v_mul_f32_e32 v106, v105, v104
	v_fma_f32 v107, -v103, v106, v105
	v_fmac_f32_e32 v106, v107, v104
	v_fma_f32 v103, -v103, v106, v105
	v_div_fmas_f32 v103, v103, v104, v106
	v_and_b32_e32 v49, 0xffff0000, v49
	v_add_f32_e32 v64, v64, v96
	v_add_f32_e32 v65, v65, v48
	v_div_fixup_f32 v102, v103, v102, 1.0
	v_sub_f32_e32 v84, v100, v199
	v_sub_f32_e32 v85, v101, v200
	v_lshlrev_b32_e32 v100, 16, v50
	v_and_b32_e32 v50, 0xffff0000, v50
	v_add_f32_e32 v66, v66, v97
	v_add_f32_e32 v67, v67, v49
	v_fma_f32 v96, v102, v64, -v96
	v_fma_f32 v48, v102, v65, -v48
	v_lshlrev_b32_e32 v101, 16, v51
	v_and_b32_e32 v51, 0xffff0000, v51
	v_add_f32_e32 v84, v84, v100
	v_add_f32_e32 v85, v85, v50
	v_cvt_pk_bf16_f32 v48, v96, v48
	v_fma_f32 v96, v102, v66, -v97
	v_fma_f32 v49, v102, v67, -v49
	v_add_f32_e32 v86, v86, v101
	v_add_f32_e32 v87, v87, v51
	v_cvt_pk_bf16_f32 v49, v96, v49
	v_fma_f32 v96, v102, v84, -v100
	v_fma_f32 v50, v102, v85, -v50
	v_cvt_pk_bf16_f32 v50, v96, v50
	v_fma_f32 v96, v102, v86, -v101
	v_fma_f32 v51, v102, v87, -v51
	v_cvt_pk_bf16_f32 v51, v96, v51
	v_min_u32_e32 v96, 10, v129
	v_add_u32_e32 v96, 6, v96
	v_cvt_f32_ubyte0_e32 v96, v96
	v_div_scale_f32 v97, s[10:11], v96, v96, 1.0
	v_rcp_f32_e32 v100, v97
	global_store_dwordx4 v[98:99], v[48:51], off sc1
	s_movk_i32 s7, 0x3000
	s_movk_i32 s8, 0x4000
	v_fma_f32 v101, -v97, v100, 1.0
	v_fmac_f32_e32 v100, v101, v100
	v_div_scale_f32 v101, vcc, 1.0, v96, 1.0
	v_mul_f32_e32 v102, v101, v100
	v_fma_f32 v103, -v97, v102, v101
	v_fmac_f32_e32 v102, v103, v100
	v_fma_f32 v97, -v97, v102, v101
	v_sub_f32_e32 v48, v64, v203
	v_sub_f32_e32 v49, v65, v204
	v_sub_f32_e32 v64, v84, v207
	s_waitcnt vmcnt(15)
	v_lshlrev_b32_e32 v84, 16, v40
	v_and_b32_e32 v40, 0xffff0000, v40
	v_div_fmas_f32 v97, v97, v100, v102
	v_sub_f32_e32 v50, v66, v205
	v_sub_f32_e32 v51, v67, v206
	v_sub_f32_e32 v65, v85, v208
	v_lshlrev_b32_e32 v85, 16, v41
	v_and_b32_e32 v41, 0xffff0000, v41
	v_add_f32_e32 v48, v48, v84
	v_add_f32_e32 v49, v49, v40
	v_div_fixup_f32 v96, v97, v96, 1.0
	v_sub_f32_e32 v66, v86, v209
	v_sub_f32_e32 v67, v87, v210
	v_lshlrev_b32_e32 v86, 16, v42
	v_and_b32_e32 v42, 0xffff0000, v42
	v_lshlrev_b32_e32 v87, 16, v43
	v_and_b32_e32 v43, 0xffff0000, v43
	v_add_f32_e32 v50, v50, v85
	v_add_f32_e32 v51, v51, v41
	v_fma_f32 v84, v96, v48, -v84
	v_fma_f32 v40, v96, v49, -v40
	v_add_f32_e32 v64, v64, v86
	v_add_f32_e32 v65, v65, v42
	v_add_f32_e32 v67, v67, v43
	v_cvt_pk_bf16_f32 v40, v84, v40
	v_fma_f32 v84, v96, v50, -v85
	v_fma_f32 v41, v96, v51, -v41
	v_add_f32_e32 v66, v66, v87
	v_cvt_pk_bf16_f32 v41, v84, v41
	v_fma_f32 v84, v96, v64, -v86
	v_fma_f32 v42, v96, v65, -v42
	v_fma_f32 v43, v96, v67, -v43
	v_cvt_pk_bf16_f32 v42, v84, v42
	v_fma_f32 v84, v96, v66, -v87
	v_cvt_pk_bf16_f32 v43, v84, v43
	global_store_dwordx4 v[98:99], v[40:43], off offset:2048 sc1
	s_movk_i32 s5, 0x5000
	s_movk_i32 s6, 0x6000
	v_sub_f32_e32 v40, v48, v163
	v_sub_f32_e32 v48, v64, v167
	s_waitcnt vmcnt(15)
	v_lshlrev_b32_e32 v64, 16, v36
	v_add_f32_e32 v84, v40, v64
	v_min_u32_e32 v40, 9, v129
	v_add_u32_e32 v40, 7, v40
	v_sub_f32_e32 v41, v49, v164
	v_and_b32_e32 v36, 0xffff0000, v36
	v_cvt_f32_ubyte0_e32 v40, v40
	v_sub_f32_e32 v42, v50, v165
	v_sub_f32_e32 v49, v65, v168
	v_lshlrev_b32_e32 v65, 16, v37
	v_add_f32_e32 v85, v41, v36
	v_div_scale_f32 v41, s[10:11], v40, v40, 1.0
	v_add_f32_e32 v86, v42, v65
	v_rcp_f32_e32 v42, v41
	v_sub_f32_e32 v43, v51, v166
	v_and_b32_e32 v37, 0xffff0000, v37
	v_add_f32_e32 v87, v43, v37
	v_fma_f32 v43, -v41, v42, 1.0
	v_fmac_f32_e32 v42, v43, v42
	v_div_scale_f32 v43, vcc, 1.0, v40, 1.0
	v_mul_f32_e32 v96, v43, v42
	v_fma_f32 v97, -v41, v96, v43
	v_fmac_f32_e32 v96, v97, v42
	v_fma_f32 v41, -v41, v96, v43
	v_div_fmas_f32 v41, v41, v42, v96
	v_div_fixup_f32 v40, v41, v40, 1.0
	v_sub_f32_e32 v50, v66, v169
	v_lshlrev_b32_e32 v66, 16, v38
	v_and_b32_e32 v38, 0xffff0000, v38
	v_fma_f32 v41, v40, v84, -v64
	v_fma_f32 v36, v40, v85, -v36
	v_sub_f32_e32 v51, v67, v170
	v_lshlrev_b32_e32 v67, 16, v39
	v_and_b32_e32 v39, 0xffff0000, v39
	v_add_f32_e32 v48, v48, v66
	v_add_f32_e32 v49, v49, v38
	v_cvt_pk_bf16_f32 v36, v41, v36
	v_fma_f32 v41, v40, v86, -v65
	v_fma_f32 v37, v40, v87, -v37
	v_add_f32_e32 v50, v50, v67
	v_add_f32_e32 v51, v51, v39
	v_cvt_pk_bf16_f32 v37, v41, v37
	v_fma_f32 v41, v40, v48, -v66
	v_fma_f32 v38, v40, v49, -v38
	v_cvt_pk_bf16_f32 v38, v41, v38
	v_fma_f32 v41, v40, v50, -v67
	v_fma_f32 v39, v40, v51, -v39
	v_add_co_u32_e32 v40, vcc, s7, v124
	v_cvt_pk_bf16_f32 v39, v41, v39
	s_waitcnt vmcnt(14)
; __device__ __forceinline__ unsigned cvt_pk_bf16(float lo, float hi) { unsigned r; asm volatile("v_cvt_pk_bf16_f32 %0, %1, %2" : "=v"(r) : "v"(lo), "v"(hi)); return r; }
; #define UNPK8(q, f) const float f[8] = {bf_lo((q).x), bf_hi((q).x), bf_lo((q).y), bf_hi((q).y), bf_lo((q).z), bf_hi((q).z), bf_lo((q).w), bf_hi((q).w)}
; template <int W> __device__ __forceinline__ void pool_run(const bf16_t* up, bf16_t* dp, int t0) {
;     u32x4 q[W + 15];
; #pragma unroll
;     for (int i = 0; i < W + 15; ++i) { const int dt = i - (W - 1); const bool ok = (t0 + dt >= 0); const u32x4 v = *(const u32x4*)(up + (ptrdiff_t)(ok ? dt : 0) * PW); q[i] = ok ? v : (u32x4){0u, 0u, 0u, 0u}; }
;     float s[8];
; #pragma unroll
;     for (int e = 0; e < 8; ++e) s[e] = 0.f;
; #pragma unroll
;     for (int i = 0; i < W - 1; ++i) { UNPK8(q[i], f);
; #pragma unroll
;         for (int e = 0; e < 8; ++e) s[e] += f[e]; }
; #pragma unroll
;     for (int j = 0; j < 16; ++j) {
;         UNPK8(q[j + W - 1], cur);
; #pragma unroll
;         for (int e = 0; e < 8; ++e) s[e] += cur[e];
;         const int cnt = (t0 + j + 1) < W ? (t0 + j + 1) : W; const float inv = 1.0f / (float)cnt;
;         u32x4 o; o.x = cvt_pk_bf16(s[0] * inv - cur[0], s[1] * inv - cur[1]); o.y = cvt_pk_bf16(s[2] * inv - cur[2], s[3] * inv - cur[3]);
;         o.z = cvt_pk_bf16(s[4] * inv - cur[4], s[5] * inv - cur[5]); o.w = cvt_pk_bf16(s[6] * inv - cur[6], s[7] * inv - cur[7]);
;         *(u32x4*)(dp + (size_t)j * PW) = o;
;         UNPK8(q[j], old);
; #pragma unroll
;         for (int e = 0; e < 8; ++e) s[e] -= old[e];
;     }
; }
	v_lshlrev_b32_e32 v64, 16, v32
	v_addc_co_u32_e32 v41, vcc, 0, v125, vcc
	v_add_co_u32_e32 v42, vcc, s8, v124
	v_and_b32_e32 v32, 0xffff0000, v32
	s_nop 0
	v_addc_co_u32_e32 v43, vcc, 0, v125, vcc
	global_store_dwordx4 v[42:43], v[36:39], off offset:-4096 sc1
	v_sub_f32_e32 v49, v49, v160
	v_lshlrev_b32_e32 v65, 16, v33
	v_sub_f32_e32 v36, v84, v155
	v_min_u32_e32 v84, 8, v129
	v_add_u32_e32 v84, 8, v84
	v_cvt_f32_ubyte0_e32 v84, v84
	v_sub_f32_e32 v37, v85, v156
	v_div_scale_f32 v85, s[8:9], v84, v84, 1.0
	v_sub_f32_e32 v38, v86, v157
	v_rcp_f32_e32 v86, v85
	v_sub_f32_e32 v39, v87, v158
	v_and_b32_e32 v33, 0xffff0000, v33
	v_lshlrev_b32_e32 v66, 16, v34
	v_fma_f32 v87, -v85, v86, 1.0
	v_fmac_f32_e32 v86, v87, v86
	v_div_scale_f32 v87, vcc, 1.0, v84, 1.0
	v_mul_f32_e32 v96, v87, v86
	v_fma_f32 v97, -v85, v96, v87
	v_fmac_f32_e32 v96, v97, v86
	v_fma_f32 v85, -v85, v96, v87
	v_div_fmas_f32 v85, v85, v86, v96
	v_and_b32_e32 v34, 0xffff0000, v34
	v_add_f32_e32 v36, v36, v64
	v_add_f32_e32 v37, v37, v32
	v_div_fixup_f32 v84, v85, v84, 1.0
	v_sub_f32_e32 v48, v48, v159
	v_sub_f32_e32 v51, v51, v162
	v_lshlrev_b32_e32 v67, 16, v35
	v_and_b32_e32 v35, 0xffff0000, v35
	v_add_f32_e32 v38, v38, v65
	v_add_f32_e32 v39, v39, v33
	v_add_f32_e32 v49, v49, v34
	v_fma_f32 v64, v84, v36, -v64
	v_fma_f32 v32, v84, v37, -v32
	v_sub_f32_e32 v50, v50, v161
	v_add_f32_e32 v48, v48, v66
	v_add_f32_e32 v51, v51, v35
	v_cvt_pk_bf16_f32 v32, v64, v32
	v_fma_f32 v64, v84, v38, -v65
	v_fma_f32 v33, v84, v39, -v33
	v_fma_f32 v34, v84, v49, -v34
	v_add_f32_e32 v50, v50, v67
	v_cvt_pk_bf16_f32 v33, v64, v33
	v_fma_f32 v64, v84, v48, -v66
	v_cvt_pk_bf16_f32 v34, v64, v34
	v_fma_f32 v35, v84, v51, -v35
	v_fma_f32 v64, v84, v50, -v67
	v_cvt_pk_bf16_f32 v35, v64, v35
	global_store_dwordx4 v[40:41], v[32:35], off offset:2048 sc1
	s_waitcnt vmcnt(15)
	v_lshlrev_b32_e32 v40, 16, v28
	v_and_b32_e32 v28, 0xffff0000, v28
	v_sub_f32_e32 v34, v38, v149
	v_sub_f32_e32 v38, v50, v153
	v_min_u32_e32 v50, 7, v129
	v_add_u32_e32 v50, 9, v50
	v_cvt_f32_ubyte0_e32 v50, v50
	v_sub_f32_e32 v35, v39, v150
	v_sub_f32_e32 v39, v51, v154
	v_div_scale_f32 v51, s[8:9], v50, v50, 1.0
	v_rcp_f32_e32 v64, v51
	v_sub_f32_e32 v32, v36, v147
	v_sub_f32_e32 v33, v37, v148
	v_lshlrev_b32_e32 v41, 16, v29
	v_fma_f32 v65, -v51, v64, 1.0
	v_fmac_f32_e32 v64, v65, v64
	v_div_scale_f32 v65, vcc, 1.0, v50, 1.0
	v_mul_f32_e32 v66, v65, v64
	v_fma_f32 v67, -v51, v66, v65
	v_fmac_f32_e32 v66, v67, v64
	v_fma_f32 v51, -v51, v66, v65
	v_div_fmas_f32 v51, v51, v64, v66
	v_and_b32_e32 v29, 0xffff0000, v29
	v_add_f32_e32 v32, v32, v40
	v_add_f32_e32 v33, v33, v28
	v_div_fixup_f32 v50, v51, v50, 1.0
	v_sub_f32_e32 v36, v48, v151
	v_sub_f32_e32 v37, v49, v152
	v_lshlrev_b32_e32 v48, 16, v30
	v_and_b32_e32 v30, 0xffff0000, v30
	v_add_f32_e32 v34, v34, v41
	v_add_f32_e32 v35, v35, v29
	v_fma_f32 v40, v50, v32, -v40
	v_fma_f32 v28, v50, v33, -v28
	v_lshlrev_b32_e32 v49, 16, v31
	v_and_b32_e32 v31, 0xffff0000, v31
	v_add_f32_e32 v36, v36, v48
	v_add_f32_e32 v37, v37, v30
	v_cvt_pk_bf16_f32 v28, v40, v28
	v_fma_f32 v40, v50, v34, -v41
	v_fma_f32 v29, v50, v35, -v29
	v_add_f32_e32 v38, v38, v49
	v_add_f32_e32 v39, v39, v31
	v_cvt_pk_bf16_f32 v29, v40, v29
	v_fma_f32 v40, v50, v36, -v48
	v_fma_f32 v30, v50, v37, -v30
	v_cvt_pk_bf16_f32 v30, v40, v30
	v_fma_f32 v40, v50, v38, -v49
	v_fma_f32 v31, v50, v39, -v31
	v_cvt_pk_bf16_f32 v31, v40, v31
	v_min_u32_e32 v40, 6, v129
	v_add_u32_e32 v40, 10, v40
	v_cvt_f32_ubyte0_e32 v40, v40
	v_div_scale_f32 v41, s[8:9], v40, v40, 1.0
	v_rcp_f32_e32 v48, v41
	global_store_dwordx4 v[42:43], v[28:31], off sc1
	s_movk_i32 s4, 0x7000
	v_fma_f32 v49, -v41, v48, 1.0
	v_fmac_f32_e32 v48, v49, v48
	v_div_scale_f32 v49, vcc, 1.0, v40, 1.0
	v_mul_f32_e32 v50, v49, v48
	v_fma_f32 v51, -v41, v50, v49
	v_fmac_f32_e32 v50, v51, v48
	v_fma_f32 v41, -v41, v50, v49
	v_sub_f32_e32 v28, v32, v139
	v_sub_f32_e32 v29, v33, v140
	v_sub_f32_e32 v32, v36, v143
	s_waitcnt vmcnt(15)
	v_lshlrev_b32_e32 v36, 16, v24
	v_and_b32_e32 v24, 0xffff0000, v24
	v_div_fmas_f32 v41, v41, v48, v50
	v_sub_f32_e32 v30, v34, v141
	v_sub_f32_e32 v31, v35, v142
	v_sub_f32_e32 v33, v37, v144
	v_lshlrev_b32_e32 v37, 16, v25
	v_and_b32_e32 v25, 0xffff0000, v25
	v_add_f32_e32 v28, v28, v36
	v_add_f32_e32 v29, v29, v24
	v_div_fixup_f32 v40, v41, v40, 1.0
	v_sub_f32_e32 v34, v38, v145
	v_sub_f32_e32 v35, v39, v146
	v_lshlrev_b32_e32 v38, 16, v26
	v_and_b32_e32 v26, 0xffff0000, v26
	v_lshlrev_b32_e32 v39, 16, v27
	v_and_b32_e32 v27, 0xffff0000, v27
	v_add_f32_e32 v30, v30, v37
	v_add_f32_e32 v31, v31, v25
	v_fma_f32 v36, v40, v28, -v36
	v_fma_f32 v24, v40, v29, -v24
	v_add_f32_e32 v32, v32, v38
	v_add_f32_e32 v33, v33, v26
	v_add_f32_e32 v35, v35, v27
	v_cvt_pk_bf16_f32 v24, v36, v24
	v_fma_f32 v36, v40, v30, -v37
	v_fma_f32 v25, v40, v31, -v25
	v_add_f32_e32 v34, v34, v39
	v_cvt_pk_bf16_f32 v25, v36, v25
	v_fma_f32 v36, v40, v32, -v38
	v_fma_f32 v26, v40, v33, -v26
	v_fma_f32 v27, v40, v35, -v27
	v_cvt_pk_bf16_f32 v26, v36, v26
	v_fma_f32 v36, v40, v34, -v39
	v_cvt_pk_bf16_f32 v27, v36, v27
	global_store_dwordx4 v[42:43], v[24:27], off offset:2048 sc1
	s_nop 1
	v_sub_f32_e32 v24, v28, v131
	v_sub_f32_e32 v28, v32, v135
	s_waitcnt vmcnt(15)
; __device__ __forceinline__ unsigned cvt_pk_bf16(float lo, float hi) { unsigned r; asm volatile("v_cvt_pk_bf16_f32 %0, %1, %2" : "=v"(r) : "v"(lo), "v"(hi)); return r; }
; #define UNPK8(q, f) const float f[8] = {bf_lo((q).x), bf_hi((q).x), bf_lo((q).y), bf_hi((q).y), bf_lo((q).z), bf_hi((q).z), bf_lo((q).w), bf_hi((q).w)}
; template <int W> __device__ __forceinline__ void pool_run(const bf16_t* up, bf16_t* dp, int t0) {
;     u32x4 q[W + 15];
; #pragma unroll
;     for (int i = 0; i < W + 15; ++i) { const int dt = i - (W - 1); const bool ok = (t0 + dt >= 0); const u32x4 v = *(const u32x4*)(up + (ptrdiff_t)(ok ? dt : 0) * PW); q[i] = ok ? v : (u32x4){0u, 0u, 0u, 0u}; }
;     float s[8];
; #pragma unroll
;     for (int e = 0; e < 8; ++e) s[e] = 0.f;
; #pragma unroll
;     for (int i = 0; i < W - 1; ++i) { UNPK8(q[i], f);
; #pragma unroll
;         for (int e = 0; e < 8; ++e) s[e] += f[e]; }
; #pragma unroll
;     for (int j = 0; j < 16; ++j) {
;         UNPK8(q[j + W - 1], cur);
; #pragma unroll
;         for (int e = 0; e < 8; ++e) s[e] += cur[e];
;         const int cnt = (t0 + j + 1) < W ? (t0 + j + 1) : W; const float inv = 1.0f / (float)cnt;
;         u32x4 o; o.x = cvt_pk_bf16(s[0] * inv - cur[0], s[1] * inv - cur[1]); o.y = cvt_pk_bf16(s[2] * inv - cur[2], s[3] * inv - cur[3]);
;         o.z = cvt_pk_bf16(s[4] * inv - cur[4], s[5] * inv - cur[5]); o.w = cvt_pk_bf16(s[6] * inv - cur[6], s[7] * inv - cur[7]);
;         *(u32x4*)(dp + (size_t)j * PW) = o;
;         UNPK8(q[j], old);
; #pragma unroll
;         for (int e = 0; e < 8; ++e) s[e] -= old[e];
;     }
; }
	v_lshlrev_b32_e32 v32, 16, v20
	v_add_f32_e32 v36, v24, v32
	v_min_u32_e32 v24, 5, v129
	v_add_u32_e32 v24, 11, v24
	v_sub_f32_e32 v25, v29, v132
	v_and_b32_e32 v20, 0xffff0000, v20
	v_cvt_f32_ubyte0_e32 v24, v24
	v_sub_f32_e32 v26, v30, v133
	v_sub_f32_e32 v29, v33, v136
	v_lshlrev_b32_e32 v33, 16, v21
	v_add_f32_e32 v37, v25, v20
	v_div_scale_f32 v25, s[8:9], v24, v24, 1.0
	v_add_f32_e32 v38, v26, v33
	v_rcp_f32_e32 v26, v25
	v_sub_f32_e32 v27, v31, v134
	v_and_b32_e32 v21, 0xffff0000, v21
	v_add_f32_e32 v39, v27, v21
	v_fma_f32 v27, -v25, v26, 1.0
	v_fmac_f32_e32 v26, v27, v26
	v_div_scale_f32 v27, vcc, 1.0, v24, 1.0
	v_mul_f32_e32 v40, v27, v26
	v_fma_f32 v41, -v25, v40, v27
	v_fmac_f32_e32 v40, v41, v26
	v_fma_f32 v25, -v25, v40, v27
	v_div_fmas_f32 v25, v25, v26, v40
	v_div_fixup_f32 v24, v25, v24, 1.0
	v_sub_f32_e32 v30, v34, v137
	v_lshlrev_b32_e32 v34, 16, v22
	v_and_b32_e32 v22, 0xffff0000, v22
	v_fma_f32 v25, v24, v36, -v32
	v_fma_f32 v20, v24, v37, -v20
	v_sub_f32_e32 v31, v35, v138
	v_lshlrev_b32_e32 v35, 16, v23
	v_and_b32_e32 v23, 0xffff0000, v23
	v_add_f32_e32 v28, v28, v34
	v_add_f32_e32 v29, v29, v22
	v_cvt_pk_bf16_f32 v20, v25, v20
	v_fma_f32 v25, v24, v38, -v33
	v_fma_f32 v21, v24, v39, -v21
	v_add_f32_e32 v30, v30, v35
	v_add_f32_e32 v31, v31, v23
	v_cvt_pk_bf16_f32 v21, v25, v21
	v_fma_f32 v25, v24, v28, -v34
	v_fma_f32 v22, v24, v29, -v22
	v_cvt_pk_bf16_f32 v22, v25, v22
	v_fma_f32 v25, v24, v30, -v35
	v_fma_f32 v23, v24, v31, -v23
	v_add_co_u32_e32 v24, vcc, s5, v124
	v_cvt_pk_bf16_f32 v23, v25, v23
	s_waitcnt vmcnt(14)
	v_lshlrev_b32_e32 v32, 16, v16
	v_addc_co_u32_e32 v25, vcc, 0, v125, vcc
	v_add_co_u32_e32 v26, vcc, s6, v124
	v_and_b32_e32 v16, 0xffff0000, v16
	s_nop 0
	v_addc_co_u32_e32 v27, vcc, 0, v125, vcc
	global_store_dwordx4 v[26:27], v[20:23], off offset:-4096 sc1
	v_sub_f32_e32 v29, v29, v93
	v_lshlrev_b32_e32 v33, 16, v17
	v_sub_f32_e32 v20, v36, v88
	v_min_u32_e32 v36, 4, v129
	v_add_u32_e32 v36, 12, v36
	v_cvt_f32_ubyte0_e32 v36, v36
	v_sub_f32_e32 v21, v37, v89
	v_div_scale_f32 v37, s[6:7], v36, v36, 1.0
	v_sub_f32_e32 v22, v38, v90
	v_rcp_f32_e32 v38, v37
	v_sub_f32_e32 v23, v39, v91
	v_and_b32_e32 v17, 0xffff0000, v17
	v_lshlrev_b32_e32 v34, 16, v18
	v_fma_f32 v39, -v37, v38, 1.0
	v_fmac_f32_e32 v38, v39, v38
	v_div_scale_f32 v39, vcc, 1.0, v36, 1.0
	v_mul_f32_e32 v40, v39, v38
	v_fma_f32 v41, -v37, v40, v39
	v_fmac_f32_e32 v40, v41, v38
	v_fma_f32 v37, -v37, v40, v39
	v_div_fmas_f32 v37, v37, v38, v40
	v_and_b32_e32 v18, 0xffff0000, v18
	v_add_f32_e32 v20, v20, v32
	v_add_f32_e32 v21, v21, v16
	v_div_fixup_f32 v36, v37, v36, 1.0
	v_sub_f32_e32 v28, v28, v92
	v_sub_f32_e32 v31, v31, v95
	v_lshlrev_b32_e32 v35, 16, v19
	v_and_b32_e32 v19, 0xffff0000, v19
	v_add_f32_e32 v22, v22, v33
	v_add_f32_e32 v23, v23, v17
	v_add_f32_e32 v29, v29, v18
	v_fma_f32 v32, v36, v20, -v32
	v_fma_f32 v16, v36, v21, -v16
	v_sub_f32_e32 v30, v30, v94
	v_add_f32_e32 v28, v28, v34
	v_add_f32_e32 v31, v31, v19
	v_cvt_pk_bf16_f32 v16, v32, v16
	v_fma_f32 v32, v36, v22, -v33
	v_fma_f32 v17, v36, v23, -v17
	v_fma_f32 v18, v36, v29, -v18
	v_add_f32_e32 v30, v30, v35
	v_cvt_pk_bf16_f32 v17, v32, v17
	v_fma_f32 v32, v36, v28, -v34
	v_cvt_pk_bf16_f32 v18, v32, v18
	v_fma_f32 v19, v36, v31, -v19
	v_fma_f32 v32, v36, v30, -v35
	v_cvt_pk_bf16_f32 v19, v32, v19
	global_store_dwordx4 v[24:25], v[16:19], off offset:2048 sc1
	s_waitcnt vmcnt(15)
	v_lshlrev_b32_e32 v24, 16, v12
	v_and_b32_e32 v12, 0xffff0000, v12
	v_sub_f32_e32 v18, v22, v78
	v_sub_f32_e32 v22, v30, v82
	v_min_u32_e32 v30, 3, v129
	v_add_u32_e32 v30, 13, v30
	v_cvt_f32_ubyte0_e32 v30, v30
	v_sub_f32_e32 v19, v23, v79
	v_sub_f32_e32 v23, v31, v83
	v_div_scale_f32 v31, s[6:7], v30, v30, 1.0
	v_rcp_f32_e32 v32, v31
	v_sub_f32_e32 v16, v20, v76
	v_sub_f32_e32 v17, v21, v77
	v_lshlrev_b32_e32 v25, 16, v13
	v_fma_f32 v33, -v31, v32, 1.0
	v_fmac_f32_e32 v32, v33, v32
	v_div_scale_f32 v33, vcc, 1.0, v30, 1.0
	v_mul_f32_e32 v34, v33, v32
	v_fma_f32 v35, -v31, v34, v33
	v_fmac_f32_e32 v34, v35, v32
	v_fma_f32 v31, -v31, v34, v33
	v_div_fmas_f32 v31, v31, v32, v34
	v_and_b32_e32 v13, 0xffff0000, v13
	v_add_f32_e32 v16, v16, v24
	v_add_f32_e32 v17, v17, v12
	v_div_fixup_f32 v30, v31, v30, 1.0
	v_sub_f32_e32 v20, v28, v80
	v_sub_f32_e32 v21, v29, v81
	v_lshlrev_b32_e32 v28, 16, v14
	v_and_b32_e32 v14, 0xffff0000, v14
	v_add_f32_e32 v18, v18, v25
	v_add_f32_e32 v19, v19, v13
	v_fma_f32 v24, v30, v16, -v24
	v_fma_f32 v12, v30, v17, -v12
	v_lshlrev_b32_e32 v29, 16, v15
	v_and_b32_e32 v15, 0xffff0000, v15
	v_add_f32_e32 v20, v20, v28
	v_add_f32_e32 v21, v21, v14
	v_cvt_pk_bf16_f32 v12, v24, v12
	v_fma_f32 v24, v30, v18, -v25
	v_fma_f32 v13, v30, v19, -v13
	v_add_f32_e32 v22, v22, v29
	v_add_f32_e32 v23, v23, v15
	v_cvt_pk_bf16_f32 v13, v24, v13
	v_fma_f32 v24, v30, v20, -v28
	v_fma_f32 v14, v30, v21, -v14
	v_cvt_pk_bf16_f32 v14, v24, v14
	v_fma_f32 v24, v30, v22, -v29
	v_fma_f32 v15, v30, v23, -v15
	v_cvt_pk_bf16_f32 v15, v24, v15
	v_min_u32_e32 v24, 2, v129
	v_add_u32_e32 v24, 14, v24
	v_cvt_f32_ubyte0_e32 v24, v24
	v_div_scale_f32 v25, s[6:7], v24, v24, 1.0
	v_rcp_f32_e32 v28, v25
	global_store_dwordx4 v[26:27], v[12:15], off sc1
	v_fma_f32 v29, -v25, v28, 1.0
	v_fmac_f32_e32 v28, v29, v28
	v_div_scale_f32 v29, vcc, 1.0, v24, 1.0
	v_mul_f32_e32 v30, v29, v28
	v_fma_f32 v31, -v25, v30, v29
	v_fmac_f32_e32 v30, v31, v28
	v_fma_f32 v25, -v25, v30, v29
	v_sub_f32_e32 v12, v16, v68
	v_sub_f32_e32 v13, v17, v69
	v_sub_f32_e32 v16, v20, v72
	s_waitcnt vmcnt(15)
; __device__ __forceinline__ unsigned cvt_pk_bf16(float lo, float hi) { unsigned r; asm volatile("v_cvt_pk_bf16_f32 %0, %1, %2" : "=v"(r) : "v"(lo), "v"(hi)); return r; }
; #define UNPK8(q, f) const float f[8] = {bf_lo((q).x), bf_hi((q).x), bf_lo((q).y), bf_hi((q).y), bf_lo((q).z), bf_hi((q).z), bf_lo((q).w), bf_hi((q).w)}
; template <int W> __device__ __forceinline__ void pool_run(const bf16_t* up, bf16_t* dp, int t0) {
;     u32x4 q[W + 15];
; #pragma unroll
;     for (int i = 0; i < W + 15; ++i) { const int dt = i - (W - 1); const bool ok = (t0 + dt >= 0); const u32x4 v = *(const u32x4*)(up + (ptrdiff_t)(ok ? dt : 0) * PW); q[i] = ok ? v : (u32x4){0u, 0u, 0u, 0u}; }
;     float s[8];
; #pragma unroll
;     for (int e = 0; e < 8; ++e) s[e] = 0.f;
; #pragma unroll
;     for (int i = 0; i < W - 1; ++i) { UNPK8(q[i], f);
; #pragma unroll
;         for (int e = 0; e < 8; ++e) s[e] += f[e]; }
; #pragma unroll
;     for (int j = 0; j < 16; ++j) {
;         UNPK8(q[j + W - 1], cur);
; #pragma unroll
;         for (int e = 0; e < 8; ++e) s[e] += cur[e];
;         const int cnt = (t0 + j + 1) < W ? (t0 + j + 1) : W; const float inv = 1.0f / (float)cnt;
;         u32x4 o; o.x = cvt_pk_bf16(s[0] * inv - cur[0], s[1] * inv - cur[1]); o.y = cvt_pk_bf16(s[2] * inv - cur[2], s[3] * inv - cur[3]);
;         o.z = cvt_pk_bf16(s[4] * inv - cur[4], s[5] * inv - cur[5]); o.w = cvt_pk_bf16(s[6] * inv - cur[6], s[7] * inv - cur[7]);
;         *(u32x4*)(dp + (size_t)j * PW) = o;
;         UNPK8(q[j], old);
; #pragma unroll
;         for (int e = 0; e < 8; ++e) s[e] -= old[e];
;     }
; }
	v_lshlrev_b32_e32 v20, 16, v8
	v_and_b32_e32 v8, 0xffff0000, v8
	v_div_fmas_f32 v25, v25, v28, v30
	v_sub_f32_e32 v14, v18, v70
	v_sub_f32_e32 v15, v19, v71
	v_sub_f32_e32 v17, v21, v73
	v_lshlrev_b32_e32 v21, 16, v9
	v_and_b32_e32 v9, 0xffff0000, v9
	v_add_f32_e32 v12, v12, v20
	v_add_f32_e32 v13, v13, v8
	v_div_fixup_f32 v24, v25, v24, 1.0
	v_sub_f32_e32 v18, v22, v74
	v_sub_f32_e32 v19, v23, v75
	v_lshlrev_b32_e32 v22, 16, v10
	v_and_b32_e32 v10, 0xffff0000, v10
	v_lshlrev_b32_e32 v23, 16, v11
	v_and_b32_e32 v11, 0xffff0000, v11
	v_add_f32_e32 v14, v14, v21
	v_add_f32_e32 v15, v15, v9
	v_fma_f32 v20, v24, v12, -v20
	v_fma_f32 v8, v24, v13, -v8
	v_add_f32_e32 v16, v16, v22
	v_add_f32_e32 v17, v17, v10
	v_add_f32_e32 v19, v19, v11
	v_cvt_pk_bf16_f32 v8, v20, v8
	v_fma_f32 v20, v24, v14, -v21
	v_fma_f32 v9, v24, v15, -v9
	v_add_f32_e32 v18, v18, v23
	v_cvt_pk_bf16_f32 v9, v20, v9
	v_fma_f32 v20, v24, v16, -v22
	v_fma_f32 v10, v24, v17, -v10
	v_fma_f32 v11, v24, v19, -v11
	v_cvt_pk_bf16_f32 v10, v20, v10
	v_fma_f32 v20, v24, v18, -v23
	v_cvt_pk_bf16_f32 v11, v20, v11
	global_store_dwordx4 v[26:27], v[8:11], off offset:2048 sc1
	s_nop 1
	v_sub_f32_e32 v8, v12, v56
	v_sub_f32_e32 v12, v16, v60
	s_waitcnt vmcnt(15)
	v_lshlrev_b32_e32 v16, 16, v4
	v_sub_f32_e32 v9, v13, v57
	v_and_b32_e32 v4, 0xffff0000, v4
	v_add_f32_e32 v20, v8, v16
	v_div_scale_f32 v8, s[6:7], v130, v130, 1.0
	v_add_f32_e32 v21, v9, v4
	v_rcp_f32_e32 v9, v8
	v_sub_f32_e32 v10, v14, v58
	v_sub_f32_e32 v11, v15, v59
	v_sub_f32_e32 v13, v17, v61
	v_fma_f32 v22, -v8, v9, 1.0
	v_fmac_f32_e32 v9, v22, v9
	v_div_scale_f32 v22, vcc, 1.0, v130, 1.0
	v_mul_f32_e32 v23, v22, v9
	v_fma_f32 v24, -v8, v23, v22
	v_fmac_f32_e32 v23, v24, v9
	v_fma_f32 v8, -v8, v23, v22
	v_div_fmas_f32 v8, v8, v9, v23
	v_lshlrev_b32_e32 v17, 16, v5
	v_and_b32_e32 v5, 0xffff0000, v5
	v_div_fixup_f32 v8, v8, v130, 1.0
	v_sub_f32_e32 v14, v18, v62
	v_lshlrev_b32_e32 v18, 16, v6
	v_and_b32_e32 v6, 0xffff0000, v6
	v_add_f32_e32 v10, v10, v17
	v_add_f32_e32 v11, v11, v5
	v_fma_f32 v9, v8, v20, -v16
	v_fma_f32 v4, v8, v21, -v4
	v_sub_f32_e32 v15, v19, v63
	v_lshlrev_b32_e32 v19, 16, v7
	v_and_b32_e32 v7, 0xffff0000, v7
	v_add_f32_e32 v12, v12, v18
	v_add_f32_e32 v13, v13, v6
	v_cvt_pk_bf16_f32 v4, v9, v4
	v_fma_f32 v9, v8, v10, -v17
	v_fma_f32 v5, v8, v11, -v5
	v_add_f32_e32 v14, v14, v19
	v_add_f32_e32 v15, v15, v7
	v_cvt_pk_bf16_f32 v5, v9, v5
	v_fma_f32 v9, v8, v12, -v18
	v_fma_f32 v6, v8, v13, -v6
	v_cvt_pk_bf16_f32 v6, v9, v6
	v_fma_f32 v9, v8, v14, -v19
	v_fma_f32 v7, v8, v15, -v7
	v_add_co_u32_e32 v8, vcc, s4, v124
	v_cvt_pk_bf16_f32 v7, v9, v7
	s_mov_b32 s4, 0x3d800000
	s_nop 0
	v_addc_co_u32_e32 v9, vcc, 0, v125, vcc
	global_store_dwordx4 v[8:9], v[4:7], off sc1
	v_sub_f32_e32 v8, v12, v52
	s_waitcnt vmcnt(15)
	v_lshlrev_b32_e32 v12, 16, v0
	v_sub_f32_e32 v4, v20, v44
	v_sub_f32_e32 v5, v21, v45
	v_and_b32_e32 v0, 0xffff0000, v0
	v_sub_f32_e32 v6, v10, v46
	v_sub_f32_e32 v7, v11, v47
	v_sub_f32_e32 v9, v13, v53
	v_lshlrev_b32_e32 v13, 16, v1
	v_and_b32_e32 v1, 0xffff0000, v1
	v_add_f32_e32 v4, v4, v12
	v_add_f32_e32 v5, v5, v0
	v_sub_f32_e32 v10, v14, v54
	v_lshlrev_b32_e32 v14, 16, v2
	v_and_b32_e32 v2, 0xffff0000, v2
	v_add_f32_e32 v6, v6, v13
	v_add_f32_e32 v7, v7, v1
	v_fma_f32 v4, v4, s4, -v12
	v_fma_f32 v0, v5, s4, -v0
	v_sub_f32_e32 v11, v15, v55
	v_lshlrev_b32_e32 v15, 16, v3
	v_and_b32_e32 v3, 0xffff0000, v3
	v_add_f32_e32 v8, v8, v14
	v_add_f32_e32 v9, v9, v2
	v_cvt_pk_bf16_f32 v0, v4, v0
	v_fma_f32 v4, v6, s4, -v13
	v_fma_f32 v1, v7, s4, -v1
	v_add_f32_e32 v10, v10, v15
	v_add_f32_e32 v11, v11, v3
	v_cvt_pk_bf16_f32 v1, v4, v1
	v_fma_f32 v4, v8, s4, -v14
	v_fma_f32 v2, v9, s4, -v2
	v_cvt_pk_bf16_f32 v2, v4, v2
	v_fma_f32 v4, v10, s4, -v15
	v_fma_f32 v3, v11, s4, -v3
	v_cvt_pk_bf16_f32 v3, v4, v3

; __device__ __forceinline__ unsigned cvt_pk_bf16(float lo, float hi) { unsigned r; asm volatile("v_cvt_pk_bf16_f32 %0, %1, %2" : "=v"(r) : "v"(lo), "v"(hi)); return r; }
; #define UNPK8(q, f) const float f[8] = {bf_lo((q).x), bf_hi((q).x), bf_lo((q).y), bf_hi((q).y), bf_lo((q).z), bf_hi((q).z), bf_lo((q).w), bf_hi((q).w)}
; template <int W> __device__ __forceinline__ void pool_run(const bf16_t* up, bf16_t* dp, int t0) {
;     u32x4 q[W + 15];
; #pragma unroll
;     for (int i = 0; i < W + 15; ++i) { const int dt = i - (W - 1); const bool ok = (t0 + dt >= 0); const u32x4 v = *(const u32x4*)(up + (ptrdiff_t)(ok ? dt : 0) * PW); q[i] = ok ? v : (u32x4){0u, 0u, 0u, 0u}; }
;     float s[8];
; #pragma unroll
;     for (int e = 0; e < 8; ++e) s[e] = 0.f;
; #pragma unroll
;     for (int i = 0; i < W - 1; ++i) { UNPK8(q[i], f);
; #pragma unroll
;         for (int e = 0; e < 8; ++e) s[e] += f[e]; }
; #pragma unroll
;     for (int j = 0; j < 16; ++j) {
;         UNPK8(q[j + W - 1], cur);
; #pragma unroll
;         for (int e = 0; e < 8; ++e) s[e] += cur[e];
;         const int cnt = (t0 + j + 1) < W ? (t0 + j + 1) : W; const float inv = 1.0f / (float)cnt;
;         u32x4 o; o.x = cvt_pk_bf16(s[0] * inv - cur[0], s[1] * inv - cur[1]); o.y = cvt_pk_bf16(s[2] * inv - cur[2], s[3] * inv - cur[3]);
;         o.z = cvt_pk_bf16(s[4] * inv - cur[4], s[5] * inv - cur[5]); o.w = cvt_pk_bf16(s[6] * inv - cur[6], s[7] * inv - cur[7]);
;         *(u32x4*)(dp + (size_t)j * PW) = o;
;         UNPK8(q[j], old);
; #pragma unroll
;         for (int e = 0; e < 8; ++e) s[e] -= old[e];
;     }
; }
.LBB0_456:
	s_or_b64 exec, exec, s[4:5]
	global_load_dwordx4 v[66:69], v[126:127], off
	global_load_dwordx4 v[70:73], v[126:127], off offset:2048
	v_add_co_u32_e32 v0, vcc, 0x1000, v126
	s_waitcnt vmcnt(2)
	v_lshlrev_b32_e32 v65, 16, v56
	v_addc_co_u32_e32 v1, vcc, 0, v127, vcc
	global_load_dwordx4 v[74:77], v[0:1], off
	global_load_dwordx4 v[48:51], v[0:1], off offset:2048
	v_add_co_u32_e32 v0, vcc, 0x2000, v126
	v_lshlrev_b32_e32 v79, 16, v58
	s_nop 0
	v_addc_co_u32_e32 v1, vcc, 0, v127, vcc
	global_load_dwordx4 v[44:47], v[0:1], off
	global_load_dwordx4 v[40:43], v[0:1], off offset:2048
	v_add_f32_e32 v81, 0, v65
	v_add_f32_e32 v85, 0, v79
	v_lshlrev_b32_e32 v89, 16, v52
	v_lshlrev_b32_e32 v93, 16, v54
	v_and_b32_e32 v90, 0xffff0000, v52
	v_add_f32_e32 v52, v81, v89
	v_add_f32_e32 v81, v85, v93
	v_lshlrev_b32_e32 v85, 16, v60
	v_add_co_u32_e32 v0, vcc, 0x3000, v126
	v_and_b32_e32 v56, 0xffff0000, v56
	v_add_f32_e32 v52, v52, v85
	v_addc_co_u32_e32 v1, vcc, 0, v127, vcc
	v_lshlrev_b32_e32 v78, 16, v57
	v_and_b32_e32 v58, 0xffff0000, v58
	v_add_f32_e32 v82, 0, v56
	global_load_dwordx4 v[36:39], v[0:1], off
	global_load_dwordx4 v[32:35], v[0:1], off offset:2048
	v_add_co_u32_e32 v0, vcc, 0x4000, v126
	v_add_f32_e32 v83, 0, v78
	v_add_f32_e32 v86, 0, v58
	v_lshlrev_b32_e32 v91, 16, v53
	v_and_b32_e32 v92, 0xffff0000, v53
	v_and_b32_e32 v94, 0xffff0000, v54
	v_add_f32_e32 v53, v82, v90
	v_and_b32_e32 v60, 0xffff0000, v60
	v_addc_co_u32_e32 v1, vcc, 0, v127, vcc
	v_add_f32_e32 v54, v83, v91
	v_add_f32_e32 v82, v86, v94
	v_lshlrev_b32_e32 v86, 16, v61
	v_add_f32_e32 v53, v53, v60
	global_load_dwordx4 v[28:31], v[0:1], off
	global_load_dwordx4 v[24:27], v[0:1], off offset:2048
	v_add_co_u32_e32 v0, vcc, 0x5000, v126
	v_add_f32_e32 v54, v54, v86
	s_nop 0
	v_addc_co_u32_e32 v1, vcc, 0, v127, vcc
	v_and_b32_e32 v57, 0xffff0000, v57
	global_load_dwordx4 v[20:23], v[0:1], off
	global_load_dwordx4 v[16:19], v[0:1], off offset:2048
	v_add_co_u32_e32 v0, vcc, 0x6000, v126
	v_add_f32_e32 v84, 0, v57
	s_nop 0
	v_addc_co_u32_e32 v1, vcc, 0, v127, vcc
	v_lshlrev_b32_e32 v95, 16, v55
	v_and_b32_e32 v96, 0xffff0000, v55
	v_add_f32_e32 v55, v84, v92
	v_and_b32_e32 v61, 0xffff0000, v61
	global_load_dwordx4 v[12:15], v[0:1], off
	global_load_dwordx4 v[8:11], v[0:1], off offset:2048
	v_add_co_u32_e32 v0, vcc, 0x7000, v126
	v_add_f32_e32 v55, v55, v61
	s_nop 0
	v_addc_co_u32_e32 v1, vcc, 0, v127, vcc
	v_lshlrev_b32_e32 v80, 16, v59
	v_and_b32_e32 v59, 0xffff0000, v59
	v_add_f32_e32 v87, 0, v80
	v_add_f32_e32 v88, 0, v59
	v_add_f32_e32 v83, v87, v95
	v_lshlrev_b32_e32 v87, 16, v62
	v_and_b32_e32 v62, 0xffff0000, v62
	v_add_f32_e32 v84, v88, v96
	v_lshlrev_b32_e32 v88, 16, v63
	v_and_b32_e32 v63, 0xffff0000, v63
	s_waitcnt vmcnt(13)
	v_lshlrev_b32_e32 v97, 16, v66
	v_add_f32_e32 v101, v52, v97
	v_min_u32_e32 v52, 3, v129
	v_add_u32_e32 v52, 1, v52
	v_and_b32_e32 v66, 0xffff0000, v66
	v_cvt_f32_ubyte0_e32 v52, v52
	v_lshlrev_b32_e32 v98, 16, v67
	v_add_f32_e32 v102, v53, v66
	v_div_scale_f32 v53, s[12:13], v52, v52, 1.0
	v_add_f32_e32 v103, v54, v98
	v_rcp_f32_e32 v54, v53
	v_and_b32_e32 v67, 0xffff0000, v67
	v_add_f32_e32 v104, v55, v67
	v_add_f32_e32 v81, v81, v87
	v_fma_f32 v55, -v53, v54, 1.0
	v_fmac_f32_e32 v54, v55, v54
	v_div_scale_f32 v55, vcc, 1.0, v52, 1.0
	v_mul_f32_e32 v105, v55, v54
	v_fma_f32 v106, -v53, v105, v55
	v_fmac_f32_e32 v105, v106, v54
	v_fma_f32 v53, -v53, v105, v55
	v_div_fmas_f32 v53, v53, v54, v105
	v_div_fixup_f32 v55, v53, v52, 1.0
	v_add_f32_e32 v82, v82, v62
	v_lshlrev_b32_e32 v99, 16, v68
	v_and_b32_e32 v68, 0xffff0000, v68
	v_fma_f32 v52, v55, v101, -v97
	v_fma_f32 v53, v55, v102, -v66
	global_load_dwordx4 v[4:7], v[0:1], off
	s_nop 0
	global_load_dwordx4 v[0:3], v[0:1], off offset:2048
	v_add_f32_e32 v83, v83, v88
	v_add_f32_e32 v84, v84, v63
	v_lshlrev_b32_e32 v100, 16, v69
	v_and_b32_e32 v69, 0xffff0000, v69
	v_add_f32_e32 v81, v81, v99
	v_add_f32_e32 v82, v82, v68
	v_cvt_pk_bf16_f32 v52, v52, v53
	v_fma_f32 v53, v55, v103, -v98
	v_fma_f32 v54, v55, v104, -v67
	v_add_f32_e32 v83, v83, v100
	v_add_f32_e32 v84, v84, v69
	v_cvt_pk_bf16_f32 v53, v53, v54
	v_fma_f32 v54, v55, v81, -v99
	v_fma_f32 v105, v55, v82, -v68
	v_cvt_pk_bf16_f32 v54, v54, v105
	v_fma_f32 v105, v55, v83, -v100
	v_fma_f32 v55, v55, v84, -v69
	v_cvt_pk_bf16_f32 v55, v105, v55
	global_store_dwordx4 v[124:125], v[52:55], off sc1
	v_sub_f32_e32 v59, v84, v59
	s_movk_i32 s7, 0x1000
	v_sub_f32_e32 v52, v101, v65
	s_waitcnt vmcnt(15)
	v_lshlrev_b32_e32 v65, 16, v70
	v_sub_f32_e32 v53, v102, v56
	v_sub_f32_e32 v56, v81, v79
	v_add_f32_e32 v81, v52, v65
	v_min_u32_e32 v52, 2, v129
	v_add_u32_e32 v52, 2, v52
	v_and_b32_e32 v70, 0xffff0000, v70
	v_cvt_f32_ubyte0_e32 v52, v52
	v_sub_f32_e32 v54, v103, v78
	v_sub_f32_e32 v55, v104, v57
	v_sub_f32_e32 v57, v82, v58
	v_lshlrev_b32_e32 v78, 16, v71
	v_add_f32_e32 v82, v53, v70
	v_div_scale_f32 v53, s[12:13], v52, v52, 1.0
	v_sub_f32_e32 v58, v83, v80
	v_add_f32_e32 v83, v54, v78
	v_rcp_f32_e32 v54, v53
	v_and_b32_e32 v71, 0xffff0000, v71
	v_add_f32_e32 v84, v55, v71
	v_lshlrev_b32_e32 v79, 16, v72
	v_fma_f32 v55, -v53, v54, 1.0
	v_fmac_f32_e32 v54, v55, v54
	v_div_scale_f32 v55, vcc, 1.0, v52, 1.0
	v_mul_f32_e32 v101, v55, v54
	v_fma_f32 v102, -v53, v101, v55
	v_fmac_f32_e32 v101, v102, v54
	v_fma_f32 v53, -v53, v101, v55
	v_div_fmas_f32 v53, v53, v54, v101
	v_div_fixup_f32 v55, v53, v52, 1.0
	v_and_b32_e32 v72, 0xffff0000, v72
	v_fma_f32 v52, v55, v81, -v65
	v_fma_f32 v53, v55, v82, -v70
	v_lshlrev_b32_e32 v80, 16, v73
	v_and_b32_e32 v73, 0xffff0000, v73
	v_add_f32_e32 v56, v56, v79
	v_add_f32_e32 v57, v57, v72
	v_cvt_pk_bf16_f32 v52, v52, v53
	v_fma_f32 v53, v55, v83, -v78
	v_fma_f32 v54, v55, v84, -v71
	v_add_f32_e32 v58, v58, v80
	v_add_f32_e32 v59, v59, v73
	v_cvt_pk_bf16_f32 v53, v53, v54
	v_fma_f32 v54, v55, v56, -v79
	v_fma_f32 v101, v55, v57, -v72
	v_cvt_pk_bf16_f32 v54, v54, v101
	v_fma_f32 v101, v55, v58, -v80
	v_fma_f32 v55, v55, v59, -v73
	v_cvt_pk_bf16_f32 v55, v101, v55
	global_store_dwordx4 v[124:125], v[52:55], off offset:2048 sc1
	v_sub_f32_e32 v56, v56, v93
	v_sub_f32_e32 v57, v57, v94
	v_sub_f32_e32 v52, v81, v89
	s_waitcnt vmcnt(15)
; __device__ __forceinline__ unsigned cvt_pk_bf16(float lo, float hi) { unsigned r; asm volatile("v_cvt_pk_bf16_f32 %0, %1, %2" : "=v"(r) : "v"(lo), "v"(hi)); return r; }
; #define UNPK8(q, f) const float f[8] = {bf_lo((q).x), bf_hi((q).x), bf_lo((q).y), bf_hi((q).y), bf_lo((q).z), bf_hi((q).z), bf_lo((q).w), bf_hi((q).w)}
; template <int W> __device__ __forceinline__ void pool_run(const bf16_t* up, bf16_t* dp, int t0) {
;     u32x4 q[W + 15];
; #pragma unroll
;     for (int i = 0; i < W + 15; ++i) { const int dt = i - (W - 1); const bool ok = (t0 + dt >= 0); const u32x4 v = *(const u32x4*)(up + (ptrdiff_t)(ok ? dt : 0) * PW); q[i] = ok ? v : (u32x4){0u, 0u, 0u, 0u}; }
;     float s[8];
; #pragma unroll
;     for (int e = 0; e < 8; ++e) s[e] = 0.f;
; #pragma unroll
;     for (int i = 0; i < W - 1; ++i) { UNPK8(q[i], f);
; #pragma unroll
;         for (int e = 0; e < 8; ++e) s[e] += f[e]; }
; #pragma unroll
;     for (int j = 0; j < 16; ++j) {
;         UNPK8(q[j + W - 1], cur);
; #pragma unroll
;         for (int e = 0; e < 8; ++e) s[e] += cur[e];
;         const int cnt = (t0 + j + 1) < W ? (t0 + j + 1) : W; const float inv = 1.0f / (float)cnt;
;         u32x4 o; o.x = cvt_pk_bf16(s[0] * inv - cur[0], s[1] * inv - cur[1]); o.y = cvt_pk_bf16(s[2] * inv - cur[2], s[3] * inv - cur[3]);
;         o.z = cvt_pk_bf16(s[4] * inv - cur[4], s[5] * inv - cur[5]); o.w = cvt_pk_bf16(s[6] * inv - cur[6], s[7] * inv - cur[7]);
;         *(u32x4*)(dp + (size_t)j * PW) = o;
;         UNPK8(q[j], old);
; #pragma unroll
;         for (int e = 0; e < 8; ++e) s[e] -= old[e];
;     }
; }
	v_lshlrev_b32_e32 v81, 16, v74
	v_sub_f32_e32 v53, v82, v90
	v_and_b32_e32 v74, 0xffff0000, v74
	v_add_f32_e32 v89, v52, v81
	v_div_scale_f32 v52, s[12:13], v64, v64, 1.0
	v_add_f32_e32 v90, v53, v74
	v_rcp_f32_e32 v53, v52
	v_sub_f32_e32 v54, v83, v91
	v_lshlrev_b32_e32 v82, 16, v75
	v_add_f32_e32 v91, v54, v82
	v_fma_f32 v54, -v52, v53, 1.0
	v_sub_f32_e32 v55, v84, v92
	v_and_b32_e32 v75, 0xffff0000, v75
	v_fmac_f32_e32 v53, v54, v53
	v_div_scale_f32 v54, vcc, 1.0, v64, 1.0
	v_lshlrev_b32_e32 v83, 16, v76
	v_add_f32_e32 v92, v55, v75
	v_mul_f32_e32 v55, v54, v53
	v_add_f32_e32 v93, v56, v83
	v_fma_f32 v56, -v52, v55, v54
	v_fmac_f32_e32 v55, v56, v53
	v_fma_f32 v52, -v52, v55, v54
	v_div_fmas_f32 v52, v52, v53, v55
	v_div_fixup_f32 v55, v52, v64, 1.0
	v_and_b32_e32 v76, 0xffff0000, v76
	v_fma_f32 v52, v55, v89, -v81
	v_fma_f32 v53, v55, v90, -v74
	v_sub_f32_e32 v58, v58, v95
	v_sub_f32_e32 v59, v59, v96
	v_lshlrev_b32_e32 v84, 16, v77
	v_and_b32_e32 v77, 0xffff0000, v77
	v_add_f32_e32 v94, v57, v76
	v_cvt_pk_bf16_f32 v52, v52, v53
	v_fma_f32 v53, v55, v91, -v82
	v_fma_f32 v54, v55, v92, -v75
	v_add_f32_e32 v95, v58, v84
	v_add_f32_e32 v96, v59, v77
	v_cvt_pk_bf16_f32 v53, v53, v54
	v_fma_f32 v54, v55, v93, -v83
	v_fma_f32 v56, v55, v94, -v76
	v_cvt_pk_bf16_f32 v54, v54, v56
	v_fma_f32 v56, v55, v95, -v84
	v_fma_f32 v55, v55, v96, -v77
	v_cvt_pk_bf16_f32 v55, v56, v55
	v_add_co_u32_e32 v56, vcc, s7, v124
	s_movk_i32 s10, 0x2000
	s_nop 0
	v_addc_co_u32_e32 v57, vcc, 0, v125, vcc
	v_add_co_u32_e32 v58, vcc, s10, v124
	s_waitcnt vmcnt(14)
	v_lshlrev_b32_e32 v64, 16, v48
	v_addc_co_u32_e32 v59, vcc, 0, v125, vcc
	global_store_dwordx4 v[58:59], v[52:55], off offset:-4096 sc1
	s_mov_b32 s7, 0x3e800000
	v_sub_f32_e32 v63, v96, v63
	v_sub_f32_e32 v52, v89, v85
	v_sub_f32_e32 v53, v90, v60
	v_and_b32_e32 v85, 0xffff0000, v48
	v_sub_f32_e32 v54, v91, v86
	v_sub_f32_e32 v55, v92, v61
	v_sub_f32_e32 v60, v93, v87
	v_lshlrev_b32_e32 v86, 16, v49
	v_and_b32_e32 v87, 0xffff0000, v49
	v_add_f32_e32 v52, v52, v64
	v_add_f32_e32 v53, v53, v85
	v_sub_f32_e32 v61, v94, v62
	v_sub_f32_e32 v62, v95, v88
	v_lshlrev_b32_e32 v88, 16, v50
	v_and_b32_e32 v89, 0xffff0000, v50
	v_add_f32_e32 v54, v54, v86
	v_add_f32_e32 v55, v55, v87
	v_fma_f32 v48, v52, s7, -v64
	v_fma_f32 v49, v53, s7, -v85
	v_lshlrev_b32_e32 v90, 16, v51
	v_add_f32_e32 v60, v60, v88
	v_add_f32_e32 v61, v61, v89
	v_cvt_pk_bf16_f32 v48, v48, v49
	v_fma_f32 v49, v54, s7, -v86
	v_fma_f32 v50, v55, s7, -v87
	v_and_b32_e32 v91, 0xffff0000, v51
	v_add_f32_e32 v62, v62, v90
	v_cvt_pk_bf16_f32 v49, v49, v50
	v_fma_f32 v50, v60, s7, -v88
	v_fma_f32 v51, v61, s7, -v89
	v_add_f32_e32 v63, v63, v91
	v_cvt_pk_bf16_f32 v50, v50, v51
	v_fma_f32 v51, v62, s7, -v90
	v_fma_f32 v92, v63, s7, -v91
	v_cvt_pk_bf16_f32 v51, v51, v92
	global_store_dwordx4 v[56:57], v[48:51], off offset:2048 sc1
	s_waitcnt vmcnt(15)
	v_lshlrev_b32_e32 v56, 16, v44
	v_and_b32_e32 v57, 0xffff0000, v44
	v_sub_f32_e32 v48, v52, v97
	v_sub_f32_e32 v49, v53, v66
	v_sub_f32_e32 v50, v54, v98
	v_sub_f32_e32 v51, v55, v67
	v_sub_f32_e32 v52, v60, v99
	v_sub_f32_e32 v53, v61, v68
	v_lshlrev_b32_e32 v60, 16, v45
	v_and_b32_e32 v61, 0xffff0000, v45
	v_add_f32_e32 v48, v48, v56
	v_add_f32_e32 v49, v49, v57
	v_sub_f32_e32 v54, v62, v100
	v_sub_f32_e32 v55, v63, v69
	v_lshlrev_b32_e32 v62, 16, v46
	v_and_b32_e32 v63, 0xffff0000, v46
	v_add_f32_e32 v50, v50, v60
	v_add_f32_e32 v51, v51, v61
	v_fma_f32 v44, v48, s7, -v56
	v_fma_f32 v45, v49, s7, -v57
	v_lshlrev_b32_e32 v66, 16, v47
	v_add_f32_e32 v52, v52, v62
	v_add_f32_e32 v53, v53, v63
	v_cvt_pk_bf16_f32 v44, v44, v45
	v_fma_f32 v45, v50, s7, -v60
	v_fma_f32 v46, v51, s7, -v61
	v_and_b32_e32 v67, 0xffff0000, v47
	v_add_f32_e32 v54, v54, v66
	v_cvt_pk_bf16_f32 v45, v45, v46
	v_fma_f32 v46, v52, s7, -v62
	v_fma_f32 v47, v53, s7, -v63
	v_add_f32_e32 v55, v55, v67
	v_cvt_pk_bf16_f32 v46, v46, v47
	v_fma_f32 v47, v54, s7, -v66
	v_fma_f32 v68, v55, s7, -v67
	v_cvt_pk_bf16_f32 v47, v47, v68
	global_store_dwordx4 v[58:59], v[44:47], off sc1
	s_waitcnt vmcnt(15)
	v_and_b32_e32 v68, 0xffff0000, v42
	v_lshlrev_b32_e32 v69, 16, v43
	v_sub_f32_e32 v44, v48, v65
	v_sub_f32_e32 v45, v49, v70
	v_sub_f32_e32 v48, v52, v79
	v_sub_f32_e32 v49, v53, v72
	v_lshlrev_b32_e32 v52, 16, v40
	v_and_b32_e32 v53, 0xffff0000, v40
	v_sub_f32_e32 v46, v50, v78
	v_sub_f32_e32 v47, v51, v71
	v_sub_f32_e32 v50, v54, v80
	v_sub_f32_e32 v51, v55, v73
	v_lshlrev_b32_e32 v54, 16, v41
	v_and_b32_e32 v55, 0xffff0000, v41
	v_add_f32_e32 v44, v44, v52
	v_add_f32_e32 v45, v45, v53
	v_lshlrev_b32_e32 v65, 16, v42
	v_add_f32_e32 v46, v46, v54
	v_add_f32_e32 v47, v47, v55
	v_fma_f32 v40, v44, s7, -v52
	v_fma_f32 v41, v45, s7, -v53
	v_add_f32_e32 v48, v48, v65
	v_add_f32_e32 v49, v49, v68
	v_cvt_pk_bf16_f32 v40, v40, v41
	v_fma_f32 v41, v46, s7, -v54
	v_fma_f32 v42, v47, s7, -v55
	v_and_b32_e32 v70, 0xffff0000, v43
	v_add_f32_e32 v50, v50, v69
	v_cvt_pk_bf16_f32 v41, v41, v42
	v_fma_f32 v42, v48, s7, -v65
	v_fma_f32 v43, v49, s7, -v68
	v_add_f32_e32 v51, v51, v70
	v_cvt_pk_bf16_f32 v42, v42, v43
	v_fma_f32 v43, v50, s7, -v69
	v_fma_f32 v71, v51, s7, -v70
	v_cvt_pk_bf16_f32 v43, v43, v71
	global_store_dwordx4 v[58:59], v[40:43], off offset:2048 sc1
	s_waitcnt vmcnt(15)
; __device__ __forceinline__ unsigned cvt_pk_bf16(float lo, float hi) { unsigned r; asm volatile("v_cvt_pk_bf16_f32 %0, %1, %2" : "=v"(r) : "v"(lo), "v"(hi)); return r; }
; #define UNPK8(q, f) const float f[8] = {bf_lo((q).x), bf_hi((q).x), bf_lo((q).y), bf_hi((q).y), bf_lo((q).z), bf_hi((q).z), bf_lo((q).w), bf_hi((q).w)}
; template <int W> __device__ __forceinline__ void pool_run(const bf16_t* up, bf16_t* dp, int t0) {
;     ...
;     for (int j = 0; j < 16; ++j) {
;         UNPK8(q[j + W - 1], cur);
; #pragma unroll
;         for (int e = 0; e < 8; ++e) s[e] += cur[e];
;         const int cnt = (t0 + j + 1) < W ? (t0 + j + 1) : W; const float inv = 1.0f / (float)cnt;
;         u32x4 o; o.x = cvt_pk_bf16(s[0] * inv - cur[0], s[1] * inv - cur[1]); o.y = cvt_pk_bf16(s[2] * inv - cur[2], s[3] * inv - cur[3]);
;         o.z = cvt_pk_bf16(s[4] * inv - cur[4], s[5] * inv - cur[5]); o.w = cvt_pk_bf16(s[6] * inv - cur[6], s[7] * inv - cur[7]);
;         *(u32x4*)(dp + (size_t)j * PW) = o;
;         UNPK8(q[j], old);
; #pragma unroll
;         for (int e = 0; e < 8; ++e) s[e] -= old[e];
;     }
	v_lshlrev_b32_e32 v58, 16, v38
	v_and_b32_e32 v59, 0xffff0000, v38
	v_sub_f32_e32 v40, v44, v81
	v_sub_f32_e32 v41, v45, v74
	v_sub_f32_e32 v44, v48, v83
	v_sub_f32_e32 v45, v49, v76
	v_lshlrev_b32_e32 v48, 16, v36
	v_and_b32_e32 v49, 0xffff0000, v36
	v_sub_f32_e32 v42, v46, v82
	v_sub_f32_e32 v43, v47, v75
	v_sub_f32_e32 v46, v50, v84
	v_sub_f32_e32 v47, v51, v77
	v_lshlrev_b32_e32 v50, 16, v37
	v_and_b32_e32 v51, 0xffff0000, v37
	v_add_f32_e32 v73, v40, v48
	v_add_f32_e32 v74, v41, v49
	v_add_f32_e32 v75, v42, v50
	v_add_f32_e32 v76, v43, v51
	v_fma_f32 v36, v73, s7, -v48
	v_fma_f32 v37, v74, s7, -v49
	v_lshlrev_b32_e32 v71, 16, v39
	v_and_b32_e32 v72, 0xffff0000, v39
	v_add_f32_e32 v44, v44, v58
	v_add_f32_e32 v45, v45, v59
	v_cvt_pk_bf16_f32 v36, v36, v37
	v_fma_f32 v37, v75, s7, -v50
	v_fma_f32 v38, v76, s7, -v51
	v_add_f32_e32 v46, v46, v71
	v_add_f32_e32 v47, v47, v72
	v_cvt_pk_bf16_f32 v37, v37, v38
	v_fma_f32 v38, v44, s7, -v58
	v_fma_f32 v39, v45, s7, -v59
	s_movk_i32 s8, 0x3000
	v_cvt_pk_bf16_f32 v38, v38, v39
	v_fma_f32 v39, v46, s7, -v71
	v_fma_f32 v40, v47, s7, -v72
	v_cvt_pk_bf16_f32 v39, v39, v40
	v_add_co_u32_e32 v40, vcc, s8, v124
	s_movk_i32 s9, 0x4000
	s_nop 0
	v_addc_co_u32_e32 v41, vcc, 0, v125, vcc
	v_add_co_u32_e32 v42, vcc, s9, v124
	v_sub_f32_e32 v44, v44, v88
	s_nop 0
	v_addc_co_u32_e32 v43, vcc, 0, v125, vcc
	global_store_dwordx4 v[42:43], v[36:39], off offset:-4096 sc1
	v_sub_f32_e32 v45, v45, v89
	s_waitcnt vmcnt(15)
	v_and_b32_e32 v77, 0xffff0000, v34
	v_sub_f32_e32 v36, v73, v64
	v_sub_f32_e32 v37, v74, v85
	v_lshlrev_b32_e32 v64, 16, v32
	v_and_b32_e32 v73, 0xffff0000, v32
	v_sub_f32_e32 v38, v75, v86
	v_sub_f32_e32 v39, v76, v87
	v_lshlrev_b32_e32 v74, 16, v33
	v_and_b32_e32 v75, 0xffff0000, v33
	v_add_f32_e32 v36, v36, v64
	v_add_f32_e32 v37, v37, v73
	v_lshlrev_b32_e32 v76, 16, v34
	v_add_f32_e32 v38, v38, v74
	v_add_f32_e32 v39, v39, v75
	v_fma_f32 v32, v36, s7, -v64
	v_fma_f32 v33, v37, s7, -v73
	v_sub_f32_e32 v46, v46, v90
	v_lshlrev_b32_e32 v78, 16, v35
	v_add_f32_e32 v44, v44, v76
	v_add_f32_e32 v45, v45, v77
	v_cvt_pk_bf16_f32 v32, v32, v33
	v_fma_f32 v33, v38, s7, -v74
	v_fma_f32 v34, v39, s7, -v75
	v_sub_f32_e32 v47, v47, v91
	v_and_b32_e32 v79, 0xffff0000, v35
	v_add_f32_e32 v46, v46, v78
	v_cvt_pk_bf16_f32 v33, v33, v34
	v_fma_f32 v34, v44, s7, -v76
	v_fma_f32 v35, v45, s7, -v77
	v_add_f32_e32 v47, v47, v79
	v_cvt_pk_bf16_f32 v34, v34, v35
	v_fma_f32 v35, v46, s7, -v78
	v_fma_f32 v80, v47, s7, -v79
	v_cvt_pk_bf16_f32 v35, v35, v80
	global_store_dwordx4 v[40:41], v[32:35], off offset:2048 sc1
	s_waitcnt vmcnt(15)
	v_lshlrev_b32_e32 v40, 16, v28
	v_and_b32_e32 v41, 0xffff0000, v28
	v_sub_f32_e32 v32, v36, v56
	v_sub_f32_e32 v33, v37, v57
	v_sub_f32_e32 v34, v38, v60
	v_sub_f32_e32 v35, v39, v61
	v_sub_f32_e32 v36, v44, v62
	v_sub_f32_e32 v37, v45, v63
	v_lshlrev_b32_e32 v44, 16, v29
	v_and_b32_e32 v45, 0xffff0000, v29
	v_add_f32_e32 v32, v32, v40
	v_add_f32_e32 v33, v33, v41
	v_sub_f32_e32 v38, v46, v66
	v_sub_f32_e32 v39, v47, v67
	v_lshlrev_b32_e32 v46, 16, v30
	v_and_b32_e32 v47, 0xffff0000, v30
	v_add_f32_e32 v34, v34, v44
	v_add_f32_e32 v35, v35, v45
	v_fma_f32 v28, v32, s7, -v40
	v_fma_f32 v29, v33, s7, -v41
	v_lshlrev_b32_e32 v56, 16, v31
	v_add_f32_e32 v36, v36, v46
	v_add_f32_e32 v37, v37, v47
	v_cvt_pk_bf16_f32 v28, v28, v29
	v_fma_f32 v29, v34, s7, -v44
	v_fma_f32 v30, v35, s7, -v45
	v_and_b32_e32 v57, 0xffff0000, v31
	v_add_f32_e32 v38, v38, v56
	v_cvt_pk_bf16_f32 v29, v29, v30
	v_fma_f32 v30, v36, s7, -v46
	v_fma_f32 v31, v37, s7, -v47
	v_add_f32_e32 v39, v39, v57
	v_cvt_pk_bf16_f32 v30, v30, v31
	v_fma_f32 v31, v38, s7, -v56
	v_fma_f32 v60, v39, s7, -v57
	v_cvt_pk_bf16_f32 v31, v31, v60
	global_store_dwordx4 v[42:43], v[28:31], off sc1
	s_movk_i32 s5, 0x5000
	s_movk_i32 s6, 0x6000
	v_sub_f32_e32 v28, v32, v52
	v_sub_f32_e32 v29, v33, v53
	v_sub_f32_e32 v32, v36, v65
	v_sub_f32_e32 v33, v37, v68
	s_waitcnt vmcnt(15)
	v_lshlrev_b32_e32 v36, 16, v24
	v_and_b32_e32 v37, 0xffff0000, v24
	v_sub_f32_e32 v30, v34, v54
	v_sub_f32_e32 v31, v35, v55
	v_sub_f32_e32 v34, v38, v69
	v_sub_f32_e32 v35, v39, v70
	v_lshlrev_b32_e32 v38, 16, v25
	v_and_b32_e32 v39, 0xffff0000, v25
	v_add_f32_e32 v28, v28, v36
	v_add_f32_e32 v29, v29, v37
	v_lshlrev_b32_e32 v52, 16, v26
	v_and_b32_e32 v53, 0xffff0000, v26
	v_add_f32_e32 v30, v30, v38
	v_add_f32_e32 v31, v31, v39
	v_fma_f32 v24, v28, s7, -v36
	v_fma_f32 v25, v29, s7, -v37
	v_lshlrev_b32_e32 v54, 16, v27
	v_add_f32_e32 v32, v32, v52
	v_add_f32_e32 v33, v33, v53
	v_cvt_pk_bf16_f32 v24, v24, v25
	v_fma_f32 v25, v30, s7, -v38
	v_fma_f32 v26, v31, s7, -v39
	v_and_b32_e32 v55, 0xffff0000, v27
	v_add_f32_e32 v34, v34, v54
	v_cvt_pk_bf16_f32 v25, v25, v26
	v_fma_f32 v26, v32, s7, -v52
	v_fma_f32 v27, v33, s7, -v53
	v_add_f32_e32 v35, v35, v55
	v_cvt_pk_bf16_f32 v26, v26, v27
	v_fma_f32 v27, v34, s7, -v54
	v_fma_f32 v60, v35, s7, -v55
	v_cvt_pk_bf16_f32 v27, v27, v60
	global_store_dwordx4 v[42:43], v[24:27], off offset:2048 sc1
	s_waitcnt vmcnt(15)
; __device__ __forceinline__ unsigned cvt_pk_bf16(float lo, float hi) { unsigned r; asm volatile("v_cvt_pk_bf16_f32 %0, %1, %2" : "=v"(r) : "v"(lo), "v"(hi)); return r; }
; #define UNPK8(q, f) const float f[8] = {bf_lo((q).x), bf_hi((q).x), bf_lo((q).y), bf_hi((q).y), bf_lo((q).z), bf_hi((q).z), bf_lo((q).w), bf_hi((q).w)}
; template <int W> __device__ __forceinline__ void pool_run(const bf16_t* up, bf16_t* dp, int t0) {
;     ...
;     for (int j = 0; j < 16; ++j) {
;         UNPK8(q[j + W - 1], cur);
; #pragma unroll
;         for (int e = 0; e < 8; ++e) s[e] += cur[e];
;         const int cnt = (t0 + j + 1) < W ? (t0 + j + 1) : W; const float inv = 1.0f / (float)cnt;
;         u32x4 o; o.x = cvt_pk_bf16(s[0] * inv - cur[0], s[1] * inv - cur[1]); o.y = cvt_pk_bf16(s[2] * inv - cur[2], s[3] * inv - cur[3]);
;         o.z = cvt_pk_bf16(s[4] * inv - cur[4], s[5] * inv - cur[5]); o.w = cvt_pk_bf16(s[6] * inv - cur[6], s[7] * inv - cur[7]);
;         *(u32x4*)(dp + (size_t)j * PW) = o;
;         UNPK8(q[j], old);
; #pragma unroll
;         for (int e = 0; e < 8; ++e) s[e] -= old[e];
;     }
	v_lshlrev_b32_e32 v42, 16, v22
	v_and_b32_e32 v43, 0xffff0000, v22
	v_sub_f32_e32 v24, v28, v48
	v_sub_f32_e32 v25, v29, v49
	v_sub_f32_e32 v28, v32, v58
	v_sub_f32_e32 v29, v33, v59
	v_lshlrev_b32_e32 v32, 16, v20
	v_and_b32_e32 v33, 0xffff0000, v20
	v_sub_f32_e32 v26, v30, v50
	v_sub_f32_e32 v27, v31, v51
	v_sub_f32_e32 v30, v34, v71
	v_sub_f32_e32 v31, v35, v72
	v_lshlrev_b32_e32 v34, 16, v21
	v_and_b32_e32 v35, 0xffff0000, v21
	v_add_f32_e32 v50, v24, v32
	v_add_f32_e32 v51, v25, v33
	v_add_f32_e32 v58, v26, v34
	v_add_f32_e32 v59, v27, v35
	v_fma_f32 v20, v50, s7, -v32
	v_fma_f32 v21, v51, s7, -v33
	v_lshlrev_b32_e32 v48, 16, v23
	v_and_b32_e32 v49, 0xffff0000, v23
	v_add_f32_e32 v28, v28, v42
	v_add_f32_e32 v29, v29, v43
	v_cvt_pk_bf16_f32 v20, v20, v21
	v_fma_f32 v21, v58, s7, -v34
	v_fma_f32 v22, v59, s7, -v35
	v_add_f32_e32 v30, v30, v48
	v_add_f32_e32 v31, v31, v49
	v_cvt_pk_bf16_f32 v21, v21, v22
	v_fma_f32 v22, v28, s7, -v42
	v_fma_f32 v23, v29, s7, -v43
	v_cvt_pk_bf16_f32 v22, v22, v23
	v_fma_f32 v23, v30, s7, -v48
	v_fma_f32 v24, v31, s7, -v49
	v_cvt_pk_bf16_f32 v23, v23, v24
	v_add_co_u32_e32 v24, vcc, s5, v124
	v_sub_f32_e32 v28, v28, v76
	s_nop 0
	v_addc_co_u32_e32 v25, vcc, 0, v125, vcc
	v_add_co_u32_e32 v26, vcc, s6, v124
	v_sub_f32_e32 v29, v29, v77
	s_nop 0
	v_addc_co_u32_e32 v27, vcc, 0, v125, vcc
	global_store_dwordx4 v[26:27], v[20:23], off offset:-4096 sc1
	s_waitcnt vmcnt(15)
	v_lshlrev_b32_e32 v60, 16, v18
	v_and_b32_e32 v61, 0xffff0000, v18
	v_sub_f32_e32 v20, v50, v64
	v_sub_f32_e32 v21, v51, v73
	v_lshlrev_b32_e32 v50, 16, v16
	v_and_b32_e32 v51, 0xffff0000, v16
	v_sub_f32_e32 v22, v58, v74
	v_sub_f32_e32 v23, v59, v75
	v_lshlrev_b32_e32 v58, 16, v17
	v_and_b32_e32 v59, 0xffff0000, v17
	v_add_f32_e32 v20, v20, v50
	v_add_f32_e32 v21, v21, v51
	v_add_f32_e32 v22, v22, v58
	v_add_f32_e32 v23, v23, v59
	v_fma_f32 v16, v20, s7, -v50
	v_fma_f32 v17, v21, s7, -v51
	v_sub_f32_e32 v30, v30, v78
	v_lshlrev_b32_e32 v62, 16, v19
	v_add_f32_e32 v28, v28, v60
	v_add_f32_e32 v29, v29, v61
	v_cvt_pk_bf16_f32 v16, v16, v17
	v_fma_f32 v17, v22, s7, -v58
	v_fma_f32 v18, v23, s7, -v59
	v_sub_f32_e32 v31, v31, v79
	v_and_b32_e32 v63, 0xffff0000, v19
	v_add_f32_e32 v30, v30, v62
	v_cvt_pk_bf16_f32 v17, v17, v18
	v_fma_f32 v18, v28, s7, -v60
	v_fma_f32 v19, v29, s7, -v61
	v_add_f32_e32 v31, v31, v63
	v_cvt_pk_bf16_f32 v18, v18, v19
	v_fma_f32 v19, v30, s7, -v62
	v_fma_f32 v64, v31, s7, -v63
	v_cvt_pk_bf16_f32 v19, v19, v64
	global_store_dwordx4 v[24:25], v[16:19], off offset:2048 sc1
	s_waitcnt vmcnt(15)
	v_lshlrev_b32_e32 v24, 16, v12
	v_and_b32_e32 v12, 0xffff0000, v12
	v_sub_f32_e32 v16, v20, v40
	v_sub_f32_e32 v17, v21, v41
	v_sub_f32_e32 v18, v22, v44
	v_sub_f32_e32 v19, v23, v45
	v_lshlrev_b32_e32 v25, 16, v13
	v_and_b32_e32 v13, 0xffff0000, v13
	v_add_f32_e32 v16, v16, v24
	v_add_f32_e32 v17, v17, v12
	v_sub_f32_e32 v20, v28, v46
	v_sub_f32_e32 v21, v29, v47
	v_sub_f32_e32 v23, v31, v57
	v_lshlrev_b32_e32 v28, 16, v14
	v_and_b32_e32 v14, 0xffff0000, v14
	v_lshlrev_b32_e32 v29, 16, v15
	v_and_b32_e32 v15, 0xffff0000, v15
	v_add_f32_e32 v18, v18, v25
	v_add_f32_e32 v19, v19, v13
	v_fma_f32 v24, v16, s7, -v24
	v_fma_f32 v12, v17, s7, -v12
	v_sub_f32_e32 v22, v30, v56
	v_add_f32_e32 v20, v20, v28
	v_add_f32_e32 v21, v21, v14
	v_add_f32_e32 v23, v23, v15
	v_cvt_pk_bf16_f32 v12, v24, v12
	v_fma_f32 v24, v18, s7, -v25
	v_fma_f32 v13, v19, s7, -v13
	v_add_f32_e32 v22, v22, v29
	v_cvt_pk_bf16_f32 v13, v24, v13
	v_fma_f32 v24, v20, s7, -v28
	v_fma_f32 v14, v21, s7, -v14
	v_fma_f32 v15, v23, s7, -v15
	v_cvt_pk_bf16_f32 v14, v24, v14
	v_fma_f32 v24, v22, s7, -v29
	v_cvt_pk_bf16_f32 v15, v24, v15
	global_store_dwordx4 v[26:27], v[12:15], off sc1
	s_movk_i32 s4, 0x7000
	s_nop 0
	v_sub_f32_e32 v12, v16, v36
	v_sub_f32_e32 v13, v17, v37
	v_sub_f32_e32 v16, v20, v52
	s_waitcnt vmcnt(15)
; __device__ __forceinline__ unsigned cvt_pk_bf16(float lo, float hi) { unsigned r; asm volatile("v_cvt_pk_bf16_f32 %0, %1, %2" : "=v"(r) : "v"(lo), "v"(hi)); return r; }
; #define UNPK8(q, f) const float f[8] = {bf_lo((q).x), bf_hi((q).x), bf_lo((q).y), bf_hi((q).y), bf_lo((q).z), bf_hi((q).z), bf_lo((q).w), bf_hi((q).w)}
; template <int W> __device__ __forceinline__ void pool_run(const bf16_t* up, bf16_t* dp, int t0) {
;     ...
;     for (int j = 0; j < 16; ++j) {
;         UNPK8(q[j + W - 1], cur);
; #pragma unroll
;         for (int e = 0; e < 8; ++e) s[e] += cur[e];
;         const int cnt = (t0 + j + 1) < W ? (t0 + j + 1) : W; const float inv = 1.0f / (float)cnt;
;         u32x4 o; o.x = cvt_pk_bf16(s[0] * inv - cur[0], s[1] * inv - cur[1]); o.y = cvt_pk_bf16(s[2] * inv - cur[2], s[3] * inv - cur[3]);
;         o.z = cvt_pk_bf16(s[4] * inv - cur[4], s[5] * inv - cur[5]); o.w = cvt_pk_bf16(s[6] * inv - cur[6], s[7] * inv - cur[7]);
;         *(u32x4*)(dp + (size_t)j * PW) = o;
;         UNPK8(q[j], old);
; #pragma unroll
;         for (int e = 0; e < 8; ++e) s[e] -= old[e];
;     }
	v_lshlrev_b32_e32 v20, 16, v8
	v_and_b32_e32 v8, 0xffff0000, v8
	v_sub_f32_e32 v14, v18, v38
	v_sub_f32_e32 v15, v19, v39
	v_sub_f32_e32 v17, v21, v53
	v_lshlrev_b32_e32 v21, 16, v9
	v_and_b32_e32 v9, 0xffff0000, v9
	v_add_f32_e32 v12, v12, v20
	v_add_f32_e32 v13, v13, v8
	v_sub_f32_e32 v18, v22, v54
	v_sub_f32_e32 v19, v23, v55
	v_lshlrev_b32_e32 v22, 16, v10
	v_and_b32_e32 v10, 0xffff0000, v10
	v_lshlrev_b32_e32 v23, 16, v11
	v_and_b32_e32 v11, 0xffff0000, v11
	v_add_f32_e32 v14, v14, v21
	v_add_f32_e32 v15, v15, v9
	v_fma_f32 v20, v12, s7, -v20
	v_fma_f32 v8, v13, s7, -v8
	v_add_f32_e32 v16, v16, v22
	v_add_f32_e32 v17, v17, v10
	v_add_f32_e32 v19, v19, v11
	v_cvt_pk_bf16_f32 v8, v20, v8
	v_fma_f32 v20, v14, s7, -v21
	v_fma_f32 v9, v15, s7, -v9
	v_add_f32_e32 v18, v18, v23
	v_cvt_pk_bf16_f32 v9, v20, v9
	v_fma_f32 v20, v16, s7, -v22
	v_fma_f32 v10, v17, s7, -v10
	v_fma_f32 v11, v19, s7, -v11
	v_cvt_pk_bf16_f32 v10, v20, v10
	v_fma_f32 v20, v18, s7, -v23
	v_cvt_pk_bf16_f32 v11, v20, v11
	global_store_dwordx4 v[26:27], v[8:11], off offset:2048 sc1
	s_nop 1
	v_sub_f32_e32 v8, v12, v32
	v_sub_f32_e32 v9, v13, v33
	v_sub_f32_e32 v12, v16, v42
	s_waitcnt vmcnt(15)
	v_lshlrev_b32_e32 v16, 16, v4
	v_and_b32_e32 v4, 0xffff0000, v4
	v_sub_f32_e32 v10, v14, v34
	v_sub_f32_e32 v11, v15, v35
	v_sub_f32_e32 v13, v17, v43
	v_lshlrev_b32_e32 v17, 16, v5
	v_and_b32_e32 v5, 0xffff0000, v5
	v_add_f32_e32 v20, v8, v16
	v_add_f32_e32 v21, v9, v4
	v_sub_f32_e32 v14, v18, v48
	v_lshlrev_b32_e32 v18, 16, v6
	v_and_b32_e32 v6, 0xffff0000, v6
	v_add_f32_e32 v10, v10, v17
	v_add_f32_e32 v11, v11, v5
	v_fma_f32 v8, v20, s7, -v16
	v_fma_f32 v4, v21, s7, -v4
	v_sub_f32_e32 v15, v19, v49
	v_lshlrev_b32_e32 v19, 16, v7
	v_and_b32_e32 v7, 0xffff0000, v7
	v_add_f32_e32 v12, v12, v18
	v_add_f32_e32 v13, v13, v6
	v_cvt_pk_bf16_f32 v4, v8, v4
	v_fma_f32 v8, v10, s7, -v17
	v_fma_f32 v5, v11, s7, -v5
	v_add_f32_e32 v14, v14, v19
	v_add_f32_e32 v15, v15, v7
	v_cvt_pk_bf16_f32 v5, v8, v5
	v_fma_f32 v8, v12, s7, -v18
	v_fma_f32 v6, v13, s7, -v6
	v_cvt_pk_bf16_f32 v6, v8, v6
	v_fma_f32 v8, v14, s7, -v19
	v_fma_f32 v7, v15, s7, -v7
	v_cvt_pk_bf16_f32 v7, v8, v7
	v_add_co_u32_e32 v8, vcc, s4, v124
	s_nop 1
	v_addc_co_u32_e32 v9, vcc, 0, v125, vcc
	global_store_dwordx4 v[8:9], v[4:7], off sc1
	v_sub_f32_e32 v8, v12, v60
	s_waitcnt vmcnt(15)
	v_lshlrev_b32_e32 v12, 16, v0
	v_sub_f32_e32 v4, v20, v50
	v_sub_f32_e32 v5, v21, v51
	v_and_b32_e32 v0, 0xffff0000, v0
	v_sub_f32_e32 v6, v10, v58
	v_sub_f32_e32 v7, v11, v59
	v_sub_f32_e32 v9, v13, v61
	v_lshlrev_b32_e32 v13, 16, v1
	v_and_b32_e32 v1, 0xffff0000, v1
	v_add_f32_e32 v4, v4, v12
	v_add_f32_e32 v5, v5, v0
	v_sub_f32_e32 v10, v14, v62
	v_sub_f32_e32 v11, v15, v63
	v_lshlrev_b32_e32 v14, 16, v2
	v_and_b32_e32 v2, 0xffff0000, v2
	v_lshlrev_b32_e32 v15, 16, v3
	v_and_b32_e32 v3, 0xffff0000, v3
	v_add_f32_e32 v6, v6, v13
	v_add_f32_e32 v7, v7, v1
	v_fma_f32 v4, v4, s7, -v12
	v_fma_f32 v0, v5, s7, -v0
	v_add_f32_e32 v8, v8, v14
	v_add_f32_e32 v9, v9, v2
	v_add_f32_e32 v11, v11, v3
	v_cvt_pk_bf16_f32 v0, v4, v0
	v_fma_f32 v4, v6, s7, -v13
	v_fma_f32 v1, v7, s7, -v1
	v_add_f32_e32 v10, v10, v15
	v_cvt_pk_bf16_f32 v1, v4, v1
	v_fma_f32 v4, v8, s7, -v14
	v_fma_f32 v2, v9, s7, -v2
	v_fma_f32 v3, v11, s7, -v3
	v_cvt_pk_bf16_f32 v2, v4, v2
	v_fma_f32 v4, v10, s7, -v15
	v_cvt_pk_bf16_f32 v3, v4, v3
	s_branch .LBB0_460

; __device__ __forceinline__ unsigned cvt_pk_bf16(float lo, float hi) { unsigned r; asm volatile("v_cvt_pk_bf16_f32 %0, %1, %2" : "=v"(r) : "v"(lo), "v"(hi)); return r; }
; #define UNPK8(q, f) const float f[8] = {bf_lo((q).x), bf_hi((q).x), bf_lo((q).y), bf_hi((q).y), bf_lo((q).z), bf_hi((q).z), bf_lo((q).w), bf_hi((q).w)}
; template <int W> __device__ __forceinline__ void pool_run(const bf16_t* up, bf16_t* dp, int t0) {
;     u32x4 q[W + 15];
; #pragma unroll
;     for (int i = 0; i < W + 15; ++i) { const int dt = i - (W - 1); const bool ok = (t0 + dt >= 0); const u32x4 v = *(const u32x4*)(up + (ptrdiff_t)(ok ? dt : 0) * PW); q[i] = ok ? v : (u32x4){0u, 0u, 0u, 0u}; }
;     float s[8];
; #pragma unroll
;     for (int e = 0; e < 8; ++e) s[e] = 0.f;
; #pragma unroll
;     for (int i = 0; i < W - 1; ++i) { UNPK8(q[i], f);
; #pragma unroll
;         for (int e = 0; e < 8; ++e) s[e] += f[e]; }
; #pragma unroll
;     for (int j = 0; j < 16; ++j) {
;         UNPK8(q[j + W - 1], cur);
; #pragma unroll
;         for (int e = 0; e < 8; ++e) s[e] += cur[e];
;         const int cnt = (t0 + j + 1) < W ? (t0 + j + 1) : W; const float inv = 1.0f / (float)cnt;
;         u32x4 o; o.x = cvt_pk_bf16(s[0] * inv - cur[0], s[1] * inv - cur[1]); o.y = cvt_pk_bf16(s[2] * inv - cur[2], s[3] * inv - cur[3]);
;         o.z = cvt_pk_bf16(s[4] * inv - cur[4], s[5] * inv - cur[5]); o.w = cvt_pk_bf16(s[6] * inv - cur[6], s[7] * inv - cur[7]);
;         *(u32x4*)(dp + (size_t)j * PW) = o;
;         UNPK8(q[j], old);
; #pragma unroll
;         for (int e = 0; e < 8; ++e) s[e] -= old[e];
;     }
.LBB0_459:
	s_or_b64 exec, exec, s[4:5]
	global_load_dwordx4 v[46:49], v[126:127], off
	global_load_dwordx4 v[50:53], v[126:127], off offset:2048
	v_add_co_u32_e32 v4, vcc, 0x1000, v126
	s_waitcnt vmcnt(2)
	v_lshlrev_b32_e32 v66, 16, v0
	v_addc_co_u32_e32 v5, vcc, 0, v127, vcc
	global_load_dwordx4 v[54:57], v[4:5], off
	global_load_dwordx4 v[58:61], v[4:5], off offset:2048
	v_and_b32_e32 v67, 0xffff0000, v0
	v_add_co_u32_e32 v0, vcc, 0x2000, v126
	v_lshlrev_b32_e32 v68, 16, v1
	v_and_b32_e32 v69, 0xffff0000, v1
	v_addc_co_u32_e32 v1, vcc, 0, v127, vcc
	global_load_dwordx4 v[62:65], v[0:1], off
	global_load_dwordx4 v[40:43], v[0:1], off offset:2048
	v_lshlrev_b32_e32 v70, 16, v2
	v_and_b32_e32 v71, 0xffff0000, v2
	v_add_co_u32_e32 v2, vcc, 0x3000, v126
	v_lshlrev_b32_e32 v72, 16, v3
	v_and_b32_e32 v73, 0xffff0000, v3
	v_addc_co_u32_e32 v3, vcc, 0, v127, vcc
	global_load_dwordx4 v[36:39], v[2:3], off
	global_load_dwordx4 v[32:35], v[2:3], off offset:2048
	v_add_co_u32_e32 v0, vcc, 0x4000, v126
	v_add_f32_e32 v45, 0, v66
	s_nop 0
	v_addc_co_u32_e32 v1, vcc, 0, v127, vcc
	global_load_dwordx4 v[28:31], v[0:1], off
	global_load_dwordx4 v[24:27], v[0:1], off offset:2048
	v_add_co_u32_e32 v2, vcc, 0x5000, v126
	v_add_f32_e32 v74, 0, v67
	s_nop 0
	v_addc_co_u32_e32 v3, vcc, 0, v127, vcc
	v_add_co_u32_e32 v0, vcc, 0x6000, v126
	global_load_dwordx4 v[20:23], v[2:3], off
	global_load_dwordx4 v[16:19], v[2:3], off offset:2048
	v_addc_co_u32_e32 v1, vcc, 0, v127, vcc
	v_add_co_u32_e32 v2, vcc, 0x7000, v126
	v_add_f32_e32 v75, 0, v68
	s_nop 0
	v_addc_co_u32_e32 v3, vcc, 0, v127, vcc
	v_add_f32_e32 v76, 0, v69
	v_add_f32_e32 v77, 0, v70
	v_add_f32_e32 v78, 0, v71
	v_add_f32_e32 v79, 0, v72
	v_add_f32_e32 v80, 0, v73
	global_load_dwordx4 v[12:15], v[0:1], off
	global_load_dwordx4 v[8:11], v[0:1], off offset:2048
	global_load_dwordx4 v[4:7], v[2:3], off
	s_nop 0
	global_load_dwordx4 v[0:3], v[2:3], off offset:2048
	s_movk_i32 s7, 0x1000
	s_movk_i32 s8, 0x2000
	s_movk_i32 s5, 0x3000
	s_movk_i32 s6, 0x4000
	s_movk_i32 s1, 0x5000
	s_movk_i32 s4, 0x6000
	s_movk_i32 s0, 0x7000
	s_waitcnt vmcnt(15)
	v_lshlrev_b32_e32 v81, 16, v46
	v_add_f32_e32 v87, v45, v81
	v_div_scale_f32 v45, s[10:11], v44, v44, 1.0
	v_and_b32_e32 v82, 0xffff0000, v46
	v_rcp_f32_e32 v46, v45
	v_lshlrev_b32_e32 v83, 16, v47
	v_and_b32_e32 v84, 0xffff0000, v47
	v_add_f32_e32 v74, v74, v82
	v_fma_f32 v47, -v45, v46, 1.0
	v_fmac_f32_e32 v46, v47, v46
	v_div_scale_f32 v47, vcc, 1.0, v44, 1.0
	v_mul_f32_e32 v88, v47, v46
	v_fma_f32 v89, -v45, v88, v47
	v_fmac_f32_e32 v88, v89, v46
	v_fma_f32 v45, -v45, v88, v47
	v_div_fmas_f32 v45, v45, v46, v88
	v_div_fixup_f32 v47, v45, v44, 1.0
	v_lshlrev_b32_e32 v85, 16, v48
	v_and_b32_e32 v48, 0xffff0000, v48
	v_add_f32_e32 v75, v75, v83
	v_add_f32_e32 v76, v76, v84
	v_fma_f32 v44, v47, v87, -v81
	v_fma_f32 v45, v47, v74, -v82
	v_lshlrev_b32_e32 v86, 16, v49
	v_and_b32_e32 v49, 0xffff0000, v49
	v_add_f32_e32 v77, v77, v85
	v_add_f32_e32 v78, v78, v48
	v_cvt_pk_bf16_f32 v44, v44, v45
	v_fma_f32 v45, v47, v75, -v83
	v_fma_f32 v46, v47, v76, -v84
	v_add_f32_e32 v79, v79, v86
	v_add_f32_e32 v80, v80, v49
	v_cvt_pk_bf16_f32 v45, v45, v46
	v_fma_f32 v46, v47, v77, -v85
	v_fma_f32 v88, v47, v78, -v48
	v_cvt_pk_bf16_f32 v46, v46, v88
	v_fma_f32 v88, v47, v79, -v86
	v_fma_f32 v47, v47, v80, -v49
	v_cvt_pk_bf16_f32 v47, v88, v47
	global_store_dwordx4 v[124:125], v[44:47], off sc1
	s_nop 1
	v_sub_f32_e32 v44, v87, v66
	v_sub_f32_e32 v45, v74, v67
	v_sub_f32_e32 v66, v77, v70
	v_sub_f32_e32 v67, v78, v71
	s_waitcnt vmcnt(15)
	v_lshlrev_b32_e32 v70, 16, v50
	v_and_b32_e32 v71, 0xffff0000, v50
	v_sub_f32_e32 v46, v75, v68
	v_sub_f32_e32 v47, v76, v69
	v_sub_f32_e32 v68, v79, v72
	v_sub_f32_e32 v69, v80, v73
	v_lshlrev_b32_e32 v72, 16, v51
	v_and_b32_e32 v73, 0xffff0000, v51
	v_add_f32_e32 v50, v44, v70
	v_add_f32_e32 v51, v45, v71
	v_lshlrev_b32_e32 v74, 16, v52
	v_and_b32_e32 v52, 0xffff0000, v52
	v_add_f32_e32 v76, v46, v72
	v_add_f32_e32 v77, v47, v73
	v_fma_f32 v44, v50, 0.5, -v70
	v_fma_f32 v45, v51, 0.5, -v71
	v_lshlrev_b32_e32 v75, 16, v53
	v_add_f32_e32 v66, v66, v74
	v_add_f32_e32 v67, v67, v52
	v_cvt_pk_bf16_f32 v44, v44, v45
	v_fma_f32 v45, v76, 0.5, -v72
	v_fma_f32 v46, v77, 0.5, -v73
	v_and_b32_e32 v53, 0xffff0000, v53
	v_add_f32_e32 v68, v68, v75
	v_cvt_pk_bf16_f32 v45, v45, v46
	v_fma_f32 v46, v66, 0.5, -v74
	v_fma_f32 v47, v67, 0.5, -v52
	v_add_f32_e32 v69, v69, v53
	v_cvt_pk_bf16_f32 v46, v46, v47
	v_fma_f32 v47, v68, 0.5, -v75
	v_fma_f32 v78, v69, 0.5, -v53
	v_cvt_pk_bf16_f32 v47, v47, v78
	global_store_dwordx4 v[124:125], v[44:47], off offset:2048 sc1
	v_sub_f32_e32 v48, v67, v48
	s_waitcnt vmcnt(15)
	v_lshlrev_b32_e32 v67, 16, v55
	v_sub_f32_e32 v44, v50, v81
	v_sub_f32_e32 v45, v51, v82
	v_sub_f32_e32 v50, v66, v85
	v_lshlrev_b32_e32 v66, 16, v54
	v_and_b32_e32 v54, 0xffff0000, v54
	v_sub_f32_e32 v46, v76, v83
	v_sub_f32_e32 v47, v77, v84
	v_and_b32_e32 v55, 0xffff0000, v55
	v_add_f32_e32 v76, v44, v66
	v_add_f32_e32 v77, v45, v54
	v_sub_f32_e32 v51, v68, v86
	v_lshlrev_b32_e32 v68, 16, v56
	v_and_b32_e32 v56, 0xffff0000, v56
	v_add_f32_e32 v78, v46, v67
	v_add_f32_e32 v79, v47, v55
	v_fma_f32 v44, v76, 0.5, -v66
	v_fma_f32 v45, v77, 0.5, -v54
	v_sub_f32_e32 v49, v69, v49
	v_lshlrev_b32_e32 v69, 16, v57
	v_and_b32_e32 v57, 0xffff0000, v57
	v_add_f32_e32 v80, v50, v68
	v_add_f32_e32 v81, v48, v56
	v_cvt_pk_bf16_f32 v44, v44, v45
	v_fma_f32 v45, v78, 0.5, -v67
	v_fma_f32 v46, v79, 0.5, -v55
	v_add_f32_e32 v82, v51, v69
	v_add_f32_e32 v83, v49, v57
	v_cvt_pk_bf16_f32 v45, v45, v46
	v_fma_f32 v46, v80, 0.5, -v68
	v_fma_f32 v47, v81, 0.5, -v56
	v_cvt_pk_bf16_f32 v46, v46, v47
	v_fma_f32 v47, v82, 0.5, -v69
	v_fma_f32 v48, v83, 0.5, -v57
	v_cvt_pk_bf16_f32 v47, v47, v48
	v_add_co_u32_e32 v48, vcc, s7, v124
	v_sub_f32_e32 v52, v81, v52
	s_nop 0
	v_addc_co_u32_e32 v49, vcc, 0, v125, vcc
	v_add_co_u32_e32 v50, vcc, s8, v124
	v_sub_f32_e32 v53, v83, v53
	s_nop 0
	v_addc_co_u32_e32 v51, vcc, 0, v125, vcc
	global_store_dwordx4 v[50:51], v[44:47], off offset:-4096 sc1
	s_nop 1
	v_sub_f32_e32 v44, v76, v70
	v_sub_f32_e32 v45, v77, v71
	v_sub_f32_e32 v46, v78, v72
	s_waitcnt vmcnt(15)
; __device__ __forceinline__ unsigned cvt_pk_bf16(float lo, float hi) { unsigned r; asm volatile("v_cvt_pk_bf16_f32 %0, %1, %2" : "=v"(r) : "v"(lo), "v"(hi)); return r; }
; #define UNPK8(q, f) const float f[8] = {bf_lo((q).x), bf_hi((q).x), bf_lo((q).y), bf_hi((q).y), bf_lo((q).z), bf_hi((q).z), bf_lo((q).w), bf_hi((q).w)}
; template <int W> __device__ __forceinline__ void pool_run(const bf16_t* up, bf16_t* dp, int t0) {
;     ...
;     for (int j = 0; j < 16; ++j) {
;         UNPK8(q[j + W - 1], cur);
; #pragma unroll
;         for (int e = 0; e < 8; ++e) s[e] += cur[e];
;         const int cnt = (t0 + j + 1) < W ? (t0 + j + 1) : W; const float inv = 1.0f / (float)cnt;
;         u32x4 o; o.x = cvt_pk_bf16(s[0] * inv - cur[0], s[1] * inv - cur[1]); o.y = cvt_pk_bf16(s[2] * inv - cur[2], s[3] * inv - cur[3]);
;         o.z = cvt_pk_bf16(s[4] * inv - cur[4], s[5] * inv - cur[5]); o.w = cvt_pk_bf16(s[6] * inv - cur[6], s[7] * inv - cur[7]);
;         *(u32x4*)(dp + (size_t)j * PW) = o;
;         UNPK8(q[j], old);
; #pragma unroll
;         for (int e = 0; e < 8; ++e) s[e] -= old[e];
;     }
	v_lshlrev_b32_e32 v72, 16, v58
	v_and_b32_e32 v58, 0xffff0000, v58
	v_sub_f32_e32 v47, v79, v73
	v_lshlrev_b32_e32 v73, 16, v59
	v_and_b32_e32 v59, 0xffff0000, v59
	v_add_f32_e32 v76, v44, v72
	v_add_f32_e32 v77, v45, v58
	v_sub_f32_e32 v70, v80, v74
	v_lshlrev_b32_e32 v74, 16, v60
	v_and_b32_e32 v60, 0xffff0000, v60
	v_add_f32_e32 v78, v46, v73
	v_add_f32_e32 v79, v47, v59
	v_fma_f32 v44, v76, 0.5, -v72
	v_fma_f32 v45, v77, 0.5, -v58
	v_sub_f32_e32 v71, v82, v75
	v_lshlrev_b32_e32 v75, 16, v61
	v_add_f32_e32 v70, v70, v74
	v_add_f32_e32 v52, v52, v60
	v_cvt_pk_bf16_f32 v44, v44, v45
	v_fma_f32 v45, v78, 0.5, -v73
	v_fma_f32 v46, v79, 0.5, -v59
	v_and_b32_e32 v61, 0xffff0000, v61
	v_add_f32_e32 v71, v71, v75
	v_cvt_pk_bf16_f32 v45, v45, v46
	v_fma_f32 v46, v70, 0.5, -v74
	v_fma_f32 v47, v52, 0.5, -v60
	v_add_f32_e32 v53, v53, v61
	v_cvt_pk_bf16_f32 v46, v46, v47
	v_fma_f32 v47, v71, 0.5, -v75
	v_fma_f32 v80, v53, 0.5, -v61
	v_cvt_pk_bf16_f32 v47, v47, v80
	global_store_dwordx4 v[48:49], v[44:47], off offset:2048 sc1
	v_sub_f32_e32 v49, v52, v56
	v_sub_f32_e32 v53, v53, v57
	v_sub_f32_e32 v44, v76, v66
	v_sub_f32_e32 v45, v77, v54
	v_sub_f32_e32 v47, v79, v55
	s_waitcnt vmcnt(15)
	v_lshlrev_b32_e32 v54, 16, v62
	v_and_b32_e32 v55, 0xffff0000, v62
	v_sub_f32_e32 v46, v78, v67
	v_lshlrev_b32_e32 v56, 16, v63
	v_and_b32_e32 v57, 0xffff0000, v63
	v_add_f32_e32 v66, v44, v54
	v_add_f32_e32 v67, v45, v55
	v_sub_f32_e32 v48, v70, v68
	v_sub_f32_e32 v52, v71, v69
	v_lshlrev_b32_e32 v62, 16, v64
	v_and_b32_e32 v63, 0xffff0000, v64
	v_add_f32_e32 v68, v46, v56
	v_add_f32_e32 v69, v47, v57
	v_fma_f32 v44, v66, 0.5, -v54
	v_fma_f32 v45, v67, 0.5, -v55
	v_lshlrev_b32_e32 v64, 16, v65
	v_add_f32_e32 v48, v48, v62
	v_add_f32_e32 v49, v49, v63
	v_cvt_pk_bf16_f32 v44, v44, v45
	v_fma_f32 v45, v68, 0.5, -v56
	v_fma_f32 v46, v69, 0.5, -v57
	v_and_b32_e32 v65, 0xffff0000, v65
	v_add_f32_e32 v52, v52, v64
	v_cvt_pk_bf16_f32 v45, v45, v46
	v_fma_f32 v46, v48, 0.5, -v62
	v_fma_f32 v47, v49, 0.5, -v63
	v_add_f32_e32 v53, v53, v65
	v_cvt_pk_bf16_f32 v46, v46, v47
	v_fma_f32 v47, v52, 0.5, -v64
	v_fma_f32 v70, v53, 0.5, -v65
	v_cvt_pk_bf16_f32 v47, v47, v70
	global_store_dwordx4 v[50:51], v[44:47], off sc1
	v_sub_f32_e32 v49, v49, v60
	v_sub_f32_e32 v53, v53, v61
	v_sub_f32_e32 v44, v66, v72
	v_sub_f32_e32 v45, v67, v58
	v_sub_f32_e32 v47, v69, v59
	s_waitcnt vmcnt(15)
	v_lshlrev_b32_e32 v58, 16, v40
	v_and_b32_e32 v59, 0xffff0000, v40
	v_sub_f32_e32 v46, v68, v73
	v_lshlrev_b32_e32 v60, 16, v41
	v_and_b32_e32 v61, 0xffff0000, v41
	v_add_f32_e32 v44, v44, v58
	v_add_f32_e32 v45, v45, v59
	v_sub_f32_e32 v48, v48, v74
	v_lshlrev_b32_e32 v66, 16, v42
	v_and_b32_e32 v67, 0xffff0000, v42
	v_add_f32_e32 v46, v46, v60
	v_add_f32_e32 v47, v47, v61
	v_fma_f32 v40, v44, 0.5, -v58
	v_fma_f32 v41, v45, 0.5, -v59
	v_sub_f32_e32 v52, v52, v75
	v_lshlrev_b32_e32 v68, 16, v43
	v_add_f32_e32 v48, v48, v66
	v_add_f32_e32 v49, v49, v67
	v_cvt_pk_bf16_f32 v40, v40, v41
	v_fma_f32 v41, v46, 0.5, -v60
	v_fma_f32 v42, v47, 0.5, -v61
	v_and_b32_e32 v69, 0xffff0000, v43
	v_add_f32_e32 v52, v52, v68
	v_cvt_pk_bf16_f32 v41, v41, v42
	v_fma_f32 v42, v48, 0.5, -v66
	v_fma_f32 v43, v49, 0.5, -v67
	v_add_f32_e32 v53, v53, v69
	v_cvt_pk_bf16_f32 v42, v42, v43
	v_fma_f32 v43, v52, 0.5, -v68
	v_fma_f32 v70, v53, 0.5, -v69
	v_cvt_pk_bf16_f32 v43, v43, v70
	global_store_dwordx4 v[50:51], v[40:43], off offset:2048 sc1
	s_waitcnt vmcnt(15)
	v_lshlrev_b32_e32 v50, 16, v37
	v_and_b32_e32 v51, 0xffff0000, v37
	v_sub_f32_e32 v40, v44, v54
	v_sub_f32_e32 v41, v45, v55
	v_sub_f32_e32 v44, v48, v62
	v_sub_f32_e32 v45, v49, v63
	v_lshlrev_b32_e32 v48, 16, v36
	v_and_b32_e32 v49, 0xffff0000, v36
	v_sub_f32_e32 v42, v46, v56
	v_sub_f32_e32 v43, v47, v57
	v_add_f32_e32 v56, v40, v48
	v_add_f32_e32 v57, v41, v49
	v_sub_f32_e32 v46, v52, v64
	v_sub_f32_e32 v47, v53, v65
	v_lshlrev_b32_e32 v52, 16, v38
	v_and_b32_e32 v53, 0xffff0000, v38
	v_add_f32_e32 v62, v42, v50
	v_add_f32_e32 v63, v43, v51
	v_fma_f32 v36, v56, 0.5, -v48
	v_fma_f32 v37, v57, 0.5, -v49
	v_lshlrev_b32_e32 v54, 16, v39
	v_and_b32_e32 v55, 0xffff0000, v39
	v_add_f32_e32 v44, v44, v52
	v_add_f32_e32 v45, v45, v53
	v_cvt_pk_bf16_f32 v36, v36, v37
	v_fma_f32 v37, v62, 0.5, -v50
	v_fma_f32 v38, v63, 0.5, -v51
	v_add_f32_e32 v46, v46, v54
	v_add_f32_e32 v47, v47, v55
	v_cvt_pk_bf16_f32 v37, v37, v38
	v_fma_f32 v38, v44, 0.5, -v52
	v_fma_f32 v39, v45, 0.5, -v53
	v_cvt_pk_bf16_f32 v38, v38, v39
	v_fma_f32 v39, v46, 0.5, -v54
	v_fma_f32 v40, v47, 0.5, -v55
	v_cvt_pk_bf16_f32 v39, v39, v40
	v_add_co_u32_e32 v40, vcc, s5, v124
	v_sub_f32_e32 v44, v44, v66
	s_nop 0
	v_addc_co_u32_e32 v41, vcc, 0, v125, vcc
	v_add_co_u32_e32 v42, vcc, s6, v124
	v_sub_f32_e32 v45, v45, v67
	s_nop 0
	v_addc_co_u32_e32 v43, vcc, 0, v125, vcc
	global_store_dwordx4 v[42:43], v[36:39], off offset:-4096 sc1
	v_sub_f32_e32 v46, v46, v68
	v_sub_f32_e32 v47, v47, v69
	v_sub_f32_e32 v36, v56, v58
	v_sub_f32_e32 v37, v57, v59
	s_waitcnt vmcnt(15)
	v_lshlrev_b32_e32 v56, 16, v32
	v_and_b32_e32 v57, 0xffff0000, v32
	v_sub_f32_e32 v38, v62, v60
	v_sub_f32_e32 v39, v63, v61
	v_lshlrev_b32_e32 v58, 16, v33
	v_and_b32_e32 v59, 0xffff0000, v33
	v_add_f32_e32 v36, v36, v56
	v_add_f32_e32 v37, v37, v57
	v_lshlrev_b32_e32 v60, 16, v34
	v_and_b32_e32 v61, 0xffff0000, v34
	v_add_f32_e32 v38, v38, v58
	v_add_f32_e32 v39, v39, v59
	v_fma_f32 v32, v36, 0.5, -v56
	v_fma_f32 v33, v37, 0.5, -v57
	v_lshlrev_b32_e32 v62, 16, v35
	v_add_f32_e32 v44, v44, v60
	v_add_f32_e32 v45, v45, v61
	v_cvt_pk_bf16_f32 v32, v32, v33
	v_fma_f32 v33, v38, 0.5, -v58
	v_fma_f32 v34, v39, 0.5, -v59
	v_and_b32_e32 v63, 0xffff0000, v35
	v_add_f32_e32 v46, v46, v62
	v_cvt_pk_bf16_f32 v33, v33, v34
	v_fma_f32 v34, v44, 0.5, -v60
	v_fma_f32 v35, v45, 0.5, -v61
	v_add_f32_e32 v47, v47, v63
	v_cvt_pk_bf16_f32 v34, v34, v35
	v_fma_f32 v35, v46, 0.5, -v62
	v_fma_f32 v64, v47, 0.5, -v63
	v_cvt_pk_bf16_f32 v35, v35, v64
	global_store_dwordx4 v[40:41], v[32:35], off offset:2048 sc1
	s_waitcnt vmcnt(15)
; __device__ __forceinline__ unsigned cvt_pk_bf16(float lo, float hi) { unsigned r; asm volatile("v_cvt_pk_bf16_f32 %0, %1, %2" : "=v"(r) : "v"(lo), "v"(hi)); return r; }
; #define UNPK8(q, f) const float f[8] = {bf_lo((q).x), bf_hi((q).x), bf_lo((q).y), bf_hi((q).y), bf_lo((q).z), bf_hi((q).z), bf_lo((q).w), bf_hi((q).w)}
; template <int W> __device__ __forceinline__ void pool_run(const bf16_t* up, bf16_t* dp, int t0) {
;     ...
;     for (int j = 0; j < 16; ++j) {
;         UNPK8(q[j + W - 1], cur);
; #pragma unroll
;         for (int e = 0; e < 8; ++e) s[e] += cur[e];
;         const int cnt = (t0 + j + 1) < W ? (t0 + j + 1) : W; const float inv = 1.0f / (float)cnt;
;         u32x4 o; o.x = cvt_pk_bf16(s[0] * inv - cur[0], s[1] * inv - cur[1]); o.y = cvt_pk_bf16(s[2] * inv - cur[2], s[3] * inv - cur[3]);
;         o.z = cvt_pk_bf16(s[4] * inv - cur[4], s[5] * inv - cur[5]); o.w = cvt_pk_bf16(s[6] * inv - cur[6], s[7] * inv - cur[7]);
;         *(u32x4*)(dp + (size_t)j * PW) = o;
;         UNPK8(q[j], old);
; #pragma unroll
;         for (int e = 0; e < 8; ++e) s[e] -= old[e];
;     }
	v_lshlrev_b32_e32 v40, 16, v28
	v_and_b32_e32 v41, 0xffff0000, v28
	v_sub_f32_e32 v32, v36, v48
	v_sub_f32_e32 v33, v37, v49
	v_sub_f32_e32 v34, v38, v50
	v_sub_f32_e32 v35, v39, v51
	v_sub_f32_e32 v36, v44, v52
	v_sub_f32_e32 v37, v45, v53
	v_lshlrev_b32_e32 v44, 16, v29
	v_and_b32_e32 v45, 0xffff0000, v29
	v_add_f32_e32 v32, v32, v40
	v_add_f32_e32 v33, v33, v41
	v_sub_f32_e32 v38, v46, v54
	v_sub_f32_e32 v39, v47, v55
	v_lshlrev_b32_e32 v46, 16, v30
	v_and_b32_e32 v47, 0xffff0000, v30
	v_add_f32_e32 v34, v34, v44
	v_add_f32_e32 v35, v35, v45
	v_fma_f32 v28, v32, 0.5, -v40
	v_fma_f32 v29, v33, 0.5, -v41
	v_lshlrev_b32_e32 v48, 16, v31
	v_add_f32_e32 v36, v36, v46
	v_add_f32_e32 v37, v37, v47
	v_cvt_pk_bf16_f32 v28, v28, v29
	v_fma_f32 v29, v34, 0.5, -v44
	v_fma_f32 v30, v35, 0.5, -v45
	v_and_b32_e32 v49, 0xffff0000, v31
	v_add_f32_e32 v38, v38, v48
	v_cvt_pk_bf16_f32 v29, v29, v30
	v_fma_f32 v30, v36, 0.5, -v46
	v_fma_f32 v31, v37, 0.5, -v47
	v_add_f32_e32 v39, v39, v49
	v_cvt_pk_bf16_f32 v30, v30, v31
	v_fma_f32 v31, v38, 0.5, -v48
	v_fma_f32 v50, v39, 0.5, -v49
	v_cvt_pk_bf16_f32 v31, v31, v50
	global_store_dwordx4 v[42:43], v[28:31], off sc1
	s_waitcnt vmcnt(15)
	v_lshlrev_b32_e32 v50, 16, v26
	v_and_b32_e32 v51, 0xffff0000, v26
	v_sub_f32_e32 v28, v32, v56
	v_sub_f32_e32 v29, v33, v57
	v_sub_f32_e32 v32, v36, v60
	v_sub_f32_e32 v33, v37, v61
	v_lshlrev_b32_e32 v36, 16, v24
	v_and_b32_e32 v37, 0xffff0000, v24
	v_sub_f32_e32 v30, v34, v58
	v_sub_f32_e32 v31, v35, v59
	v_sub_f32_e32 v34, v38, v62
	v_sub_f32_e32 v35, v39, v63
	v_lshlrev_b32_e32 v38, 16, v25
	v_and_b32_e32 v39, 0xffff0000, v25
	v_add_f32_e32 v28, v28, v36
	v_add_f32_e32 v29, v29, v37
	v_add_f32_e32 v30, v30, v38
	v_add_f32_e32 v31, v31, v39
	v_fma_f32 v24, v28, 0.5, -v36
	v_fma_f32 v25, v29, 0.5, -v37
	v_lshlrev_b32_e32 v52, 16, v27
	v_add_f32_e32 v32, v32, v50
	v_add_f32_e32 v33, v33, v51
	v_cvt_pk_bf16_f32 v24, v24, v25
	v_fma_f32 v25, v30, 0.5, -v38
	v_fma_f32 v26, v31, 0.5, -v39
	v_and_b32_e32 v53, 0xffff0000, v27
	v_add_f32_e32 v34, v34, v52
	v_cvt_pk_bf16_f32 v25, v25, v26
	v_fma_f32 v26, v32, 0.5, -v50
	v_fma_f32 v27, v33, 0.5, -v51
	v_add_f32_e32 v35, v35, v53
	v_cvt_pk_bf16_f32 v26, v26, v27
	v_fma_f32 v27, v34, 0.5, -v52
	v_fma_f32 v54, v35, 0.5, -v53
	v_cvt_pk_bf16_f32 v27, v27, v54
	global_store_dwordx4 v[42:43], v[24:27], off offset:2048 sc1
	s_waitcnt vmcnt(15)
	v_lshlrev_b32_e32 v42, 16, v23
	v_and_b32_e32 v43, 0xffff0000, v23
	v_sub_f32_e32 v24, v28, v40
	v_sub_f32_e32 v25, v29, v41
	v_sub_f32_e32 v28, v32, v46
	v_sub_f32_e32 v29, v33, v47
	v_lshlrev_b32_e32 v32, 16, v20
	v_and_b32_e32 v33, 0xffff0000, v20
	v_sub_f32_e32 v26, v30, v44
	v_sub_f32_e32 v27, v31, v45
	v_sub_f32_e32 v30, v34, v48
	v_sub_f32_e32 v31, v35, v49
	v_lshlrev_b32_e32 v34, 16, v21
	v_and_b32_e32 v35, 0xffff0000, v21
	v_add_f32_e32 v44, v24, v32
	v_add_f32_e32 v45, v25, v33
	v_lshlrev_b32_e32 v40, 16, v22
	v_and_b32_e32 v41, 0xffff0000, v22
	v_add_f32_e32 v46, v26, v34
	v_add_f32_e32 v47, v27, v35
	v_fma_f32 v20, v44, 0.5, -v32
	v_fma_f32 v21, v45, 0.5, -v33
	v_add_f32_e32 v28, v28, v40
	v_add_f32_e32 v29, v29, v41
	v_cvt_pk_bf16_f32 v20, v20, v21
	v_fma_f32 v21, v46, 0.5, -v34
	v_fma_f32 v22, v47, 0.5, -v35
	v_add_f32_e32 v30, v30, v42
	v_add_f32_e32 v31, v31, v43
	v_cvt_pk_bf16_f32 v21, v21, v22
	v_fma_f32 v22, v28, 0.5, -v40
	v_fma_f32 v23, v29, 0.5, -v41
	v_cvt_pk_bf16_f32 v22, v22, v23
	v_fma_f32 v23, v30, 0.5, -v42
	v_fma_f32 v24, v31, 0.5, -v43
	v_cvt_pk_bf16_f32 v23, v23, v24
	v_add_co_u32_e32 v24, vcc, s1, v124
	v_sub_f32_e32 v28, v28, v50
	s_nop 0
	v_addc_co_u32_e32 v25, vcc, 0, v125, vcc
	v_add_co_u32_e32 v26, vcc, s4, v124
	v_sub_f32_e32 v29, v29, v51
	s_nop 0
	v_addc_co_u32_e32 v27, vcc, 0, v125, vcc
	global_store_dwordx4 v[26:27], v[20:23], off offset:-4096 sc1
	v_sub_f32_e32 v30, v30, v52
	v_sub_f32_e32 v31, v31, v53
	v_sub_f32_e32 v20, v44, v36
	v_sub_f32_e32 v21, v45, v37
	s_waitcnt vmcnt(15)
	v_lshlrev_b32_e32 v36, 16, v16
	v_and_b32_e32 v37, 0xffff0000, v16
	v_sub_f32_e32 v22, v46, v38
	v_sub_f32_e32 v23, v47, v39
	v_lshlrev_b32_e32 v38, 16, v17
	v_and_b32_e32 v39, 0xffff0000, v17
	v_add_f32_e32 v20, v20, v36
	v_add_f32_e32 v21, v21, v37
	v_lshlrev_b32_e32 v44, 16, v18
	v_and_b32_e32 v45, 0xffff0000, v18
	v_add_f32_e32 v22, v22, v38
	v_add_f32_e32 v23, v23, v39
	v_fma_f32 v16, v20, 0.5, -v36
	v_fma_f32 v17, v21, 0.5, -v37
	v_lshlrev_b32_e32 v46, 16, v19
	v_add_f32_e32 v28, v28, v44
	v_add_f32_e32 v29, v29, v45
	v_cvt_pk_bf16_f32 v16, v16, v17
	v_fma_f32 v17, v22, 0.5, -v38
	v_fma_f32 v18, v23, 0.5, -v39
	v_and_b32_e32 v47, 0xffff0000, v19
	v_add_f32_e32 v30, v30, v46
	v_cvt_pk_bf16_f32 v17, v17, v18
	v_fma_f32 v18, v28, 0.5, -v44
	v_fma_f32 v19, v29, 0.5, -v45
	v_add_f32_e32 v31, v31, v47
	v_cvt_pk_bf16_f32 v18, v18, v19
	v_fma_f32 v19, v30, 0.5, -v46
	v_fma_f32 v48, v31, 0.5, -v47
	v_cvt_pk_bf16_f32 v19, v19, v48
	global_store_dwordx4 v[24:25], v[16:19], off offset:2048 sc1
	s_waitcnt vmcnt(15)
	v_lshlrev_b32_e32 v24, 16, v12
	v_and_b32_e32 v25, 0xffff0000, v12
	v_sub_f32_e32 v16, v20, v32
	v_sub_f32_e32 v17, v21, v33
	v_sub_f32_e32 v18, v22, v34
	v_sub_f32_e32 v19, v23, v35
	v_sub_f32_e32 v20, v28, v40
	v_sub_f32_e32 v21, v29, v41
	v_lshlrev_b32_e32 v28, 16, v13
	v_and_b32_e32 v29, 0xffff0000, v13
	v_add_f32_e32 v16, v16, v24
	v_add_f32_e32 v17, v17, v25
	v_sub_f32_e32 v22, v30, v42
	v_sub_f32_e32 v23, v31, v43
	v_lshlrev_b32_e32 v30, 16, v14
	v_and_b32_e32 v31, 0xffff0000, v14
	v_add_f32_e32 v18, v18, v28
	v_add_f32_e32 v19, v19, v29
	v_fma_f32 v12, v16, 0.5, -v24
	v_fma_f32 v13, v17, 0.5, -v25
	v_lshlrev_b32_e32 v32, 16, v15
	v_add_f32_e32 v20, v20, v30
	v_add_f32_e32 v21, v21, v31
	v_cvt_pk_bf16_f32 v12, v12, v13
	v_fma_f32 v13, v18, 0.5, -v28
	v_fma_f32 v14, v19, 0.5, -v29
	v_and_b32_e32 v33, 0xffff0000, v15
	v_add_f32_e32 v22, v22, v32
	v_cvt_pk_bf16_f32 v13, v13, v14
	v_fma_f32 v14, v20, 0.5, -v30
	v_fma_f32 v15, v21, 0.5, -v31
	v_add_f32_e32 v23, v23, v33
	v_cvt_pk_bf16_f32 v14, v14, v15
	v_fma_f32 v15, v22, 0.5, -v32
	v_fma_f32 v34, v23, 0.5, -v33
	v_cvt_pk_bf16_f32 v15, v15, v34
	global_store_dwordx4 v[26:27], v[12:15], off sc1
	s_waitcnt vmcnt(15)
; template <int W> __device__ __forceinline__ void pool_run(const bf16_t* up, bf16_t* dp, int t0) {
;     ...
;     for (int j = 0; j < 16; ++j) {
;         UNPK8(q[j + W - 1], cur);
; #pragma unroll
;         for (int e = 0; e < 8; ++e) s[e] += cur[e];
;         const int cnt = (t0 + j + 1) < W ? (t0 + j + 1) : W; const float inv = 1.0f / (float)cnt;
;         u32x4 o; o.x = cvt_pk_bf16(s[0] * inv - cur[0], s[1] * inv - cur[1]); o.y = cvt_pk_bf16(s[2] * inv - cur[2], s[3] * inv - cur[3]);
;         o.z = cvt_pk_bf16(s[4] * inv - cur[4], s[5] * inv - cur[5]); o.w = cvt_pk_bf16(s[6] * inv - cur[6], s[7] * inv - cur[7]);
;         *(u32x4*)(dp + (size_t)j * PW) = o;
;         UNPK8(q[j], old);
; #pragma unroll
;         for (int e = 0; e < 8; ++e) s[e] -= old[e];
;     }
; __global__ void __launch_bounds__(NTHR, 2) hybrid_block_fwd(Args a) {
;     ...
;         for (int idx = gtid; idx < 256 * 3 * (LW / 4); idx += NT) {
;             const int c4 = (idx % (LW / 4)) * 4, rr = (idx / (LW / 4)) % 3, blk = idx / (3 * (LW / 4));
;             const bool seq0 = (blk & 127) == 0; const int pb = seq0 ? blk : blk - 1; const size_t row = (size_t)blk * 64 + rr;
;             const float* H = HEADU + (size_t)blk * 3 * LW + c4; const float* T = TAILU + (size_t)pb * 3 * LW + c4;
;             const f32x4 z = (f32x4){0.f, 0.f, 0.f, 0.f};
;             const f32x4 t0 = *(const f32x4*)(T), t1 = *(const f32x4*)(T + LW), t2 = *(const f32x4*)(T + 2 * LW);
;             const f32x4 h0 = *(const f32x4*)(H), h1 = *(const f32x4*)(H + (rr >= 1 ? LW : 0)), h2 = *(const f32x4*)(H + (rr >= 2 ? 2 * LW : 0));
;             const f32x4 T0 = seq0 ? z : t0, T1 = seq0 ? z : t1, T2 = seq0 ? z : t2;
;             const f32x4 u0 = rr == 0 ? h0 : (rr == 1 ? h1 : h2);
;             const f32x4 u1 = rr == 0 ? T2 : (rr == 1 ? h0 : h1);
;             const f32x4 u2 = rr == 0 ? T1 : (rr == 1 ? T2 : h0);
;             const f32x4 u3 = rr == 0 ? T0 : (rr == 1 ? T1 : T2);
;             const f32x4 v = *(const f32x4*)(lru_conv_b + c4) + *(const f32x4*)(lru_conv_w + c4) * u3 + *(const f32x4*)(lru_conv_w + LW + c4) * u2 + *(const f32x4*)(lru_conv_w + 2 * LW + c4) * u1 + *(const f32x4*)(lru_conv_w + 3 * LW + c4) * u0;
;             u32x2 w; w.x = cvt_pk_bf16(v[0], v[1]); w.y = cvt_pk_bf16(v[2], v[3]);
;             *(u32x2*)(VV + row * LW + c4) = w;
;         }
	v_lshlrev_b32_e32 v34, 16, v10
	v_and_b32_e32 v35, 0xffff0000, v10
	v_sub_f32_e32 v12, v16, v36
	v_sub_f32_e32 v13, v17, v37
	v_sub_f32_e32 v16, v20, v44
	v_sub_f32_e32 v17, v21, v45
	v_lshlrev_b32_e32 v20, 16, v8
	v_and_b32_e32 v21, 0xffff0000, v8
	v_sub_f32_e32 v14, v18, v38
	v_sub_f32_e32 v15, v19, v39
	v_sub_f32_e32 v18, v22, v46
	v_sub_f32_e32 v19, v23, v47
	v_lshlrev_b32_e32 v22, 16, v9
	v_and_b32_e32 v23, 0xffff0000, v9
	v_add_f32_e32 v12, v12, v20
	v_add_f32_e32 v13, v13, v21
	v_add_f32_e32 v14, v14, v22
	v_add_f32_e32 v15, v15, v23
	v_fma_f32 v8, v12, 0.5, -v20
	v_fma_f32 v9, v13, 0.5, -v21
	v_lshlrev_b32_e32 v36, 16, v11
	v_add_f32_e32 v16, v16, v34
	v_add_f32_e32 v17, v17, v35
	v_cvt_pk_bf16_f32 v8, v8, v9
	v_fma_f32 v9, v14, 0.5, -v22
	v_fma_f32 v10, v15, 0.5, -v23
	v_and_b32_e32 v37, 0xffff0000, v11
	v_add_f32_e32 v18, v18, v36
	v_cvt_pk_bf16_f32 v9, v9, v10
	v_fma_f32 v10, v16, 0.5, -v34
	v_fma_f32 v11, v17, 0.5, -v35
	v_add_f32_e32 v19, v19, v37
	v_cvt_pk_bf16_f32 v10, v10, v11
	v_fma_f32 v11, v18, 0.5, -v36
	v_fma_f32 v38, v19, 0.5, -v37
	v_cvt_pk_bf16_f32 v11, v11, v38
	global_store_dwordx4 v[26:27], v[8:11], off offset:2048 sc1
	s_nop 1
	v_sub_f32_e32 v8, v12, v24
	v_sub_f32_e32 v9, v13, v25
	v_sub_f32_e32 v12, v16, v30
	s_waitcnt vmcnt(15)
	v_lshlrev_b32_e32 v16, 16, v4
	v_and_b32_e32 v4, 0xffff0000, v4
	v_sub_f32_e32 v10, v14, v28
	v_sub_f32_e32 v11, v15, v29
	v_sub_f32_e32 v13, v17, v31
	v_lshlrev_b32_e32 v17, 16, v5
	v_and_b32_e32 v5, 0xffff0000, v5
	v_add_f32_e32 v24, v8, v16
	v_add_f32_e32 v25, v9, v4
	v_sub_f32_e32 v14, v18, v32
	v_lshlrev_b32_e32 v18, 16, v6
	v_and_b32_e32 v6, 0xffff0000, v6
	v_add_f32_e32 v10, v10, v17
	v_add_f32_e32 v11, v11, v5
	v_fma_f32 v8, v24, 0.5, -v16
	v_fma_f32 v4, v25, 0.5, -v4
	v_sub_f32_e32 v15, v19, v33
	v_lshlrev_b32_e32 v19, 16, v7
	v_and_b32_e32 v7, 0xffff0000, v7
	v_add_f32_e32 v12, v12, v18
	v_add_f32_e32 v13, v13, v6
	v_cvt_pk_bf16_f32 v4, v8, v4
	v_fma_f32 v8, v10, 0.5, -v17
	v_fma_f32 v5, v11, 0.5, -v5
	v_add_f32_e32 v14, v14, v19
	v_add_f32_e32 v15, v15, v7
	v_cvt_pk_bf16_f32 v5, v8, v5
	v_fma_f32 v8, v12, 0.5, -v18
	v_fma_f32 v6, v13, 0.5, -v6
	v_cvt_pk_bf16_f32 v6, v8, v6
	v_fma_f32 v8, v14, 0.5, -v19
	v_fma_f32 v7, v15, 0.5, -v7
	v_cvt_pk_bf16_f32 v7, v8, v7
	v_add_co_u32_e32 v8, vcc, s0, v124
	s_nop 1
	v_addc_co_u32_e32 v9, vcc, 0, v125, vcc
	global_store_dwordx4 v[8:9], v[4:7], off sc1
	v_sub_f32_e32 v8, v12, v34
	s_waitcnt vmcnt(15)
	v_lshlrev_b32_e32 v12, 16, v0
	v_sub_f32_e32 v4, v24, v20
	v_sub_f32_e32 v5, v25, v21
	v_and_b32_e32 v0, 0xffff0000, v0
	v_sub_f32_e32 v6, v10, v22
	v_sub_f32_e32 v7, v11, v23
	v_sub_f32_e32 v9, v13, v35
	v_lshlrev_b32_e32 v13, 16, v1
	v_and_b32_e32 v1, 0xffff0000, v1
	v_add_f32_e32 v4, v4, v12
	v_add_f32_e32 v5, v5, v0
	v_sub_f32_e32 v10, v14, v36
	v_sub_f32_e32 v11, v15, v37
	v_lshlrev_b32_e32 v14, 16, v2
	v_and_b32_e32 v2, 0xffff0000, v2
	v_lshlrev_b32_e32 v15, 16, v3
	v_and_b32_e32 v3, 0xffff0000, v3
	v_add_f32_e32 v6, v6, v13
	v_add_f32_e32 v7, v7, v1
	v_fma_f32 v4, v4, 0.5, -v12
	v_fma_f32 v0, v5, 0.5, -v0
	v_add_f32_e32 v8, v8, v14
	v_add_f32_e32 v9, v9, v2
	v_add_f32_e32 v11, v11, v3
	v_cvt_pk_bf16_f32 v0, v4, v0
	v_fma_f32 v4, v6, 0.5, -v13
	v_fma_f32 v1, v7, 0.5, -v1
	v_add_f32_e32 v10, v10, v15
	v_cvt_pk_bf16_f32 v1, v4, v1
	v_fma_f32 v4, v8, 0.5, -v14
	v_fma_f32 v2, v9, 0.5, -v2
	v_fma_f32 v3, v11, 0.5, -v3
	v_cvt_pk_bf16_f32 v2, v4, v2
	v_fma_f32 v4, v10, 0.5, -v15
	v_cvt_pk_bf16_f32 v3, v4, v3
.LBB0_460:
	v_add_co_u32_e32 v4, vcc, 0x7000, v124
	s_mov_b32 s0, 0x60000
	s_nop 0
	v_addc_co_u32_e32 v5, vcc, 0, v125, vcc
	v_cmp_gt_i32_e32 vcc, s0, v128
	global_store_dwordx4 v[4:5], v[0:3], off offset:2048 sc1
	s_and_saveexec_b64 s[6:7], vcc
	s_cbranch_execz .LBB0_465
	v_lshlrev_b32_e32 v36, 2, v128
	s_mov_b64 s[8:9], 0
	s_mov_b32 s12, 0x55555556
	s_mov_b32 s13, 0x2aaaaaab
	s_movk_i32 s14, 0x2000
	v_mov_b32_e32 v37, 0x2000
	v_mov_b32_e32 v25, 0
	s_mov_b32 s15, 0x3ffff
	v_mov_b32_e32 v38, 0x4000
	s_branch .LBB0_463
.LBB0_462:
	s_or_b64 exec, exec, s[10:11]
	v_lshl_add_u64 v[34:35], s[66:67], 0, v[32:33]
	global_load_dwordx4 v[40:43], v[34:35], off
	v_lshl_add_u64 v[34:35], s[64:65], 0, v[32:33]
	global_load_dwordx4 v[44:47], v[34:35], off
	v_lshl_add_u64 v[34:35], s[56:57], 0, v[32:33]
	global_load_dwordx4 v[48:51], v[34:35], off
	v_lshl_add_u64 v[34:35], s[60:61], 0, v[32:33]
	global_load_dwordx4 v[52:55], v[34:35], off
	v_lshl_add_u64 v[32:33], s[16:17], 0, v[32:33]
	global_load_dwordx4 v[32:35], v[32:33], off
	v_cndmask_b32_e64 v20, 0, v20, s[0:1]
	v_cndmask_b32_e64 v21, 0, v21, s[0:1]
	v_cndmask_b32_e64 v22, 0, v22, s[0:1]
	v_cndmask_b32_e64 v23, 0, v23, s[0:1]
	v_cndmask_b32_e64 v18, 0, v18, s[0:1]
	v_cndmask_b32_e64 v19, 0, v19, s[0:1]
	v_cndmask_b32_e64 v16, 0, v16, s[0:1]
	v_cndmask_b32_e64 v17, 0, v17, s[0:1]
	v_cndmask_b32_e64 v24, 0, v12, s[0:1]
	v_cndmask_b32_e64 v39, 0, v13, s[0:1]
	v_cndmask_b32_e64 v14, 0, v14, s[0:1]
	v_cndmask_b32_e64 v15, 0, v15, s[0:1]
	v_cmp_eq_u32_e64 s[0:1], 1, v30
	v_ashrrev_i32_e32 v29, 31, v28
	v_lshlrev_b64 v[12:13], 12, v[30:31]
	s_waitcnt vmcnt(5)
	v_cndmask_b32_e64 v8, v8, v4, s[0:1]
	v_cndmask_b32_e64 v9, v9, v5, s[0:1]
	v_cndmask_b32_e64 v10, v10, v6, s[0:1]
	v_cndmask_b32_e64 v11, v11, v7, s[0:1]
	v_cndmask_b32_e32 v8, v8, v24, vcc
	v_cndmask_b32_e64 v31, v6, v14, s[0:1]
	v_cndmask_b32_e64 v56, v7, v15, s[0:1]
	v_cndmask_b32_e64 v57, v4, v24, s[0:1]
	v_cndmask_b32_e64 v58, v5, v39, s[0:1]
	v_cndmask_b32_e64 v24, v24, v16, s[0:1]
	v_cndmask_b32_e64 v59, v39, v17, s[0:1]
	v_lshlrev_b64 v[4:5], 18, v[28:29]
	v_cndmask_b32_e64 v60, v14, v18, s[0:1]
	v_cndmask_b32_e64 v61, v15, v19, s[0:1]
	v_cndmask_b32_e32 v7, v11, v15, vcc
	v_cndmask_b32_e32 v6, v10, v14, vcc
	v_cndmask_b32_e32 v15, v56, v19, vcc
	v_cndmask_b32_e32 v14, v31, v18, vcc
	v_cndmask_b32_e32 v19, v59, v21, vcc
	v_cndmask_b32_e32 v18, v24, v20, vcc
	v_lshl_add_u64 v[4:5], s[54:55], 0, v[4:5]
	v_cndmask_b32_e32 v11, v58, v17, vcc
	v_cndmask_b32_e32 v10, v57, v16, vcc
	v_cndmask_b32_e32 v17, v61, v23, vcc
	v_cndmask_b32_e32 v16, v60, v22, vcc
	v_lshl_add_u64 v[4:5], v[4:5], 0, v[12:13]
	v_cndmask_b32_e32 v9, v9, v39, vcc
	v_add_u32_e32 v30, 0x20000, v128
	v_cmp_lt_i32_e64 s[4:5], s15, v128
	v_add_u32_e32 v36, 0x80000, v36
	s_or_b64 s[8:9], s[4:5], s[8:9]
	v_lshl_add_u64 v[4:5], v[26:27], 1, v[4:5]
	v_mov_b32_e32 v128, v30
	s_waitcnt vmcnt(3)
	v_pk_fma_f32 v[12:13], v[18:19], v[44:45], v[40:41]
	v_pk_fma_f32 v[16:17], v[16:17], v[46:47], v[42:43]
	s_waitcnt vmcnt(2)
	v_pk_fma_f32 v[10:11], v[10:11], v[48:49], v[12:13]
	v_pk_fma_f32 v[14:15], v[14:15], v[50:51], v[16:17]
	s_waitcnt vmcnt(1)
	v_pk_fma_f32 v[8:9], v[8:9], v[52:53], v[10:11]
	v_pk_fma_f32 v[6:7], v[6:7], v[54:55], v[14:15]
	s_waitcnt vmcnt(0)
	v_pk_fma_f32 v[0:1], v[0:1], v[32:33], v[8:9]
	v_pk_fma_f32 v[2:3], v[2:3], v[34:35], v[6:7]
	v_cvt_pk_bf16_f32 v0, v0, v1
	s_nop 0
	v_cvt_pk_bf16_f32 v1, v2, v3
	global_store_dwordx2 v[4:5], v[0:1], off sc1
	s_andn2_b64 exec, exec, s[8:9]
	s_cbranch_execz .LBB0_465

; __device__ __forceinline__ unsigned cvt_pk_bf16(float lo, float hi) { unsigned r; asm volatile("v_cvt_pk_bf16_f32 %0, %1, %2" : "=v"(r) : "v"(lo), "v"(hi)); return r; }
; __global__ void __launch_bounds__(NTHR, 2) hybrid_block_fwd(Args a) {
;     ...
;         for (int idx = gtid; idx < 256 * 2 * (FF / 4); idx += NT) {
;             const int f4 = (idx % (FF / 4)) * 4, rr = (idx / (FF / 4)) & 1, blk = idx / (2 * (FF / 4));
;             const bool seq0 = (blk & 127) == 0; const size_t row = (size_t)blk * 64 + rr;
;             const f32x4 z = (f32x4){0.f, 0.f, 0.f, 0.f};
;             const f32x4 gc = *(const f32x4*)(HEADG + ((size_t)blk * 2 + rr) * FF + f4), vv = *(const f32x4*)(HEADV + ((size_t)blk * 2 + rr) * FF + f4);
;             f32x4 p1, p2;
;             if (rr == 0) { p1 = seq0 ? z : *(const f32x4*)(TAILG + ((size_t)(blk - 1) * 2 + 1) * FF + f4); p2 = seq0 ? z : *(const f32x4*)(TAILG + ((size_t)(blk - 1) * 2 + 0) * FF + f4); }
;             else { p1 = *(const f32x4*)(HEADG + ((size_t)blk * 2 + 0) * FF + f4); p2 = seq0 ? z : *(const f32x4*)(TAILG + ((size_t)(blk - 1) * 2 + 1) * FF + f4); }
;             const f32x4 cv = *(const f32x4*)(ffn_conv_b + f4) + *(const f32x4*)(ffn_conv_w + f4) * p2 + *(const f32x4*)(ffn_conv_w + FF + f4) * p1 + *(const f32x4*)(ffn_conv_w + 2 * FF + f4) * gc;
;             u32x2 w; w.x = cvt_pk_bf16(gelu_tanh(cv[0]) * vv[0], gelu_tanh(cv[1]) * vv[1]); w.y = cvt_pk_bf16(gelu_tanh(cv[2]) * vv[2], gelu_tanh(cv[3]) * vv[3]);
;             *(u32x2*)(ACT + row * FF + f4) = w;
;         }
.LBB0_1002:
	s_or_b64 exec, exec, s[0:1]
	s_waitcnt lgkmcnt(0)
	v_mov_b32_e32 v0, v212
	v_readlane_b32 s0, v248, 8
	s_barrier
	s_mov_b64 s[4:5], exec
	v_add_u32_e32 v1, s0, v0
	s_mov_b32 s6, 0x2aaaaaab
	v_mul_hi_i32 v2, v1, s6
	v_ashrrev_i32_e32 v3, 8, v2
	v_lshlrev_b32_e32 v4, 4, v1
	v_mul_u32_u24_e32 v5, 0x6000, v3
	v_sub_u32_e32 v4, v4, v5
	v_mov_b32_e32 v49, v3
	v_add_u32_e32 v6, v5, v4
	v_add_u32_e32 v7, 0x2700000, v6
	global_load_dwordx4 v[16:19], v7, s[94:95]
	v_add_u32_e32 v7, 0x3300000, v6
	global_load_dwordx4 v[20:23], v7, s[94:95]
	v_and_b32_e32 v8, 1, v3
	v_max_i32_e32 v9, 1, v3
	v_add_u32_e32 v9, -1, v9
	v_mul_u32_u24_e32 v9, 0x6000, v9
	v_add_u32_e32 v9, v9, v4
	v_cmp_eq_u32_e32 vcc, 1, v8
	v_mov_b32_e32 v7, 0x1b00000
	v_mov_b32_e32 v5, 0x2700000
	v_cndmask_b32_e32 v7, v7, v5, vcc
	v_add_u32_e32 v7, v7, v9
	global_load_dwordx4 v[24:27], v7, s[94:95]
	v_max_i32_e32 v9, 2, v3
	v_add_u32_e32 v9, -2, v9
	v_mul_u32_u24_e32 v9, 0x6000, v9
	v_add_u32_e32 v9, v9, v4
	v_add_u32_e32 v9, 0x1b00000, v9
	global_load_dwordx4 v[28:31], v9, s[94:95]
	global_load_dwordx4 v[32:35], v4, s[86:87]
	global_load_dwordx4 v[36:39], v4, s[84:85]
	global_load_dwordx4 v[40:43], v4, s[16:17]
	global_load_dwordx4 v[44:47], v4, s[18:19]
	v_lshrrev_b32_e32 v5, 1, v3
	v_lshl_or_b32 v5, v5, 6, v8
	v_mul_u32_u24_e32 v5, 0x3000, v5
	v_lshrrev_b32_e32 v7, 1, v4
	v_add_u32_e32 v5, v5, v7
	v_add_u32_e32 v48, 0x12700000, v5
	v_add_u32_e32 v1, 0x20000, v1
	v_mul_hi_i32 v2, v1, s6
	v_ashrrev_i32_e32 v3, 8, v2
	v_lshlrev_b32_e32 v4, 4, v1
	v_mul_u32_u24_e32 v5, 0x6000, v3
	v_sub_u32_e32 v4, v4, v5
	v_mov_b32_e32 v85, v3
	v_add_u32_e32 v6, v5, v4
	v_add_u32_e32 v7, 0x2700000, v6
	global_load_dwordx4 v[52:55], v7, s[94:95]
	v_add_u32_e32 v7, 0x3300000, v6
	global_load_dwordx4 v[56:59], v7, s[94:95]
	v_and_b32_e32 v8, 1, v3
	v_max_i32_e32 v9, 1, v3
	v_add_u32_e32 v9, -1, v9
	v_mul_u32_u24_e32 v9, 0x6000, v9
	v_add_u32_e32 v9, v9, v4
	v_cmp_eq_u32_e32 vcc, 1, v8
	v_mov_b32_e32 v7, 0x1b00000
	v_mov_b32_e32 v5, 0x2700000
	v_cndmask_b32_e32 v7, v7, v5, vcc
	v_add_u32_e32 v7, v7, v9
	global_load_dwordx4 v[60:63], v7, s[94:95]
	v_max_i32_e32 v9, 2, v3
	v_add_u32_e32 v9, -2, v9
	v_mul_u32_u24_e32 v9, 0x6000, v9
	v_add_u32_e32 v9, v9, v4
	v_add_u32_e32 v9, 0x1b00000, v9
	global_load_dwordx4 v[64:67], v9, s[94:95]
	global_load_dwordx4 v[68:71], v4, s[86:87]
	global_load_dwordx4 v[72:75], v4, s[84:85]
	global_load_dwordx4 v[76:79], v4, s[16:17]
	global_load_dwordx4 v[80:83], v4, s[18:19]
	v_lshrrev_b32_e32 v5, 1, v3
	v_lshl_or_b32 v5, v5, 6, v8
	v_mul_u32_u24_e32 v5, 0x3000, v5
	v_lshrrev_b32_e32 v7, 1, v4
	v_add_u32_e32 v5, v5, v7
	v_add_u32_e32 v84, 0x12700000, v5
	v_add_u32_e32 v1, 0x20000, v1
	v_mul_hi_i32 v2, v1, s6
	v_ashrrev_i32_e32 v3, 8, v2
	v_lshlrev_b32_e32 v4, 4, v1
	v_mul_u32_u24_e32 v5, 0x6000, v3
	v_sub_u32_e32 v4, v4, v5
	v_mov_b32_e32 v121, v3
	v_add_u32_e32 v6, v5, v4
	v_add_u32_e32 v7, 0x2700000, v6
	global_load_dwordx4 v[88:91], v7, s[94:95]
	v_add_u32_e32 v7, 0x3300000, v6
	global_load_dwordx4 v[92:95], v7, s[94:95]
	v_and_b32_e32 v8, 1, v3
	v_max_i32_e32 v9, 1, v3
	v_add_u32_e32 v9, -1, v9
	v_mul_u32_u24_e32 v9, 0x6000, v9
	v_add_u32_e32 v9, v9, v4
	v_cmp_eq_u32_e32 vcc, 1, v8
	v_mov_b32_e32 v7, 0x1b00000
	v_mov_b32_e32 v5, 0x2700000
	v_cndmask_b32_e32 v7, v7, v5, vcc
	v_add_u32_e32 v7, v7, v9
	global_load_dwordx4 v[96:99], v7, s[94:95]
	v_max_i32_e32 v9, 2, v3
	v_add_u32_e32 v9, -2, v9
	v_mul_u32_u24_e32 v9, 0x6000, v9
	v_add_u32_e32 v9, v9, v4
	v_add_u32_e32 v9, 0x1b00000, v9
	global_load_dwordx4 v[100:103], v9, s[94:95]
	global_load_dwordx4 v[104:107], v4, s[86:87]
	global_load_dwordx4 v[108:111], v4, s[84:85]
	global_load_dwordx4 v[112:115], v4, s[16:17]
	global_load_dwordx4 v[116:119], v4, s[18:19]
	v_lshrrev_b32_e32 v5, 1, v3
	v_lshl_or_b32 v5, v5, 6, v8
	v_mul_u32_u24_e32 v5, 0x3000, v5
	v_lshrrev_b32_e32 v7, 1, v4
	v_add_u32_e32 v5, v5, v7
	v_add_u32_e32 v120, 0x12700000, v5
	v_add_u32_e32 v1, 0x20000, v1
	s_waitcnt vmcnt(16)
	v_lshrrev_b32_e32 v2, 1, v49
	v_and_b32_e32 v2, 0x7f, v2
	v_cmp_eq_u32_e32 vcc, 0, v2
	v_and_b32_e32 v3, 1, v49
	v_cmp_eq_u32_e64 s[8:9], 0, v3
	s_nop 1
	s_and_b64 s[8:9], s[8:9], vcc
	s_nop 1
	v_cndmask_b32_e64 v28, v28, 0, vcc
	v_cndmask_b32_e64 v24, v24, 0, s[8:9]
	v_cndmask_b32_e64 v29, v29, 0, vcc
	v_cndmask_b32_e64 v25, v25, 0, s[8:9]
	v_cndmask_b32_e64 v30, v30, 0, vcc
	v_cndmask_b32_e64 v26, v26, 0, s[8:9]
	v_cndmask_b32_e64 v31, v31, 0, vcc
	v_cndmask_b32_e64 v27, v27, 0, s[8:9]
	v_pk_fma_f32 v[30:31], v[30:31], v[38:39], v[34:35]
	v_pk_fma_f32 v[28:29], v[28:29], v[36:37], v[32:33]
	v_pk_fma_f32 v[26:27], v[26:27], v[42:43], v[30:31]
	v_pk_fma_f32 v[24:25], v[24:25], v[40:41], v[28:29]
	v_pk_fma_f32 v[18:19], v[18:19], v[46:47], v[26:27]
	v_pk_fma_f32 v[16:17], v[16:17], v[44:45], v[24:25]
	v_mul_f32_e32 v32, 0x3d922279, v16
	v_mul_f32_e32 v33, 0x3d922279, v17
	v_mul_f32_e32 v34, 0x3d922279, v18
	v_mul_f32_e32 v35, 0x3d922279, v19
	v_fmaak_f32 v32, v16, v32, 0x3fcc422a
	v_fmaak_f32 v33, v17, v33, 0x3fcc422a
	v_fmaak_f32 v34, v18, v34, 0x3fcc422a
	v_fmaak_f32 v35, v19, v35, 0x3fcc422a
	v_mul_f32_e32 v32, v16, v32
	v_mul_f32_e32 v33, v17, v33
	v_mul_f32_e32 v34, v18, v34
	v_mul_f32_e32 v35, v19, v35
	v_mul_f32_e32 v32, 0xbfb8aa3b, v32
	v_mul_f32_e32 v33, 0xbfb8aa3b, v33
	v_mul_f32_e32 v34, 0xbfb8aa3b, v34
	v_mul_f32_e32 v35, 0xbfb8aa3b, v35
	v_exp_f32_e32 v32, v32
	v_exp_f32_e32 v33, v33
	v_exp_f32_e32 v34, v34
	v_exp_f32_e32 v35, v35
	v_add_f32_e32 v32, 1.0, v32
	v_add_f32_e32 v33, 1.0, v33
	v_add_f32_e32 v34, 1.0, v34
	v_add_f32_e32 v35, 1.0, v35
	v_rcp_f32_e32 v32, v32
	v_rcp_f32_e32 v33, v33
	v_rcp_f32_e32 v34, v34
	v_rcp_f32_e32 v35, v35
	v_mul_f32_e32 v16, v16, v32
	v_mul_f32_e32 v17, v17, v33
	v_mul_f32_e32 v18, v18, v34
	v_mul_f32_e32 v19, v19, v35
	v_mul_f32_e32 v16, v20, v16
	v_mul_f32_e32 v17, v21, v17
	v_mul_f32_e32 v18, v22, v18
	v_mul_f32_e32 v19, v23, v19
	v_cvt_pk_bf16_f32 v16, v16, v17
	v_cvt_pk_bf16_f32 v17, v18, v19
	global_store_dwordx2 v48, v[16:17], s[94:95] sc1
	s_waitcnt vmcnt(9)
; __device__ __forceinline__ unsigned cvt_pk_bf16(float lo, float hi) { unsigned r; asm volatile("v_cvt_pk_bf16_f32 %0, %1, %2" : "=v"(r) : "v"(lo), "v"(hi)); return r; }
; __global__ void __launch_bounds__(NTHR, 2) hybrid_block_fwd(Args a) {
;     ...
;         for (int idx = gtid; idx < 256 * 2 * (FF / 4); idx += NT) {
;             const int f4 = (idx % (FF / 4)) * 4, rr = (idx / (FF / 4)) & 1, blk = idx / (2 * (FF / 4));
;             const bool seq0 = (blk & 127) == 0; const size_t row = (size_t)blk * 64 + rr;
;             const f32x4 z = (f32x4){0.f, 0.f, 0.f, 0.f};
;             const f32x4 gc = *(const f32x4*)(HEADG + ((size_t)blk * 2 + rr) * FF + f4), vv = *(const f32x4*)(HEADV + ((size_t)blk * 2 + rr) * FF + f4);
;             f32x4 p1, p2;
;             if (rr == 0) { p1 = seq0 ? z : *(const f32x4*)(TAILG + ((size_t)(blk - 1) * 2 + 1) * FF + f4); p2 = seq0 ? z : *(const f32x4*)(TAILG + ((size_t)(blk - 1) * 2 + 0) * FF + f4); }
;             else { p1 = *(const f32x4*)(HEADG + ((size_t)blk * 2 + 0) * FF + f4); p2 = seq0 ? z : *(const f32x4*)(TAILG + ((size_t)(blk - 1) * 2 + 1) * FF + f4); }
;             const f32x4 cv = *(const f32x4*)(ffn_conv_b + f4) + *(const f32x4*)(ffn_conv_w + f4) * p2 + *(const f32x4*)(ffn_conv_w + FF + f4) * p1 + *(const f32x4*)(ffn_conv_w + 2 * FF + f4) * gc;
;             u32x2 w; w.x = cvt_pk_bf16(gelu_tanh(cv[0]) * vv[0], gelu_tanh(cv[1]) * vv[1]); w.y = cvt_pk_bf16(gelu_tanh(cv[2]) * vv[2], gelu_tanh(cv[3]) * vv[3]);
;             *(u32x2*)(ACT + row * FF + f4) = w;
;         }
	v_lshrrev_b32_e32 v2, 1, v85
	v_and_b32_e32 v2, 0x7f, v2
	v_cmp_eq_u32_e32 vcc, 0, v2
	v_and_b32_e32 v3, 1, v85
	v_cmp_eq_u32_e64 s[8:9], 0, v3
	s_nop 1
	s_and_b64 s[8:9], s[8:9], vcc
	s_nop 1
	v_cndmask_b32_e64 v64, v64, 0, vcc
	v_cndmask_b32_e64 v60, v60, 0, s[8:9]
	v_cndmask_b32_e64 v65, v65, 0, vcc
	v_cndmask_b32_e64 v61, v61, 0, s[8:9]
	v_cndmask_b32_e64 v66, v66, 0, vcc
	v_cndmask_b32_e64 v62, v62, 0, s[8:9]
	v_cndmask_b32_e64 v67, v67, 0, vcc
	v_cndmask_b32_e64 v63, v63, 0, s[8:9]
	v_pk_fma_f32 v[66:67], v[66:67], v[74:75], v[70:71]
	v_pk_fma_f32 v[64:65], v[64:65], v[72:73], v[68:69]
	v_pk_fma_f32 v[62:63], v[62:63], v[78:79], v[66:67]
	v_pk_fma_f32 v[60:61], v[60:61], v[76:77], v[64:65]
	v_pk_fma_f32 v[54:55], v[54:55], v[82:83], v[62:63]
	v_pk_fma_f32 v[52:53], v[52:53], v[80:81], v[60:61]
	v_mul_f32_e32 v68, 0x3d922279, v52
	v_mul_f32_e32 v69, 0x3d922279, v53
	v_mul_f32_e32 v70, 0x3d922279, v54
	v_mul_f32_e32 v71, 0x3d922279, v55
	v_fmaak_f32 v68, v52, v68, 0x3fcc422a
	v_fmaak_f32 v69, v53, v69, 0x3fcc422a
	v_fmaak_f32 v70, v54, v70, 0x3fcc422a
	v_fmaak_f32 v71, v55, v71, 0x3fcc422a
	v_mul_f32_e32 v68, v52, v68
	v_mul_f32_e32 v69, v53, v69
	v_mul_f32_e32 v70, v54, v70
	v_mul_f32_e32 v71, v55, v71
	v_mul_f32_e32 v68, 0xbfb8aa3b, v68
	v_mul_f32_e32 v69, 0xbfb8aa3b, v69
	v_mul_f32_e32 v70, 0xbfb8aa3b, v70
	v_mul_f32_e32 v71, 0xbfb8aa3b, v71
	v_exp_f32_e32 v68, v68
	v_exp_f32_e32 v69, v69
	v_exp_f32_e32 v70, v70
	v_exp_f32_e32 v71, v71
	v_add_f32_e32 v68, 1.0, v68
	v_add_f32_e32 v69, 1.0, v69
	v_add_f32_e32 v70, 1.0, v70
	v_add_f32_e32 v71, 1.0, v71
	v_rcp_f32_e32 v68, v68
	v_rcp_f32_e32 v69, v69
	v_rcp_f32_e32 v70, v70
	v_rcp_f32_e32 v71, v71
	v_mul_f32_e32 v52, v52, v68
	v_mul_f32_e32 v53, v53, v69
	v_mul_f32_e32 v54, v54, v70
	v_mul_f32_e32 v55, v55, v71
	v_mul_f32_e32 v52, v56, v52
	v_mul_f32_e32 v53, v57, v53
	v_mul_f32_e32 v54, v58, v54
	v_mul_f32_e32 v55, v59, v55
	v_cvt_pk_bf16_f32 v52, v52, v53
	v_cvt_pk_bf16_f32 v53, v54, v55
	global_store_dwordx2 v84, v[52:53], s[94:95] sc1
	s_waitcnt vmcnt(2)
	v_lshrrev_b32_e32 v2, 1, v121
	v_and_b32_e32 v2, 0x7f, v2
	v_cmp_eq_u32_e32 vcc, 0, v2
	v_and_b32_e32 v3, 1, v121
	v_cmp_eq_u32_e64 s[8:9], 0, v3
	s_nop 1
	s_and_b64 s[8:9], s[8:9], vcc
	s_nop 1
	v_cndmask_b32_e64 v100, v100, 0, vcc
	v_cndmask_b32_e64 v96, v96, 0, s[8:9]
	v_cndmask_b32_e64 v101, v101, 0, vcc
	v_cndmask_b32_e64 v97, v97, 0, s[8:9]
	v_cndmask_b32_e64 v102, v102, 0, vcc
	v_cndmask_b32_e64 v98, v98, 0, s[8:9]
	v_cndmask_b32_e64 v103, v103, 0, vcc
	v_cndmask_b32_e64 v99, v99, 0, s[8:9]
	v_pk_fma_f32 v[102:103], v[102:103], v[110:111], v[106:107]
	v_pk_fma_f32 v[100:101], v[100:101], v[108:109], v[104:105]
	v_pk_fma_f32 v[98:99], v[98:99], v[114:115], v[102:103]
	v_pk_fma_f32 v[96:97], v[96:97], v[112:113], v[100:101]
	v_pk_fma_f32 v[90:91], v[90:91], v[118:119], v[98:99]
	v_pk_fma_f32 v[88:89], v[88:89], v[116:117], v[96:97]
	v_mul_f32_e32 v104, 0x3d922279, v88
	v_mul_f32_e32 v105, 0x3d922279, v89
	v_mul_f32_e32 v106, 0x3d922279, v90
	v_mul_f32_e32 v107, 0x3d922279, v91
	v_fmaak_f32 v104, v88, v104, 0x3fcc422a
	v_fmaak_f32 v105, v89, v105, 0x3fcc422a
	v_fmaak_f32 v106, v90, v106, 0x3fcc422a
	v_fmaak_f32 v107, v91, v107, 0x3fcc422a
	v_mul_f32_e32 v104, v88, v104
	v_mul_f32_e32 v105, v89, v105
	v_mul_f32_e32 v106, v90, v106
	v_mul_f32_e32 v107, v91, v107
	v_mul_f32_e32 v104, 0xbfb8aa3b, v104
	v_mul_f32_e32 v105, 0xbfb8aa3b, v105
	v_mul_f32_e32 v106, 0xbfb8aa3b, v106
	v_mul_f32_e32 v107, 0xbfb8aa3b, v107
	v_exp_f32_e32 v104, v104
	v_exp_f32_e32 v105, v105
	v_exp_f32_e32 v106, v106
	v_exp_f32_e32 v107, v107
	v_add_f32_e32 v104, 1.0, v104
	v_add_f32_e32 v105, 1.0, v105
	v_add_f32_e32 v106, 1.0, v106
	v_add_f32_e32 v107, 1.0, v107
	v_rcp_f32_e32 v104, v104
	v_rcp_f32_e32 v105, v105
	v_rcp_f32_e32 v106, v106
	v_rcp_f32_e32 v107, v107
	v_mul_f32_e32 v88, v88, v104
	v_mul_f32_e32 v89, v89, v105
	v_mul_f32_e32 v90, v90, v106
	v_mul_f32_e32 v91, v91, v107
	v_mul_f32_e32 v88, v92, v88
	v_mul_f32_e32 v89, v93, v89
	v_mul_f32_e32 v90, v94, v90
	v_mul_f32_e32 v91, v95, v91
	v_cvt_pk_bf16_f32 v88, v88, v89
	v_cvt_pk_bf16_f32 v89, v90, v91
	global_store_dwordx2 v120, v[88:89], s[94:95] sc1
	v_mul_hi_i32 v2, v1, s6
	v_ashrrev_i32_e32 v3, 8, v2
	v_lshlrev_b32_e32 v4, 4, v1
	v_mul_u32_u24_e32 v5, 0x6000, v3
	v_sub_u32_e32 v4, v4, v5
	v_mov_b32_e32 v49, v3
	v_add_u32_e32 v6, v5, v4
	v_add_u32_e32 v7, 0x2700000, v6
	global_load_dwordx4 v[16:19], v7, s[94:95]
	v_add_u32_e32 v7, 0x3300000, v6
	global_load_dwordx4 v[20:23], v7, s[94:95]
	v_and_b32_e32 v8, 1, v3
	v_max_i32_e32 v9, 1, v3
	v_add_u32_e32 v9, -1, v9
	v_mul_u32_u24_e32 v9, 0x6000, v9
	v_add_u32_e32 v9, v9, v4
	v_cmp_eq_u32_e32 vcc, 1, v8
	v_mov_b32_e32 v7, 0x1b00000
	v_mov_b32_e32 v5, 0x2700000
	v_cndmask_b32_e32 v7, v7, v5, vcc
	v_add_u32_e32 v7, v7, v9
	global_load_dwordx4 v[24:27], v7, s[94:95]
	v_max_i32_e32 v9, 2, v3
	v_add_u32_e32 v9, -2, v9
	v_mul_u32_u24_e32 v9, 0x6000, v9
	v_add_u32_e32 v9, v9, v4
	v_add_u32_e32 v9, 0x1b00000, v9
	global_load_dwordx4 v[28:31], v9, s[94:95]
	global_load_dwordx4 v[32:35], v4, s[86:87]
	global_load_dwordx4 v[36:39], v4, s[84:85]
	global_load_dwordx4 v[40:43], v4, s[16:17]
	global_load_dwordx4 v[44:47], v4, s[18:19]
	v_lshrrev_b32_e32 v5, 1, v3
	v_lshl_or_b32 v5, v5, 6, v8
	v_mul_u32_u24_e32 v5, 0x3000, v5
	v_lshrrev_b32_e32 v7, 1, v4
	v_add_u32_e32 v5, v5, v7
	v_add_u32_e32 v48, 0x12700000, v5
	v_add_u32_e32 v1, 0x20000, v1
	v_mul_hi_i32 v2, v1, s6
	v_ashrrev_i32_e32 v3, 8, v2
	v_lshlrev_b32_e32 v4, 4, v1
	v_mul_u32_u24_e32 v5, 0x6000, v3
	v_sub_u32_e32 v4, v4, v5
	v_mov_b32_e32 v85, v3
	v_add_u32_e32 v6, v5, v4
	v_add_u32_e32 v7, 0x2700000, v6
; __device__ __forceinline__ unsigned cvt_pk_bf16(float lo, float hi) { unsigned r; asm volatile("v_cvt_pk_bf16_f32 %0, %1, %2" : "=v"(r) : "v"(lo), "v"(hi)); return r; }
; __global__ void __launch_bounds__(NTHR, 2) hybrid_block_fwd(Args a) {
;     ...
;         for (int idx = gtid; idx < 256 * 2 * (FF / 4); idx += NT) {
;             const int f4 = (idx % (FF / 4)) * 4, rr = (idx / (FF / 4)) & 1, blk = idx / (2 * (FF / 4));
;             const bool seq0 = (blk & 127) == 0; const size_t row = (size_t)blk * 64 + rr;
;             const f32x4 z = (f32x4){0.f, 0.f, 0.f, 0.f};
;             const f32x4 gc = *(const f32x4*)(HEADG + ((size_t)blk * 2 + rr) * FF + f4), vv = *(const f32x4*)(HEADV + ((size_t)blk * 2 + rr) * FF + f4);
;             f32x4 p1, p2;
;             if (rr == 0) { p1 = seq0 ? z : *(const f32x4*)(TAILG + ((size_t)(blk - 1) * 2 + 1) * FF + f4); p2 = seq0 ? z : *(const f32x4*)(TAILG + ((size_t)(blk - 1) * 2 + 0) * FF + f4); }
;             else { p1 = *(const f32x4*)(HEADG + ((size_t)blk * 2 + 0) * FF + f4); p2 = seq0 ? z : *(const f32x4*)(TAILG + ((size_t)(blk - 1) * 2 + 1) * FF + f4); }
;             const f32x4 cv = *(const f32x4*)(ffn_conv_b + f4) + *(const f32x4*)(ffn_conv_w + f4) * p2 + *(const f32x4*)(ffn_conv_w + FF + f4) * p1 + *(const f32x4*)(ffn_conv_w + 2 * FF + f4) * gc;
;             u32x2 w; w.x = cvt_pk_bf16(gelu_tanh(cv[0]) * vv[0], gelu_tanh(cv[1]) * vv[1]); w.y = cvt_pk_bf16(gelu_tanh(cv[2]) * vv[2], gelu_tanh(cv[3]) * vv[3]);
;             *(u32x2*)(ACT + row * FF + f4) = w;
;         }
	global_load_dwordx4 v[52:55], v7, s[94:95]
	v_add_u32_e32 v7, 0x3300000, v6
	global_load_dwordx4 v[56:59], v7, s[94:95]
	v_and_b32_e32 v8, 1, v3
	v_max_i32_e32 v9, 1, v3
	v_add_u32_e32 v9, -1, v9
	v_mul_u32_u24_e32 v9, 0x6000, v9
	v_add_u32_e32 v9, v9, v4
	v_cmp_eq_u32_e32 vcc, 1, v8
	v_mov_b32_e32 v7, 0x1b00000
	v_mov_b32_e32 v5, 0x2700000
	v_cndmask_b32_e32 v7, v7, v5, vcc
	v_add_u32_e32 v7, v7, v9
	global_load_dwordx4 v[60:63], v7, s[94:95]
	v_max_i32_e32 v9, 2, v3
	v_add_u32_e32 v9, -2, v9
	v_mul_u32_u24_e32 v9, 0x6000, v9
	v_add_u32_e32 v9, v9, v4
	v_add_u32_e32 v9, 0x1b00000, v9
	global_load_dwordx4 v[64:67], v9, s[94:95]
	global_load_dwordx4 v[68:71], v4, s[86:87]
	global_load_dwordx4 v[72:75], v4, s[84:85]
	global_load_dwordx4 v[76:79], v4, s[16:17]
	global_load_dwordx4 v[80:83], v4, s[18:19]
	v_lshrrev_b32_e32 v5, 1, v3
	v_lshl_or_b32 v5, v5, 6, v8
	v_mul_u32_u24_e32 v5, 0x3000, v5
	v_lshrrev_b32_e32 v7, 1, v4
	v_add_u32_e32 v5, v5, v7
	v_add_u32_e32 v84, 0x12700000, v5
	v_add_u32_e32 v1, 0x20000, v1
	v_mul_hi_i32 v2, v1, s6
	v_ashrrev_i32_e32 v3, 8, v2
	v_lshlrev_b32_e32 v4, 4, v1
	v_mul_u32_u24_e32 v5, 0x6000, v3
	v_sub_u32_e32 v4, v4, v5
	v_mov_b32_e32 v121, v3
	v_add_u32_e32 v6, v5, v4
	v_add_u32_e32 v7, 0x2700000, v6
	global_load_dwordx4 v[88:91], v7, s[94:95]
	v_add_u32_e32 v7, 0x3300000, v6
	global_load_dwordx4 v[92:95], v7, s[94:95]
	v_and_b32_e32 v8, 1, v3
	v_max_i32_e32 v9, 1, v3
	v_add_u32_e32 v9, -1, v9
	v_mul_u32_u24_e32 v9, 0x6000, v9
	v_add_u32_e32 v9, v9, v4
	v_cmp_eq_u32_e32 vcc, 1, v8
	v_mov_b32_e32 v7, 0x1b00000
	v_mov_b32_e32 v5, 0x2700000
	v_cndmask_b32_e32 v7, v7, v5, vcc
	v_add_u32_e32 v7, v7, v9
	global_load_dwordx4 v[96:99], v7, s[94:95]
	v_max_i32_e32 v9, 2, v3
	v_add_u32_e32 v9, -2, v9
	v_mul_u32_u24_e32 v9, 0x6000, v9
	v_add_u32_e32 v9, v9, v4
	v_add_u32_e32 v9, 0x1b00000, v9
	global_load_dwordx4 v[100:103], v9, s[94:95]
	global_load_dwordx4 v[104:107], v4, s[86:87]
	global_load_dwordx4 v[108:111], v4, s[84:85]
	global_load_dwordx4 v[112:115], v4, s[16:17]
	global_load_dwordx4 v[116:119], v4, s[18:19]
	v_lshrrev_b32_e32 v5, 1, v3
	v_lshl_or_b32 v5, v5, 6, v8
	v_mul_u32_u24_e32 v5, 0x3000, v5
	v_lshrrev_b32_e32 v7, 1, v4
	v_add_u32_e32 v5, v5, v7
	v_add_u32_e32 v120, 0x12700000, v5
	v_add_u32_e32 v1, 0x20000, v1
	s_waitcnt vmcnt(16)
	v_lshrrev_b32_e32 v2, 1, v49
	v_and_b32_e32 v2, 0x7f, v2
	v_cmp_eq_u32_e32 vcc, 0, v2
	v_and_b32_e32 v3, 1, v49
	v_cmp_eq_u32_e64 s[8:9], 0, v3
	s_nop 1
	s_and_b64 s[8:9], s[8:9], vcc
	s_nop 1
	v_cndmask_b32_e64 v28, v28, 0, vcc
	v_cndmask_b32_e64 v24, v24, 0, s[8:9]
	v_cndmask_b32_e64 v29, v29, 0, vcc
	v_cndmask_b32_e64 v25, v25, 0, s[8:9]
	v_cndmask_b32_e64 v30, v30, 0, vcc
	v_cndmask_b32_e64 v26, v26, 0, s[8:9]
	v_cndmask_b32_e64 v31, v31, 0, vcc
	v_cndmask_b32_e64 v27, v27, 0, s[8:9]
	v_pk_fma_f32 v[30:31], v[30:31], v[38:39], v[34:35]
	v_pk_fma_f32 v[28:29], v[28:29], v[36:37], v[32:33]
	v_pk_fma_f32 v[26:27], v[26:27], v[42:43], v[30:31]
	v_pk_fma_f32 v[24:25], v[24:25], v[40:41], v[28:29]
	v_pk_fma_f32 v[18:19], v[18:19], v[46:47], v[26:27]
	v_pk_fma_f32 v[16:17], v[16:17], v[44:45], v[24:25]
	v_mul_f32_e32 v32, 0x3d922279, v16
	v_mul_f32_e32 v33, 0x3d922279, v17
	v_mul_f32_e32 v34, 0x3d922279, v18
	v_mul_f32_e32 v35, 0x3d922279, v19
	v_fmaak_f32 v32, v16, v32, 0x3fcc422a
	v_fmaak_f32 v33, v17, v33, 0x3fcc422a
	v_fmaak_f32 v34, v18, v34, 0x3fcc422a
	v_fmaak_f32 v35, v19, v35, 0x3fcc422a
	v_mul_f32_e32 v32, v16, v32
	v_mul_f32_e32 v33, v17, v33
	v_mul_f32_e32 v34, v18, v34
	v_mul_f32_e32 v35, v19, v35
	v_mul_f32_e32 v32, 0xbfb8aa3b, v32
	v_mul_f32_e32 v33, 0xbfb8aa3b, v33
	v_mul_f32_e32 v34, 0xbfb8aa3b, v34
	v_mul_f32_e32 v35, 0xbfb8aa3b, v35
	v_exp_f32_e32 v32, v32
	v_exp_f32_e32 v33, v33
	v_exp_f32_e32 v34, v34
	v_exp_f32_e32 v35, v35
	v_add_f32_e32 v32, 1.0, v32
	v_add_f32_e32 v33, 1.0, v33
	v_add_f32_e32 v34, 1.0, v34
	v_add_f32_e32 v35, 1.0, v35
	v_rcp_f32_e32 v32, v32
	v_rcp_f32_e32 v33, v33
	v_rcp_f32_e32 v34, v34
	v_rcp_f32_e32 v35, v35
	v_mul_f32_e32 v16, v16, v32
	v_mul_f32_e32 v17, v17, v33
	v_mul_f32_e32 v18, v18, v34
	v_mul_f32_e32 v19, v19, v35
	v_mul_f32_e32 v16, v20, v16
	v_mul_f32_e32 v17, v21, v17
	v_mul_f32_e32 v18, v22, v18
	v_mul_f32_e32 v19, v23, v19
	v_cvt_pk_bf16_f32 v16, v16, v17
	v_cvt_pk_bf16_f32 v17, v18, v19
	global_store_dwordx2 v48, v[16:17], s[94:95] sc1
	s_waitcnt vmcnt(9)
; __device__ __forceinline__ unsigned cvt_pk_bf16(float lo, float hi) { unsigned r; asm volatile("v_cvt_pk_bf16_f32 %0, %1, %2" : "=v"(r) : "v"(lo), "v"(hi)); return r; }
; __global__ void __launch_bounds__(NTHR, 2) hybrid_block_fwd(Args a) {
;     ...
;         for (int idx = gtid; idx < 256 * 2 * (FF / 4); idx += NT) {
;             const int f4 = (idx % (FF / 4)) * 4, rr = (idx / (FF / 4)) & 1, blk = idx / (2 * (FF / 4));
;             const bool seq0 = (blk & 127) == 0; const size_t row = (size_t)blk * 64 + rr;
;             const f32x4 z = (f32x4){0.f, 0.f, 0.f, 0.f};
;             const f32x4 gc = *(const f32x4*)(HEADG + ((size_t)blk * 2 + rr) * FF + f4), vv = *(const f32x4*)(HEADV + ((size_t)blk * 2 + rr) * FF + f4);
;             f32x4 p1, p2;
;             if (rr == 0) { p1 = seq0 ? z : *(const f32x4*)(TAILG + ((size_t)(blk - 1) * 2 + 1) * FF + f4); p2 = seq0 ? z : *(const f32x4*)(TAILG + ((size_t)(blk - 1) * 2 + 0) * FF + f4); }
;             else { p1 = *(const f32x4*)(HEADG + ((size_t)blk * 2 + 0) * FF + f4); p2 = seq0 ? z : *(const f32x4*)(TAILG + ((size_t)(blk - 1) * 2 + 1) * FF + f4); }
;             const f32x4 cv = *(const f32x4*)(ffn_conv_b + f4) + *(const f32x4*)(ffn_conv_w + f4) * p2 + *(const f32x4*)(ffn_conv_w + FF + f4) * p1 + *(const f32x4*)(ffn_conv_w + 2 * FF + f4) * gc;
;             u32x2 w; w.x = cvt_pk_bf16(gelu_tanh(cv[0]) * vv[0], gelu_tanh(cv[1]) * vv[1]); w.y = cvt_pk_bf16(gelu_tanh(cv[2]) * vv[2], gelu_tanh(cv[3]) * vv[3]);
;             *(u32x2*)(ACT + row * FF + f4) = w;
;         }
	v_lshrrev_b32_e32 v2, 1, v85
	v_and_b32_e32 v2, 0x7f, v2
	v_cmp_eq_u32_e32 vcc, 0, v2
	v_and_b32_e32 v3, 1, v85
	v_cmp_eq_u32_e64 s[8:9], 0, v3
	s_nop 1
	s_and_b64 s[8:9], s[8:9], vcc
	s_nop 1
	v_cndmask_b32_e64 v64, v64, 0, vcc
	v_cndmask_b32_e64 v60, v60, 0, s[8:9]
	v_cndmask_b32_e64 v65, v65, 0, vcc
	v_cndmask_b32_e64 v61, v61, 0, s[8:9]
	v_cndmask_b32_e64 v66, v66, 0, vcc
	v_cndmask_b32_e64 v62, v62, 0, s[8:9]
	v_cndmask_b32_e64 v67, v67, 0, vcc
	v_cndmask_b32_e64 v63, v63, 0, s[8:9]
	v_pk_fma_f32 v[66:67], v[66:67], v[74:75], v[70:71]
	v_pk_fma_f32 v[64:65], v[64:65], v[72:73], v[68:69]
	v_pk_fma_f32 v[62:63], v[62:63], v[78:79], v[66:67]
	v_pk_fma_f32 v[60:61], v[60:61], v[76:77], v[64:65]
	v_pk_fma_f32 v[54:55], v[54:55], v[82:83], v[62:63]
	v_pk_fma_f32 v[52:53], v[52:53], v[80:81], v[60:61]
	v_mul_f32_e32 v68, 0x3d922279, v52
	v_mul_f32_e32 v69, 0x3d922279, v53
	v_mul_f32_e32 v70, 0x3d922279, v54
	v_mul_f32_e32 v71, 0x3d922279, v55
	v_fmaak_f32 v68, v52, v68, 0x3fcc422a
	v_fmaak_f32 v69, v53, v69, 0x3fcc422a
	v_fmaak_f32 v70, v54, v70, 0x3fcc422a
	v_fmaak_f32 v71, v55, v71, 0x3fcc422a
	v_mul_f32_e32 v68, v52, v68
	v_mul_f32_e32 v69, v53, v69
	v_mul_f32_e32 v70, v54, v70
	v_mul_f32_e32 v71, v55, v71
	v_mul_f32_e32 v68, 0xbfb8aa3b, v68
	v_mul_f32_e32 v69, 0xbfb8aa3b, v69
	v_mul_f32_e32 v70, 0xbfb8aa3b, v70
	v_mul_f32_e32 v71, 0xbfb8aa3b, v71
	v_exp_f32_e32 v68, v68
	v_exp_f32_e32 v69, v69
	v_exp_f32_e32 v70, v70
	v_exp_f32_e32 v71, v71
	v_add_f32_e32 v68, 1.0, v68
	v_add_f32_e32 v69, 1.0, v69
	v_add_f32_e32 v70, 1.0, v70
	v_add_f32_e32 v71, 1.0, v71
	v_rcp_f32_e32 v68, v68
	v_rcp_f32_e32 v69, v69
	v_rcp_f32_e32 v70, v70
	v_rcp_f32_e32 v71, v71
	v_mul_f32_e32 v52, v52, v68
	v_mul_f32_e32 v53, v53, v69
	v_mul_f32_e32 v54, v54, v70
	v_mul_f32_e32 v55, v55, v71
	v_mul_f32_e32 v52, v56, v52
	v_mul_f32_e32 v53, v57, v53
	v_mul_f32_e32 v54, v58, v54
	v_mul_f32_e32 v55, v59, v55
	v_cvt_pk_bf16_f32 v52, v52, v53
	v_cvt_pk_bf16_f32 v53, v54, v55
	global_store_dwordx2 v84, v[52:53], s[94:95] sc1
	s_waitcnt vmcnt(2)
	v_lshrrev_b32_e32 v2, 1, v121
	v_and_b32_e32 v2, 0x7f, v2
	v_cmp_eq_u32_e32 vcc, 0, v2
	v_and_b32_e32 v3, 1, v121
	v_cmp_eq_u32_e64 s[8:9], 0, v3
	s_nop 1
	s_and_b64 s[8:9], s[8:9], vcc
	s_nop 1
	v_cndmask_b32_e64 v100, v100, 0, vcc
	v_cndmask_b32_e64 v96, v96, 0, s[8:9]
	v_cndmask_b32_e64 v101, v101, 0, vcc
	v_cndmask_b32_e64 v97, v97, 0, s[8:9]
	v_cndmask_b32_e64 v102, v102, 0, vcc
	v_cndmask_b32_e64 v98, v98, 0, s[8:9]
	v_cndmask_b32_e64 v103, v103, 0, vcc
	v_cndmask_b32_e64 v99, v99, 0, s[8:9]
	v_pk_fma_f32 v[102:103], v[102:103], v[110:111], v[106:107]
	v_pk_fma_f32 v[100:101], v[100:101], v[108:109], v[104:105]
	v_pk_fma_f32 v[98:99], v[98:99], v[114:115], v[102:103]
	v_pk_fma_f32 v[96:97], v[96:97], v[112:113], v[100:101]
	v_pk_fma_f32 v[90:91], v[90:91], v[118:119], v[98:99]
	v_pk_fma_f32 v[88:89], v[88:89], v[116:117], v[96:97]
	v_mul_f32_e32 v104, 0x3d922279, v88
	v_mul_f32_e32 v105, 0x3d922279, v89
	v_mul_f32_e32 v106, 0x3d922279, v90
	v_mul_f32_e32 v107, 0x3d922279, v91
	v_fmaak_f32 v104, v88, v104, 0x3fcc422a
	v_fmaak_f32 v105, v89, v105, 0x3fcc422a
	v_fmaak_f32 v106, v90, v106, 0x3fcc422a
	v_fmaak_f32 v107, v91, v107, 0x3fcc422a
	v_mul_f32_e32 v104, v88, v104
	v_mul_f32_e32 v105, v89, v105
	v_mul_f32_e32 v106, v90, v106
	v_mul_f32_e32 v107, v91, v107
	v_mul_f32_e32 v104, 0xbfb8aa3b, v104
	v_mul_f32_e32 v105, 0xbfb8aa3b, v105
	v_mul_f32_e32 v106, 0xbfb8aa3b, v106
	v_mul_f32_e32 v107, 0xbfb8aa3b, v107
	v_exp_f32_e32 v104, v104
	v_exp_f32_e32 v105, v105
	v_exp_f32_e32 v106, v106
	v_exp_f32_e32 v107, v107
	v_add_f32_e32 v104, 1.0, v104
	v_add_f32_e32 v105, 1.0, v105
	v_add_f32_e32 v106, 1.0, v106
	v_add_f32_e32 v107, 1.0, v107
	v_rcp_f32_e32 v104, v104
	v_rcp_f32_e32 v105, v105
	v_rcp_f32_e32 v106, v106
	v_rcp_f32_e32 v107, v107
	v_mul_f32_e32 v88, v88, v104
	v_mul_f32_e32 v89, v89, v105
	v_mul_f32_e32 v90, v90, v106
	v_mul_f32_e32 v91, v91, v107
	v_mul_f32_e32 v88, v92, v88
	v_mul_f32_e32 v89, v93, v89
	v_mul_f32_e32 v90, v94, v90
	v_mul_f32_e32 v91, v95, v91
	v_cvt_pk_bf16_f32 v88, v88, v89
	v_cvt_pk_bf16_f32 v89, v90, v91
	global_store_dwordx2 v120, v[88:89], s[94:95] sc1
	s_or_b64 exec, exec, s[4:5]
	s_waitcnt vmcnt(0)
	s_barrier
	v_readfirstlane_b32 s0, v212
	s_cmp_lg_u32 s0, 64
	s_cbranch_scc1 .Linv_8
	buffer_inv sc1
	s_waitcnt vmcnt(0)
